# v9 with all per-block s_setprio flips removed from the GEMM K-loops
# speedup vs baseline: 1.0014x; 1.0014x over previous
; #define PG8_STAGE(bufoff, gbase, voff) do { _Pragma("unroll") for (int _i = 0; _i < 2; ++_i) \
;         __builtin_amdgcn_global_load_lds((const unsigned*)((const char*)(gbase) + (voff)[_i]), (PG8_LAS unsigned*)(lds + (bufoff) + ldsw + _i * 8192), 16, 0, 0); } while (0)
; #define PG8_LDA(dst, b, h) do { _Pragma("unroll") for (int m = 0; m < 4; ++m) _Pragma("unroll") for (int k = 0; k < 2; ++k) dst[m][k] = *(const PG8_LAS bf16x8*)(lds + PG8_SA(b, h) + aoff + m * 2048 + k * 1024); } while (0)
; #define PG8_LDB(dst, b, h) do { _Pragma("unroll") for (int n = 0; n < 2; ++n) _Pragma("unroll") for (int k = 0; k < 2; ++k) dst[n][k] = *(const PG8_LAS bf16x8*)(lds + PG8_SB(b, h) + boff + n * 2048 + k * 1024); } while (0)
; #define PG8_WAIT_V(n) asm volatile("s_waitcnt vmcnt(" #n ")" ::: "memory")
; #define PG8_WAIT_L(n) asm volatile("s_waitcnt lgkmcnt(" #n ")" ::: "memory")
; #define PG8_BAR __builtin_amdgcn_s_barrier()
; #define PG8_SCHED __builtin_amdgcn_sched_barrier(0)
;     ...
;         for (int t = 0; t < nt; t += 2) {
;             const bool last = (t == nt - 2);
;             const char* a1 = cA + (size_t)(t + 1) * kstep;
;             const char* a2 = last ? nA : cA + (size_t)(t + 2) * kstep; const char* b2 = last ? nB : cB + (size_t)(t + 2) * kstep;
;             const char* a3 = a2 + kstep; const char* b3 = b2 + kstep;
;             if (last && has_next) S.a_ready(nxt);
;             if constexpr (SP2) {
;             PG8_LDB(B0, 0, 0); PG8_LDB(B1, 0, 1); PG8_SCHED; PG8_LDA(At, 0, 0); PG8_STAGE(PG8_SA(1, 1), a1 + hstepA, voffA);
;             PG8_WAIT_V(8); PG8_WAIT_L(0); PG8_BAR; PG8_MMA(0, 0, At, B0); PG8_MMA(0, 1, At, B1); PG8_BAR; PG8_SCHED;
;             PG8_LDA(At, 0, 1); PG8_STAGE(PG8_SB(0, 0), b2, voffB); PG8_STAGE(PG8_SB(0, 1), b2 + hstepB, voffB); PG8_STAGE(PG8_SA(0, 0), a2, voffA);
;             PG8_WAIT_V(8); PG8_WAIT_L(0); PG8_BAR; PG8_MMA(1, 0, At, B0); PG8_MMA(1, 1, At, B1); PG8_BAR; PG8_SCHED;
.LBB0_538:
	v_add_u32_e32 v162, 0x10000, v153
	s_add_u32 s63, s64, 0xfffc0080
	s_addc_u32 s66, s65, -1
	s_add_i32 s68, 0, 0x10000
	s_cmp_eq_u32 s57, 12
	s_cselect_b32 s75, s6, s66
	s_cselect_b32 s74, s15, s63
	s_cselect_b32 s67, s34, s55
	s_cselect_b32 s66, s35, s45
	s_add_i32 s63, 0, 0x14000
	ds_read_b128 v[142:145], v162
	ds_read_b128 v[146:149], v162 offset:1024
	ds_read_b128 v[158:161], v162 offset:2048
	ds_read_b128 v[186:189], v162 offset:3072
	ds_read_b128 v[190:193], v162 offset:16384
	ds_read_b128 v[194:197], v162 offset:17408
	ds_read_b128 v[198:201], v162 offset:18432
	ds_read_b128 v[202:205], v162 offset:19456
	s_add_i32 m0, s81, 0xc000
	ds_read_b128 v[206:209], v156
	ds_read_b128 v[210:213], v156 offset:1024
	ds_read_b128 v[214:217], v156 offset:2048
	ds_read_b128 v[218:221], v156 offset:3072
	ds_read_b128 v[222:225], v156 offset:4096
	ds_read_b128 v[234:237], v156 offset:5120
	ds_read_b128 v[238:241], v156 offset:6144
	ds_read_b128 v[242:245], v156 offset:7168
	global_load_lds_dwordx4 v138, s[64:65]
	s_add_i32 m0, s81, 0xe000
	s_nop 0
	global_load_lds_dwordx4 v140, s[64:65]
	s_waitcnt vmcnt(8)
	s_waitcnt lgkmcnt(0)
	s_barrier
	v_mfma_i32_16x16x64_i8 v[128:131], v[142:145], v[206:209], v[128:131]
	v_mfma_i32_16x16x64_i8 v[120:123], v[158:161], v[206:209], v[120:123]
	v_mfma_i32_16x16x64_i8 v[112:115], v[142:145], v[214:217], v[112:115]
	v_mfma_i32_16x16x64_i8 v[104:107], v[158:161], v[214:217], v[104:107]
	v_mfma_i32_16x16x64_i8 v[96:99], v[142:145], v[222:225], v[96:99]
	v_mfma_i32_16x16x64_i8 v[88:91], v[158:161], v[222:225], v[88:91]
	v_mfma_i32_16x16x64_i8 v[80:83], v[142:145], v[238:241], v[80:83]
	v_mfma_i32_16x16x64_i8 v[72:75], v[158:161], v[238:241], v[72:75]
	v_mfma_i32_16x16x64_i8 v[128:131], v[146:149], v[210:213], v[128:131]
	v_mfma_i32_16x16x64_i8 v[120:123], v[186:189], v[210:213], v[120:123]
	v_mfma_i32_16x16x64_i8 v[112:115], v[146:149], v[218:221], v[112:115]
	v_mfma_i32_16x16x64_i8 v[104:107], v[186:189], v[218:221], v[104:107]
	v_mfma_i32_16x16x64_i8 v[96:99], v[146:149], v[234:237], v[96:99]
	v_mfma_i32_16x16x64_i8 v[88:91], v[186:189], v[234:237], v[88:91]
	v_mfma_i32_16x16x64_i8 v[80:83], v[146:149], v[242:245], v[80:83]
	v_mfma_i32_16x16x64_i8 v[72:75], v[186:189], v[242:245], v[72:75]
	v_mfma_i32_16x16x64_i8 v[124:127], v[190:193], v[206:209], v[124:127]
	v_mfma_i32_16x16x64_i8 v[116:119], v[198:201], v[206:209], v[116:119]
	v_mfma_i32_16x16x64_i8 v[108:111], v[190:193], v[214:217], v[108:111]
	v_mfma_i32_16x16x64_i8 v[100:103], v[198:201], v[214:217], v[100:103]
	v_mfma_i32_16x16x64_i8 v[92:95], v[190:193], v[222:225], v[92:95]
	v_mfma_i32_16x16x64_i8 v[84:87], v[198:201], v[222:225], v[84:87]
	v_mfma_i32_16x16x64_i8 v[76:79], v[190:193], v[238:241], v[76:79]
	v_mfma_i32_16x16x64_i8 v[68:71], v[198:201], v[238:241], v[68:71]
	v_mfma_i32_16x16x64_i8 v[124:127], v[194:197], v[210:213], v[124:127]
	v_mfma_i32_16x16x64_i8 v[116:119], v[202:205], v[210:213], v[116:119]
	v_mfma_i32_16x16x64_i8 v[108:111], v[194:197], v[218:221], v[108:111]
	v_mfma_i32_16x16x64_i8 v[100:103], v[202:205], v[218:221], v[100:103]
	v_mfma_i32_16x16x64_i8 v[92:95], v[194:197], v[234:237], v[92:95]
	v_mfma_i32_16x16x64_i8 v[84:87], v[202:205], v[234:237], v[84:87]
	v_mfma_i32_16x16x64_i8 v[76:79], v[194:197], v[242:245], v[76:79]
	v_mfma_i32_16x16x64_i8 v[68:71], v[202:205], v[242:245], v[68:71]
	s_barrier
	s_add_i32 s68, s68, s10
	s_mov_b32 m0, s68
	ds_read_b128 v[206:209], v156 offset:16384
	ds_read_b128 v[210:213], v156 offset:17408
	ds_read_b128 v[214:217], v156 offset:18432
	ds_read_b128 v[218:221], v156 offset:19456
	ds_read_b128 v[222:225], v156 offset:20480
	ds_read_b128 v[234:237], v156 offset:21504
	ds_read_b128 v[238:241], v156 offset:22528
	ds_read_b128 v[242:245], v156 offset:23552
	global_load_lds_dwordx4 v34, s[66:67]
	s_add_i32 m0, s68, 0x2000
	s_add_u32 s70, s66, 0x40000
	s_addc_u32 s71, s67, 0
	s_add_i32 s63, s63, s10
	global_load_lds_dwordx4 v136, s[66:67]
	s_mov_b32 m0, s63
	s_nop 0
	global_load_lds_dwordx4 v34, s[70:71]
	s_add_i32 m0, s63, 0x2000
	s_nop 0
	global_load_lds_dwordx4 v136, s[70:71]
	s_mov_b32 m0, s81
	s_nop 0
	global_load_lds_dwordx4 v132, s[74:75]
	s_mov_b32 m0, s82
	s_nop 0
	global_load_lds_dwordx4 v134, s[74:75]
	s_waitcnt vmcnt(8)
	s_waitcnt lgkmcnt(0)
	s_barrier
	v_mfma_i32_16x16x64_i8 v[64:67], v[142:145], v[206:209], v[64:67]
	v_mfma_i32_16x16x64_i8 v[56:59], v[158:161], v[206:209], v[56:59]
	v_mfma_i32_16x16x64_i8 v[48:51], v[142:145], v[214:217], v[48:51]
	v_mfma_i32_16x16x64_i8 v[40:43], v[158:161], v[214:217], v[40:43]
	v_mfma_i32_16x16x64_i8 v[30:33], v[142:145], v[222:225], v[30:33]
	v_mfma_i32_16x16x64_i8 v[22:25], v[158:161], v[222:225], v[22:25]
	v_mfma_i32_16x16x64_i8 v[14:17], v[142:145], v[238:241], v[14:17]
	v_mfma_i32_16x16x64_i8 v[6:9], v[158:161], v[238:241], v[6:9]
	v_mfma_i32_16x16x64_i8 v[64:67], v[146:149], v[210:213], v[64:67]
	v_mfma_i32_16x16x64_i8 v[56:59], v[186:189], v[210:213], v[56:59]
	v_mfma_i32_16x16x64_i8 v[48:51], v[146:149], v[218:221], v[48:51]
	v_mfma_i32_16x16x64_i8 v[40:43], v[186:189], v[218:221], v[40:43]
	v_mfma_i32_16x16x64_i8 v[30:33], v[146:149], v[234:237], v[30:33]
	v_mfma_i32_16x16x64_i8 v[22:25], v[186:189], v[234:237], v[22:25]
	v_mfma_i32_16x16x64_i8 v[14:17], v[146:149], v[242:245], v[14:17]
	v_mfma_i32_16x16x64_i8 v[6:9], v[186:189], v[242:245], v[6:9]
	v_mfma_i32_16x16x64_i8 v[60:63], v[190:193], v[206:209], v[60:63]
	v_mfma_i32_16x16x64_i8 v[52:55], v[198:201], v[206:209], v[52:55]
	v_mfma_i32_16x16x64_i8 v[44:47], v[190:193], v[214:217], v[44:47]
	v_mfma_i32_16x16x64_i8 v[36:39], v[198:201], v[214:217], v[36:39]
	v_mfma_i32_16x16x64_i8 v[26:29], v[190:193], v[222:225], v[26:29]
	v_mfma_i32_16x16x64_i8 v[18:21], v[198:201], v[222:225], v[18:21]
	v_mfma_i32_16x16x64_i8 v[10:13], v[190:193], v[238:241], v[10:13]
	v_mfma_i32_16x16x64_i8 v[2:5], v[198:201], v[238:241], v[2:5]
	v_mfma_i32_16x16x64_i8 v[60:63], v[194:197], v[210:213], v[60:63]
	v_mfma_i32_16x16x64_i8 v[52:55], v[202:205], v[210:213], v[52:55]
	v_mfma_i32_16x16x64_i8 v[44:47], v[194:197], v[218:221], v[44:47]
	v_mfma_i32_16x16x64_i8 v[36:39], v[202:205], v[218:221], v[36:39]
	v_mfma_i32_16x16x64_i8 v[26:29], v[194:197], v[234:237], v[26:29]
	v_mfma_i32_16x16x64_i8 v[18:21], v[202:205], v[234:237], v[18:21]
	v_mfma_i32_16x16x64_i8 v[10:13], v[194:197], v[242:245], v[10:13]
	v_mfma_i32_16x16x64_i8 v[2:5], v[202:205], v[242:245], v[2:5]
	s_barrier
; #define PG8_STAGE(bufoff, gbase, voff) do { _Pragma("unroll") for (int _i = 0; _i < 2; ++_i) \
;         __builtin_amdgcn_global_load_lds((const unsigned*)((const char*)(gbase) + (voff)[_i]), (PG8_LAS unsigned*)(lds + (bufoff) + ldsw + _i * 8192), 16, 0, 0); } while (0)
; #define PG8_LDA(dst, b, h) do { _Pragma("unroll") for (int m = 0; m < 4; ++m) _Pragma("unroll") for (int k = 0; k < 2; ++k) dst[m][k] = *(const PG8_LAS bf16x8*)(lds + PG8_SA(b, h) + aoff + m * 2048 + k * 1024); } while (0)
; #define PG8_LDB(dst, b, h) do { _Pragma("unroll") for (int n = 0; n < 2; ++n) _Pragma("unroll") for (int k = 0; k < 2; ++k) dst[n][k] = *(const PG8_LAS bf16x8*)(lds + PG8_SB(b, h) + boff + n * 2048 + k * 1024); } while (0)
; #define PG8_WAIT_V(n) asm volatile("s_waitcnt vmcnt(" #n ")" ::: "memory")
; #define PG8_WAIT_L(n) asm volatile("s_waitcnt lgkmcnt(" #n ")" ::: "memory")
; #define PG8_BAR __builtin_amdgcn_s_barrier()
; #define PG8_SCHED __builtin_amdgcn_sched_barrier(0)
;     ...
;             PG8_LDB(B0, 1, 0); PG8_LDB(B1, 1, 1); PG8_SCHED; PG8_LDA(At, 1, 0); PG8_STAGE(PG8_SA(0, 1), a2 + hstepA, voffA);
;             PG8_WAIT_V(8); PG8_WAIT_L(0); PG8_BAR; PG8_MMA(0, 0, At, B0); PG8_MMA(0, 1, At, B1); PG8_BAR; PG8_SCHED;
	s_add_i32 s63, 0, 0x18000
	s_add_i32 s68, 0, 0x1c000
	ds_read_b128 v[142:145], v162 offset:32768
	ds_read_b128 v[146:149], v162 offset:33792
	ds_read_b128 v[158:161], v162 offset:34816
	ds_read_b128 v[186:189], v162 offset:35840
	ds_read_b128 v[190:193], v162 offset:49152
	ds_read_b128 v[194:197], v162 offset:50176
	ds_read_b128 v[198:201], v162 offset:51200
	ds_read_b128 v[202:205], v162 offset:52224
	s_add_u32 s70, s74, 0x40000
	s_addc_u32 s71, s75, 0
	s_mov_b32 m0, s83
	ds_read_b128 v[206:209], v156 offset:32768
	ds_read_b128 v[210:213], v156 offset:33792
	ds_read_b128 v[214:217], v156 offset:34816
	ds_read_b128 v[218:221], v156 offset:35840
	ds_read_b128 v[222:225], v156 offset:36864
	ds_read_b128 v[234:237], v156 offset:37888
	ds_read_b128 v[238:241], v156 offset:38912
	ds_read_b128 v[242:245], v156 offset:39936
	global_load_lds_dwordx4 v132, s[70:71]
	s_mov_b32 m0, s84
	s_nop 0
	global_load_lds_dwordx4 v134, s[70:71]
	s_waitcnt vmcnt(8)
	s_waitcnt lgkmcnt(0)
	s_barrier
	v_mfma_i32_16x16x64_i8 v[128:131], v[142:145], v[206:209], v[128:131]
	v_mfma_i32_16x16x64_i8 v[120:123], v[158:161], v[206:209], v[120:123]
	v_mfma_i32_16x16x64_i8 v[112:115], v[142:145], v[214:217], v[112:115]
	v_mfma_i32_16x16x64_i8 v[104:107], v[158:161], v[214:217], v[104:107]
	v_mfma_i32_16x16x64_i8 v[96:99], v[142:145], v[222:225], v[96:99]
	v_mfma_i32_16x16x64_i8 v[88:91], v[158:161], v[222:225], v[88:91]
	v_mfma_i32_16x16x64_i8 v[80:83], v[142:145], v[238:241], v[80:83]
	v_mfma_i32_16x16x64_i8 v[72:75], v[158:161], v[238:241], v[72:75]
	v_mfma_i32_16x16x64_i8 v[128:131], v[146:149], v[210:213], v[128:131]
	v_mfma_i32_16x16x64_i8 v[120:123], v[186:189], v[210:213], v[120:123]
	v_mfma_i32_16x16x64_i8 v[112:115], v[146:149], v[218:221], v[112:115]
	v_mfma_i32_16x16x64_i8 v[104:107], v[186:189], v[218:221], v[104:107]
	v_mfma_i32_16x16x64_i8 v[96:99], v[146:149], v[234:237], v[96:99]
	v_mfma_i32_16x16x64_i8 v[88:91], v[186:189], v[234:237], v[88:91]
	v_mfma_i32_16x16x64_i8 v[80:83], v[146:149], v[242:245], v[80:83]
	v_mfma_i32_16x16x64_i8 v[72:75], v[186:189], v[242:245], v[72:75]
	v_mfma_i32_16x16x64_i8 v[124:127], v[190:193], v[206:209], v[124:127]
	v_mfma_i32_16x16x64_i8 v[116:119], v[198:201], v[206:209], v[116:119]
	v_mfma_i32_16x16x64_i8 v[108:111], v[190:193], v[214:217], v[108:111]
	v_mfma_i32_16x16x64_i8 v[100:103], v[198:201], v[214:217], v[100:103]
	v_mfma_i32_16x16x64_i8 v[92:95], v[190:193], v[222:225], v[92:95]
	v_mfma_i32_16x16x64_i8 v[84:87], v[198:201], v[222:225], v[84:87]
	v_mfma_i32_16x16x64_i8 v[76:79], v[190:193], v[238:241], v[76:79]
	v_mfma_i32_16x16x64_i8 v[68:71], v[198:201], v[238:241], v[68:71]
	v_mfma_i32_16x16x64_i8 v[124:127], v[194:197], v[210:213], v[124:127]
	v_mfma_i32_16x16x64_i8 v[116:119], v[202:205], v[210:213], v[116:119]
	v_mfma_i32_16x16x64_i8 v[108:111], v[194:197], v[218:221], v[108:111]
	v_mfma_i32_16x16x64_i8 v[100:103], v[202:205], v[218:221], v[100:103]
	v_mfma_i32_16x16x64_i8 v[92:95], v[194:197], v[234:237], v[92:95]
	v_mfma_i32_16x16x64_i8 v[84:87], v[202:205], v[234:237], v[84:87]
	v_mfma_i32_16x16x64_i8 v[76:79], v[194:197], v[242:245], v[76:79]
	v_mfma_i32_16x16x64_i8 v[68:71], v[202:205], v[242:245], v[68:71]
	s_barrier
; #define PG8_STAGE(bufoff, gbase, voff) do { _Pragma("unroll") for (int _i = 0; _i < 2; ++_i) \
;         __builtin_amdgcn_global_load_lds((const unsigned*)((const char*)(gbase) + (voff)[_i]), (PG8_LAS unsigned*)(lds + (bufoff) + ldsw + _i * 8192), 16, 0, 0); } while (0)
; #define PG8_LDA(dst, b, h) do { _Pragma("unroll") for (int m = 0; m < 4; ++m) _Pragma("unroll") for (int k = 0; k < 2; ++k) dst[m][k] = *(const PG8_LAS bf16x8*)(lds + PG8_SA(b, h) + aoff + m * 2048 + k * 1024); } while (0)
; #define PG8_WAIT_V(n) asm volatile("s_waitcnt vmcnt(" #n ")" ::: "memory")
; #define PG8_WAIT_L(n) asm volatile("s_waitcnt lgkmcnt(" #n ")" ::: "memory")
; #define PG8_BAR __builtin_amdgcn_s_barrier()
; #define PG8_SCHED __builtin_amdgcn_sched_barrier(0)
;     __device__ __forceinline__ void operator()(const f32x4 (&acc)[2][2][4][2], const Unit& u, int wr, int wc, int fr, int fq) const {
;     ...
;             for (int m = 0; m < 4; ++m) { const size_t ro = (size_t)(row0 + ai * HALF + m * 16) * ldc + col0;
;                 float r[8]; const float scr_ = rs ? rs[row0 + ai * HALF + m * 16] * sc : sc;
;     ...
;             PG8_LDA(At, 1, 1); PG8_STAGE(PG8_SB(1, 0), b3, voffB); PG8_STAGE(PG8_SB(1, 1), b3 + hstepB, voffB); PG8_STAGE(PG8_SA(1, 0), a3, voffA);
;             PG8_WAIT_V(8); PG8_WAIT_L(0); PG8_BAR; PG8_MMA(1, 0, At, B0); PG8_MMA(1, 1, At, B1); PG8_BAR; PG8_SCHED;
	s_add_i32 s63, s63, s10
	s_mov_b32 m0, s63
	ds_read_b128 v[206:209], v156 offset:49152
	ds_read_b128 v[210:213], v156 offset:50176
	ds_read_b128 v[214:217], v156 offset:51200
	ds_read_b128 v[218:221], v156 offset:52224
	ds_read_b128 v[222:225], v156 offset:53248
	ds_read_b128 v[234:237], v156 offset:54272
	ds_read_b128 v[238:241], v156 offset:55296
	ds_read_b128 v[242:245], v156 offset:56320
	s_add_u32 vcc_lo, s66, 0x80
	s_addc_u32 vcc_hi, s67, 0
	global_load_lds_dwordx4 v34, vcc
	s_add_i32 m0, s63, 0x2000
	s_add_u32 s66, s66, 0x40080
	s_addc_u32 s67, s67, 0
	s_add_i32 s63, s68, s10
	s_add_u32 vcc_lo, s66, 0xfffc0000
	s_addc_u32 vcc_hi, s67, -1
	global_load_lds_dwordx4 v136, vcc
	s_mov_b32 m0, s63
	s_nop 0
	global_load_lds_dwordx4 v34, s[66:67]
	s_add_i32 m0, s63, 0x2000
	s_nop 0
	global_load_lds_dwordx4 v136, s[66:67]
	s_mov_b32 m0, s86
	s_nop 0
	s_add_u32 vcc_lo, s74, 0x80
	s_addc_u32 vcc_hi, s75, 0
	global_load_lds_dwordx4 v132, vcc
	s_mov_b32 m0, s87
	s_nop 0
	s_add_u32 vcc_lo, s74, 0x80
	s_addc_u32 vcc_hi, s75, 0
	global_load_lds_dwordx4 v134, vcc
	s_waitcnt vmcnt(8)
	s_waitcnt lgkmcnt(0)
	s_barrier
	v_mfma_i32_16x16x64_i8 v[64:67], v[142:145], v[206:209], v[64:67]
	v_mfma_i32_16x16x64_i8 v[56:59], v[158:161], v[206:209], v[56:59]
	v_mfma_i32_16x16x64_i8 v[48:51], v[142:145], v[214:217], v[48:51]
	v_mfma_i32_16x16x64_i8 v[40:43], v[158:161], v[214:217], v[40:43]
	v_mfma_i32_16x16x64_i8 v[30:33], v[142:145], v[222:225], v[30:33]
	v_mfma_i32_16x16x64_i8 v[22:25], v[158:161], v[222:225], v[22:25]
	v_mfma_i32_16x16x64_i8 v[14:17], v[142:145], v[238:241], v[14:17]
	v_mfma_i32_16x16x64_i8 v[6:9], v[158:161], v[238:241], v[6:9]
	v_mfma_i32_16x16x64_i8 v[64:67], v[146:149], v[210:213], v[64:67]
	v_mfma_i32_16x16x64_i8 v[56:59], v[186:189], v[210:213], v[56:59]
	v_mfma_i32_16x16x64_i8 v[48:51], v[146:149], v[218:221], v[48:51]
	v_mfma_i32_16x16x64_i8 v[40:43], v[186:189], v[218:221], v[40:43]
	v_mfma_i32_16x16x64_i8 v[30:33], v[146:149], v[234:237], v[30:33]
	v_mfma_i32_16x16x64_i8 v[22:25], v[186:189], v[234:237], v[22:25]
	v_mfma_i32_16x16x64_i8 v[14:17], v[146:149], v[242:245], v[14:17]
	v_mfma_i32_16x16x64_i8 v[6:9], v[186:189], v[242:245], v[6:9]
	v_mfma_i32_16x16x64_i8 v[60:63], v[190:193], v[206:209], v[60:63]
	v_mfma_i32_16x16x64_i8 v[52:55], v[198:201], v[206:209], v[52:55]
	v_mfma_i32_16x16x64_i8 v[44:47], v[190:193], v[214:217], v[44:47]
	v_mfma_i32_16x16x64_i8 v[36:39], v[198:201], v[214:217], v[36:39]
	v_mfma_i32_16x16x64_i8 v[26:29], v[190:193], v[222:225], v[26:29]
	v_mfma_i32_16x16x64_i8 v[18:21], v[198:201], v[222:225], v[18:21]
	v_mfma_i32_16x16x64_i8 v[10:13], v[190:193], v[238:241], v[10:13]
	v_mfma_i32_16x16x64_i8 v[2:5], v[198:201], v[238:241], v[2:5]
	v_mfma_i32_16x16x64_i8 v[60:63], v[194:197], v[210:213], v[60:63]
	v_mfma_i32_16x16x64_i8 v[52:55], v[202:205], v[210:213], v[52:55]
	v_mfma_i32_16x16x64_i8 v[44:47], v[194:197], v[218:221], v[44:47]
	v_mfma_i32_16x16x64_i8 v[36:39], v[202:205], v[218:221], v[36:39]
	v_mfma_i32_16x16x64_i8 v[26:29], v[194:197], v[234:237], v[26:29]
	v_mfma_i32_16x16x64_i8 v[18:21], v[202:205], v[234:237], v[18:21]
	v_mfma_i32_16x16x64_i8 v[10:13], v[194:197], v[242:245], v[10:13]
	v_mfma_i32_16x16x64_i8 v[2:5], v[202:205], v[242:245], v[2:5]
	s_barrier
	s_add_i32 s57, s57, 2
	s_add_u32 s64, s64, 0x100
	s_addc_u32 s65, s65, 0
	s_add_u32 s45, s45, 0x100
	s_addc_u32 s55, s55, 0
	s_cmp_gt_u32 s57, 13
	s_cbranch_scc0 .LBB0_538
	v_lshl_add_u32 v144, s62, 8, v152
	v_ashrrev_i32_e32 v145, 31, v144
	v_lshl_add_u64 v[146:147], v[144:145], 2, s[50:51]
	global_load_dword v186, v[146:147], off
	global_load_dword v187, v[146:147], off offset:64
	global_load_dword v188, v[146:147], off offset:128
	global_load_dword v189, v[146:147], off offset:192
	global_load_dword v190, v[146:147], off offset:512
	global_load_dword v191, v[146:147], off offset:576
	global_load_dword v192, v[146:147], off offset:640
	global_load_dword v193, v[146:147], off offset:704
	s_and_b64 vcc, exec, s[52:53]
	s_cbranch_vccz .LBB0_541
	s_barrier

; #define PG8_STAGE(bufoff, gbase, voff) do { _Pragma("unroll") for (int _i = 0; _i < 2; ++_i) \
;         __builtin_amdgcn_global_load_lds((const unsigned*)((const char*)(gbase) + (voff)[_i]), (PG8_LAS unsigned*)(lds + (bufoff) + ldsw + _i * 8192), 16, 0, 0); } while (0)
; #define PG8_LDA(dst, b, h) do { _Pragma("unroll") for (int m = 0; m < 4; ++m) _Pragma("unroll") for (int k = 0; k < 2; ++k) dst[m][k] = *(const PG8_LAS bf16x8*)(lds + PG8_SA(b, h) + aoff + m * 2048 + k * 1024); } while (0)
; #define PG8_LDB(dst, b, h) do { _Pragma("unroll") for (int n = 0; n < 2; ++n) _Pragma("unroll") for (int k = 0; k < 2; ++k) dst[n][k] = *(const PG8_LAS bf16x8*)(lds + PG8_SB(b, h) + boff + n * 2048 + k * 1024); } while (0)
; #define PG8_WAIT_V(n) asm volatile("s_waitcnt vmcnt(" #n ")" ::: "memory")
; #define PG8_WAIT_L(n) asm volatile("s_waitcnt lgkmcnt(" #n ")" ::: "memory")
; #define PG8_BAR __builtin_amdgcn_s_barrier()
; #define PG8_SCHED __builtin_amdgcn_sched_barrier(0)
;     ...
;         for (int t = 0; t < nt; t += 2) {
;             const bool last = (t == nt - 2);
;             const char* a1 = cA + (size_t)(t + 1) * kstep;
;             const char* a2 = last ? nA : cA + (size_t)(t + 2) * kstep; const char* b2 = last ? nB : cB + (size_t)(t + 2) * kstep;
;             const char* a3 = a2 + kstep; const char* b3 = b2 + kstep;
;             if (last && has_next) S.a_ready(nxt);
;             if constexpr (SP2) {
;             PG8_LDB(B0, 0, 0); PG8_LDB(B1, 0, 1); PG8_SCHED; PG8_LDA(At, 0, 0); PG8_STAGE(PG8_SA(1, 1), a1 + hstepA, voffA);
;             PG8_WAIT_V(8); PG8_WAIT_L(0); PG8_BAR; PG8_MMA(0, 0, At, B0); PG8_MMA(0, 1, At, B1); PG8_BAR; PG8_SCHED;
;             PG8_LDA(At, 0, 1); PG8_STAGE(PG8_SB(0, 0), b2, voffB); PG8_STAGE(PG8_SB(0, 1), b2 + hstepB, voffB); PG8_STAGE(PG8_SA(0, 0), a2, voffA);
;             PG8_WAIT_V(8); PG8_WAIT_L(0); PG8_BAR; PG8_MMA(1, 0, At, B0); PG8_MMA(1, 1, At, B1); PG8_BAR; PG8_SCHED;
.LBB0_608:
	v_add_u32_e32 v226, 0x10000, v145
	s_add_u32 s52, s50, 0xfff80080
	s_addc_u32 s53, s51, -1
	s_add_i32 s63, 0, 0x10000
	s_cmp_eq_u32 s62, 28
	s_cselect_b32 s55, s37, s53
	s_cselect_b32 s54, s58, s52
	s_cselect_b32 s53, s31, s61
	s_cselect_b32 s52, s59, s60
	s_add_i32 s66, 0, 0x14000
	ds_read_b128 v[148:151], v226
	ds_read_b128 v[152:155], v226 offset:1024
	ds_read_b128 v[156:159], v226 offset:2048
	ds_read_b128 v[160:163], v226 offset:3072
	ds_read_b128 v[186:189], v226 offset:16384
	ds_read_b128 v[190:193], v226 offset:17408
	ds_read_b128 v[194:197], v226 offset:18432
	ds_read_b128 v[198:201], v226 offset:19456
	s_add_i32 m0, s12, 0xc000
	ds_read_b128 v[202:205], v147
	ds_read_b128 v[206:209], v147 offset:1024
	ds_read_b128 v[210:213], v147 offset:2048
	ds_read_b128 v[214:217], v147 offset:3072
	ds_read_b128 v[218:221], v147 offset:4096
	ds_read_b128 v[222:225], v147 offset:5120
	ds_read_b128 v[234:237], v147 offset:6144
	ds_read_b128 v[238:241], v147 offset:7168
	global_load_lds_dwordx4 v138, s[50:51]
	s_add_i32 m0, s12, 0xe000
	s_nop 0
	global_load_lds_dwordx4 v140, s[50:51]
	s_waitcnt vmcnt(8)
	s_waitcnt lgkmcnt(0)
	s_barrier
	v_mfma_f32_16x16x32_bf16 v[128:131], v[148:151], v[202:205], v[128:131]
	v_mfma_f32_16x16x32_bf16 v[124:127], v[156:159], v[202:205], v[124:127]
	v_mfma_f32_16x16x32_bf16 v[112:115], v[148:151], v[210:213], v[112:115]
	v_mfma_f32_16x16x32_bf16 v[108:111], v[156:159], v[210:213], v[108:111]
	v_mfma_f32_16x16x32_bf16 v[96:99], v[148:151], v[218:221], v[96:99]
	v_mfma_f32_16x16x32_bf16 v[92:95], v[156:159], v[218:221], v[92:95]
	v_mfma_f32_16x16x32_bf16 v[80:83], v[148:151], v[234:237], v[80:83]
	v_mfma_f32_16x16x32_bf16 v[76:79], v[156:159], v[234:237], v[76:79]
	v_mfma_f32_16x16x32_bf16 v[128:131], v[152:155], v[206:209], v[128:131]
	v_mfma_f32_16x16x32_bf16 v[124:127], v[160:163], v[206:209], v[124:127]
	v_mfma_f32_16x16x32_bf16 v[112:115], v[152:155], v[214:217], v[112:115]
	v_mfma_f32_16x16x32_bf16 v[108:111], v[160:163], v[214:217], v[108:111]
	v_mfma_f32_16x16x32_bf16 v[96:99], v[152:155], v[222:225], v[96:99]
	v_mfma_f32_16x16x32_bf16 v[92:95], v[160:163], v[222:225], v[92:95]
	v_mfma_f32_16x16x32_bf16 v[80:83], v[152:155], v[238:241], v[80:83]
	v_mfma_f32_16x16x32_bf16 v[76:79], v[160:163], v[238:241], v[76:79]
	v_mfma_f32_16x16x32_bf16 v[120:123], v[186:189], v[202:205], v[120:123]
	v_mfma_f32_16x16x32_bf16 v[116:119], v[194:197], v[202:205], v[116:119]
	v_mfma_f32_16x16x32_bf16 v[104:107], v[186:189], v[210:213], v[104:107]
	v_mfma_f32_16x16x32_bf16 v[100:103], v[194:197], v[210:213], v[100:103]
	v_mfma_f32_16x16x32_bf16 v[88:91], v[186:189], v[218:221], v[88:91]
	v_mfma_f32_16x16x32_bf16 v[84:87], v[194:197], v[218:221], v[84:87]
	v_mfma_f32_16x16x32_bf16 v[72:75], v[186:189], v[234:237], v[72:75]
	v_mfma_f32_16x16x32_bf16 v[68:71], v[194:197], v[234:237], v[68:71]
	v_mfma_f32_16x16x32_bf16 v[120:123], v[190:193], v[206:209], v[120:123]
	v_mfma_f32_16x16x32_bf16 v[116:119], v[198:201], v[206:209], v[116:119]
	v_mfma_f32_16x16x32_bf16 v[104:107], v[190:193], v[214:217], v[104:107]
	v_mfma_f32_16x16x32_bf16 v[100:103], v[198:201], v[214:217], v[100:103]
	v_mfma_f32_16x16x32_bf16 v[88:91], v[190:193], v[222:225], v[88:91]
	v_mfma_f32_16x16x32_bf16 v[84:87], v[198:201], v[222:225], v[84:87]
	v_mfma_f32_16x16x32_bf16 v[72:75], v[190:193], v[238:241], v[72:75]
	v_mfma_f32_16x16x32_bf16 v[68:71], v[198:201], v[238:241], v[68:71]
	s_barrier
	s_add_i32 s63, s63, s6
	s_mov_b32 m0, s63
	ds_read_b128 v[202:205], v147 offset:16384
	ds_read_b128 v[206:209], v147 offset:17408
	ds_read_b128 v[210:213], v147 offset:18432
	ds_read_b128 v[214:217], v147 offset:19456
	ds_read_b128 v[218:221], v147 offset:20480
	ds_read_b128 v[222:225], v147 offset:21504
	ds_read_b128 v[234:237], v147 offset:22528
	ds_read_b128 v[238:241], v147 offset:23552
	global_load_lds_dwordx4 v34, s[52:53]
	s_add_i32 m0, s63, 0x2000
	s_add_u32 s64, s52, 0x80000
	s_addc_u32 s65, s53, 0
	s_add_i32 s63, s66, s6
	global_load_lds_dwordx4 v132, s[52:53]
	s_mov_b32 m0, s63
	s_add_u32 s98, s54, 0x80
	s_addc_u32 s99, s55, 0
	global_load_lds_dwordx4 v34, s[64:65]
	s_add_i32 m0, s63, 0x2000
	s_nop 0
	global_load_lds_dwordx4 v132, s[64:65]
	s_mov_b32 m0, s12
	s_nop 0
	global_load_lds_dwordx4 v136, s[54:55]
	s_mov_b32 m0, s13
	s_nop 0
	global_load_lds_dwordx4 v134, s[54:55]
	s_waitcnt vmcnt(8)
	s_waitcnt lgkmcnt(0)
	s_barrier
	v_mfma_f32_16x16x32_bf16 v[64:67], v[148:151], v[202:205], v[64:67]
	v_mfma_f32_16x16x32_bf16 v[60:63], v[156:159], v[202:205], v[60:63]
	v_mfma_f32_16x16x32_bf16 v[48:51], v[148:151], v[210:213], v[48:51]
	v_mfma_f32_16x16x32_bf16 v[44:47], v[156:159], v[210:213], v[44:47]
	v_mfma_f32_16x16x32_bf16 v[30:33], v[148:151], v[218:221], v[30:33]
	v_mfma_f32_16x16x32_bf16 v[26:29], v[156:159], v[218:221], v[26:29]
	v_mfma_f32_16x16x32_bf16 v[14:17], v[148:151], v[234:237], v[14:17]
	v_mfma_f32_16x16x32_bf16 v[10:13], v[156:159], v[234:237], v[10:13]
	v_mfma_f32_16x16x32_bf16 v[64:67], v[152:155], v[206:209], v[64:67]
	v_mfma_f32_16x16x32_bf16 v[60:63], v[160:163], v[206:209], v[60:63]
	v_mfma_f32_16x16x32_bf16 v[48:51], v[152:155], v[214:217], v[48:51]
	v_mfma_f32_16x16x32_bf16 v[44:47], v[160:163], v[214:217], v[44:47]
	v_mfma_f32_16x16x32_bf16 v[30:33], v[152:155], v[222:225], v[30:33]
	v_mfma_f32_16x16x32_bf16 v[26:29], v[160:163], v[222:225], v[26:29]
	v_mfma_f32_16x16x32_bf16 v[14:17], v[152:155], v[238:241], v[14:17]
	v_mfma_f32_16x16x32_bf16 v[10:13], v[160:163], v[238:241], v[10:13]
	v_mfma_f32_16x16x32_bf16 v[56:59], v[186:189], v[202:205], v[56:59]
	v_mfma_f32_16x16x32_bf16 v[52:55], v[194:197], v[202:205], v[52:55]
	v_mfma_f32_16x16x32_bf16 v[40:43], v[186:189], v[210:213], v[40:43]
	v_mfma_f32_16x16x32_bf16 v[36:39], v[194:197], v[210:213], v[36:39]
	v_mfma_f32_16x16x32_bf16 v[22:25], v[186:189], v[218:221], v[22:25]
	v_mfma_f32_16x16x32_bf16 v[18:21], v[194:197], v[218:221], v[18:21]
	v_mfma_f32_16x16x32_bf16 v[6:9], v[186:189], v[234:237], v[6:9]
	v_mfma_f32_16x16x32_bf16 v[2:5], v[194:197], v[234:237], v[2:5]
	v_mfma_f32_16x16x32_bf16 v[56:59], v[190:193], v[206:209], v[56:59]
	v_mfma_f32_16x16x32_bf16 v[52:55], v[198:201], v[206:209], v[52:55]
	v_mfma_f32_16x16x32_bf16 v[40:43], v[190:193], v[214:217], v[40:43]
	v_mfma_f32_16x16x32_bf16 v[36:39], v[198:201], v[214:217], v[36:39]
	v_mfma_f32_16x16x32_bf16 v[22:25], v[190:193], v[222:225], v[22:25]
	v_mfma_f32_16x16x32_bf16 v[18:21], v[198:201], v[222:225], v[18:21]
	v_mfma_f32_16x16x32_bf16 v[6:9], v[190:193], v[238:241], v[6:9]
	v_mfma_f32_16x16x32_bf16 v[2:5], v[198:201], v[238:241], v[2:5]
	s_barrier
; #define PG8_STAGE(bufoff, gbase, voff) do { _Pragma("unroll") for (int _i = 0; _i < 2; ++_i) \
;         __builtin_amdgcn_global_load_lds((const unsigned*)((const char*)(gbase) + (voff)[_i]), (PG8_LAS unsigned*)(lds + (bufoff) + ldsw + _i * 8192), 16, 0, 0); } while (0)
; #define PG8_LDA(dst, b, h) do { _Pragma("unroll") for (int m = 0; m < 4; ++m) _Pragma("unroll") for (int k = 0; k < 2; ++k) dst[m][k] = *(const PG8_LAS bf16x8*)(lds + PG8_SA(b, h) + aoff + m * 2048 + k * 1024); } while (0)
; #define PG8_LDB(dst, b, h) do { _Pragma("unroll") for (int n = 0; n < 2; ++n) _Pragma("unroll") for (int k = 0; k < 2; ++k) dst[n][k] = *(const PG8_LAS bf16x8*)(lds + PG8_SB(b, h) + boff + n * 2048 + k * 1024); } while (0)
; #define PG8_WAIT_V(n) asm volatile("s_waitcnt vmcnt(" #n ")" ::: "memory")
; #define PG8_WAIT_L(n) asm volatile("s_waitcnt lgkmcnt(" #n ")" ::: "memory")
; #define PG8_BAR __builtin_amdgcn_s_barrier()
; #define PG8_SCHED __builtin_amdgcn_sched_barrier(0)
;     ...
;         for (int t = 0; t < nt; t += 2) {
;             const bool last = (t == nt - 2);
;             const char* a1 = cA + (size_t)(t + 1) * kstep;
;             const char* a2 = last ? nA : cA + (size_t)(t + 2) * kstep; const char* b2 = last ? nB : cB + (size_t)(t + 2) * kstep;
;     ...
;             PG8_LDB(B0, 1, 0); PG8_LDB(B1, 1, 1); PG8_SCHED; PG8_LDA(At, 1, 0); PG8_STAGE(PG8_SA(0, 1), a2 + hstepA, voffA);
;             PG8_WAIT_V(8); PG8_WAIT_L(0); PG8_BAR; PG8_MMA(0, 0, At, B0); PG8_MMA(0, 1, At, B1); PG8_BAR; PG8_SCHED;
;             PG8_LDA(At, 1, 1); PG8_STAGE(PG8_SB(1, 0), b3, voffB); PG8_STAGE(PG8_SB(1, 1), b3 + hstepB, voffB); PG8_STAGE(PG8_SA(1, 0), a3, voffA);
;             PG8_WAIT_V(8); PG8_WAIT_L(0); PG8_BAR; PG8_MMA(1, 0, At, B0); PG8_MMA(1, 1, At, B1); PG8_BAR; PG8_SCHED;
	s_add_i32 s63, 0, 0x18000
	s_add_i32 s64, 0, 0x1c000
	ds_read_b128 v[148:151], v226 offset:32768
	ds_read_b128 v[152:155], v226 offset:33792
	ds_read_b128 v[156:159], v226 offset:34816
	ds_read_b128 v[160:163], v226 offset:35840
	ds_read_b128 v[186:189], v226 offset:49152
	ds_read_b128 v[190:193], v226 offset:50176
	ds_read_b128 v[194:197], v226 offset:51200
	ds_read_b128 v[198:201], v226 offset:52224
	s_add_u32 s54, s54, 0x80000
	s_addc_u32 s55, s55, 0
	s_mov_b32 m0, s15
	ds_read_b128 v[202:205], v147 offset:32768
	ds_read_b128 v[206:209], v147 offset:33792
	ds_read_b128 v[210:213], v147 offset:34816
	ds_read_b128 v[214:217], v147 offset:35840
	ds_read_b128 v[218:221], v147 offset:36864
	ds_read_b128 v[222:225], v147 offset:37888
	ds_read_b128 v[234:237], v147 offset:38912
	ds_read_b128 v[238:241], v147 offset:39936
	global_load_lds_dwordx4 v136, s[54:55]
	s_mov_b32 m0, s34
	s_nop 0
	global_load_lds_dwordx4 v134, s[54:55]
	s_waitcnt vmcnt(8)
	s_waitcnt lgkmcnt(0)
	s_barrier
	v_mfma_f32_16x16x32_bf16 v[128:131], v[148:151], v[202:205], v[128:131]
	v_mfma_f32_16x16x32_bf16 v[124:127], v[156:159], v[202:205], v[124:127]
	v_mfma_f32_16x16x32_bf16 v[112:115], v[148:151], v[210:213], v[112:115]
	v_mfma_f32_16x16x32_bf16 v[108:111], v[156:159], v[210:213], v[108:111]
	v_mfma_f32_16x16x32_bf16 v[96:99], v[148:151], v[218:221], v[96:99]
	v_mfma_f32_16x16x32_bf16 v[92:95], v[156:159], v[218:221], v[92:95]
	v_mfma_f32_16x16x32_bf16 v[80:83], v[148:151], v[234:237], v[80:83]
	v_mfma_f32_16x16x32_bf16 v[76:79], v[156:159], v[234:237], v[76:79]
	v_mfma_f32_16x16x32_bf16 v[128:131], v[152:155], v[206:209], v[128:131]
	v_mfma_f32_16x16x32_bf16 v[124:127], v[160:163], v[206:209], v[124:127]
	v_mfma_f32_16x16x32_bf16 v[112:115], v[152:155], v[214:217], v[112:115]
	v_mfma_f32_16x16x32_bf16 v[108:111], v[160:163], v[214:217], v[108:111]
	v_mfma_f32_16x16x32_bf16 v[96:99], v[152:155], v[222:225], v[96:99]
	v_mfma_f32_16x16x32_bf16 v[92:95], v[160:163], v[222:225], v[92:95]
	v_mfma_f32_16x16x32_bf16 v[80:83], v[152:155], v[238:241], v[80:83]
	v_mfma_f32_16x16x32_bf16 v[76:79], v[160:163], v[238:241], v[76:79]
	v_mfma_f32_16x16x32_bf16 v[120:123], v[186:189], v[202:205], v[120:123]
	v_mfma_f32_16x16x32_bf16 v[116:119], v[194:197], v[202:205], v[116:119]
	v_mfma_f32_16x16x32_bf16 v[104:107], v[186:189], v[210:213], v[104:107]
	v_mfma_f32_16x16x32_bf16 v[100:103], v[194:197], v[210:213], v[100:103]
	v_mfma_f32_16x16x32_bf16 v[88:91], v[186:189], v[218:221], v[88:91]
	v_mfma_f32_16x16x32_bf16 v[84:87], v[194:197], v[218:221], v[84:87]
	v_mfma_f32_16x16x32_bf16 v[72:75], v[186:189], v[234:237], v[72:75]
	v_mfma_f32_16x16x32_bf16 v[68:71], v[194:197], v[234:237], v[68:71]
	v_mfma_f32_16x16x32_bf16 v[120:123], v[190:193], v[206:209], v[120:123]
	v_mfma_f32_16x16x32_bf16 v[116:119], v[198:201], v[206:209], v[116:119]
	v_mfma_f32_16x16x32_bf16 v[104:107], v[190:193], v[214:217], v[104:107]
	v_mfma_f32_16x16x32_bf16 v[100:103], v[198:201], v[214:217], v[100:103]
	v_mfma_f32_16x16x32_bf16 v[88:91], v[190:193], v[222:225], v[88:91]
	v_mfma_f32_16x16x32_bf16 v[84:87], v[198:201], v[222:225], v[84:87]
	v_mfma_f32_16x16x32_bf16 v[72:75], v[190:193], v[238:241], v[72:75]
	v_mfma_f32_16x16x32_bf16 v[68:71], v[198:201], v[238:241], v[68:71]
	s_barrier
	s_add_i32 s54, s63, s6
	s_mov_b32 m0, s54
	ds_read_b128 v[202:205], v147 offset:49152
	ds_read_b128 v[206:209], v147 offset:50176
	ds_read_b128 v[210:213], v147 offset:51200
	ds_read_b128 v[214:217], v147 offset:52224
	ds_read_b128 v[218:221], v147 offset:53248
	ds_read_b128 v[222:225], v147 offset:54272
	ds_read_b128 v[234:237], v147 offset:55296
	ds_read_b128 v[238:241], v147 offset:56320
	s_add_u32 vcc_lo, s52, 0x80
	s_addc_u32 vcc_hi, s53, 0
	global_load_lds_dwordx4 v34, vcc
	s_add_i32 m0, s54, 0x2000
	s_add_u32 s52, s52, 0x80080
	s_addc_u32 s53, s53, 0
	s_add_i32 s54, s64, s6
	s_add_u32 vcc_lo, s52, 0xfff80000
	s_addc_u32 vcc_hi, s53, -1
	global_load_lds_dwordx4 v132, vcc
	s_mov_b32 m0, s54
	s_nop 0
	global_load_lds_dwordx4 v34, s[52:53]
	s_add_i32 m0, s54, 0x2000
	s_nop 0
	global_load_lds_dwordx4 v132, s[52:53]
	s_mov_b32 m0, s24
	s_nop 0
	global_load_lds_dwordx4 v136, s[98:99]
	s_mov_b32 m0, s35
	s_nop 0
	global_load_lds_dwordx4 v134, s[98:99]
	s_waitcnt vmcnt(8)
	s_waitcnt lgkmcnt(0)
	s_barrier
	v_mfma_f32_16x16x32_bf16 v[64:67], v[148:151], v[202:205], v[64:67]
	v_mfma_f32_16x16x32_bf16 v[60:63], v[156:159], v[202:205], v[60:63]
	v_mfma_f32_16x16x32_bf16 v[48:51], v[148:151], v[210:213], v[48:51]
	v_mfma_f32_16x16x32_bf16 v[44:47], v[156:159], v[210:213], v[44:47]
	v_mfma_f32_16x16x32_bf16 v[30:33], v[148:151], v[218:221], v[30:33]
	v_mfma_f32_16x16x32_bf16 v[26:29], v[156:159], v[218:221], v[26:29]
	v_mfma_f32_16x16x32_bf16 v[14:17], v[148:151], v[234:237], v[14:17]
	v_mfma_f32_16x16x32_bf16 v[10:13], v[156:159], v[234:237], v[10:13]
	v_mfma_f32_16x16x32_bf16 v[64:67], v[152:155], v[206:209], v[64:67]
	v_mfma_f32_16x16x32_bf16 v[60:63], v[160:163], v[206:209], v[60:63]
	v_mfma_f32_16x16x32_bf16 v[48:51], v[152:155], v[214:217], v[48:51]
	v_mfma_f32_16x16x32_bf16 v[44:47], v[160:163], v[214:217], v[44:47]
	v_mfma_f32_16x16x32_bf16 v[30:33], v[152:155], v[222:225], v[30:33]
	v_mfma_f32_16x16x32_bf16 v[26:29], v[160:163], v[222:225], v[26:29]
	v_mfma_f32_16x16x32_bf16 v[14:17], v[152:155], v[238:241], v[14:17]
	v_mfma_f32_16x16x32_bf16 v[10:13], v[160:163], v[238:241], v[10:13]
	v_mfma_f32_16x16x32_bf16 v[56:59], v[186:189], v[202:205], v[56:59]
	v_mfma_f32_16x16x32_bf16 v[52:55], v[194:197], v[202:205], v[52:55]
	v_mfma_f32_16x16x32_bf16 v[40:43], v[186:189], v[210:213], v[40:43]
	v_mfma_f32_16x16x32_bf16 v[36:39], v[194:197], v[210:213], v[36:39]
	v_mfma_f32_16x16x32_bf16 v[22:25], v[186:189], v[218:221], v[22:25]
	v_mfma_f32_16x16x32_bf16 v[18:21], v[194:197], v[218:221], v[18:21]
	v_mfma_f32_16x16x32_bf16 v[6:9], v[186:189], v[234:237], v[6:9]
	v_mfma_f32_16x16x32_bf16 v[2:5], v[194:197], v[234:237], v[2:5]
	v_mfma_f32_16x16x32_bf16 v[56:59], v[190:193], v[206:209], v[56:59]
	v_mfma_f32_16x16x32_bf16 v[52:55], v[198:201], v[206:209], v[52:55]
	v_mfma_f32_16x16x32_bf16 v[40:43], v[190:193], v[214:217], v[40:43]
	v_mfma_f32_16x16x32_bf16 v[36:39], v[198:201], v[214:217], v[36:39]
	v_mfma_f32_16x16x32_bf16 v[22:25], v[190:193], v[222:225], v[22:25]
	v_mfma_f32_16x16x32_bf16 v[18:21], v[198:201], v[222:225], v[18:21]
	v_mfma_f32_16x16x32_bf16 v[6:9], v[190:193], v[238:241], v[6:9]
	v_mfma_f32_16x16x32_bf16 v[2:5], v[198:201], v[238:241], v[2:5]
	s_barrier
	s_add_i32 s62, s62, 2
	s_add_u32 s50, s50, 0x100
	s_addc_u32 s51, s51, 0
	s_add_u32 s60, s60, 0x100
	s_addc_u32 s61, s61, 0
	s_cmp_gt_u32 s62, 29
	s_cbranch_scc0 .LBB0_608
	s_and_b64 vcc, exec, s[28:29]
	s_cbranch_vccz .LBB0_611
	s_barrier

; #define PG8_STAGE(bufoff, gbase, voff) do { _Pragma("unroll") for (int _i = 0; _i < 2; ++_i) \
;         __builtin_amdgcn_global_load_lds((const unsigned*)((const char*)(gbase) + (voff)[_i]), (PG8_LAS unsigned*)(lds + (bufoff) + ldsw + _i * 8192), 16, 0, 0); } while (0)
; #define PG8_LDA(dst, b, h) do { _Pragma("unroll") for (int m = 0; m < 4; ++m) _Pragma("unroll") for (int k = 0; k < 2; ++k) dst[m][k] = *(const PG8_LAS bf16x8*)(lds + PG8_SA(b, h) + aoff + m * 2048 + k * 1024); } while (0)
; #define PG8_LDB(dst, b, h) do { _Pragma("unroll") for (int n = 0; n < 2; ++n) _Pragma("unroll") for (int k = 0; k < 2; ++k) dst[n][k] = *(const PG8_LAS bf16x8*)(lds + PG8_SB(b, h) + boff + n * 2048 + k * 1024); } while (0)
; #define PG8_WAIT_V(n) asm volatile("s_waitcnt vmcnt(" #n ")" ::: "memory")
; #define PG8_WAIT_L(n) asm volatile("s_waitcnt lgkmcnt(" #n ")" ::: "memory")
; #define PG8_BAR __builtin_amdgcn_s_barrier()
; #define PG8_SCHED __builtin_amdgcn_sched_barrier(0)
;     ...
;         for (int t = 0; t < nt; t += 2) {
;             const bool last = (t == nt - 2);
;             const char* a1 = cA + (size_t)(t + 1) * kstep;
;             const char* a2 = last ? nA : cA + (size_t)(t + 2) * kstep; const char* b2 = last ? nB : cB + (size_t)(t + 2) * kstep;
;             const char* a3 = a2 + kstep; const char* b3 = b2 + kstep;
;             if (last && has_next) S.a_ready(nxt);
;             if constexpr (SP2) {
;             PG8_LDB(B0, 0, 0); PG8_LDB(B1, 0, 1); PG8_SCHED; PG8_LDA(At, 0, 0); PG8_STAGE(PG8_SA(1, 1), a1 + hstepA, voffA);
;             PG8_WAIT_V(8); PG8_WAIT_L(0); PG8_BAR; PG8_MMA(0, 0, At, B0); PG8_MMA(0, 1, At, B1); PG8_BAR; PG8_SCHED;
;             PG8_LDA(At, 0, 1); PG8_STAGE(PG8_SB(0, 0), b2, voffB); PG8_STAGE(PG8_SB(0, 1), b2 + hstepB, voffB); PG8_STAGE(PG8_SA(0, 0), a2, voffA);
;             PG8_WAIT_V(8); PG8_WAIT_L(0); PG8_BAR; PG8_MMA(1, 0, At, B0); PG8_MMA(1, 1, At, B1); PG8_BAR; PG8_SCHED;
.LBB0_694:
	v_add_u32_e32 v163, 0x10000, v143
	s_add_u32 s44, s42, 0x100
	s_addc_u32 s45, s43, 0
	s_add_i32 s67, 0, 0x10000
	s_cmpk_eq_i32 s66, 0x54
	s_cselect_b32 s53, s37, s45
	s_cselect_b32 s52, s36, s44
	s_cselect_b32 s51, s41, s65
	s_cselect_b32 s50, s40, s64
	s_add_i32 s68, 0, 0x14000
	ds_read_b128 v[146:149], v163
	ds_read_b128 v[150:153], v163 offset:1024
	ds_read_b128 v[154:157], v163 offset:2048
	ds_read_b128 v[158:161], v163 offset:3072
	ds_read_b128 v[186:189], v163 offset:16384
	ds_read_b128 v[190:193], v163 offset:17408
	ds_read_b128 v[194:197], v163 offset:18432
	ds_read_b128 v[198:201], v163 offset:19456
	s_add_i32 m0, s34, 0xc000
	ds_read_b128 v[202:205], v145
	ds_read_b128 v[206:209], v145 offset:1024
	ds_read_b128 v[210:213], v145 offset:2048
	ds_read_b128 v[214:217], v145 offset:3072
	ds_read_b128 v[218:221], v145 offset:4096
	ds_read_b128 v[222:225], v145 offset:5120
	ds_read_b128 v[234:237], v145 offset:6144
	ds_read_b128 v[238:241], v145 offset:7168
	global_load_lds_dwordx4 v138, s[42:43]
	s_add_i32 m0, s34, 0xe000
	s_nop 0
	global_load_lds_dwordx4 v140, s[42:43]
	s_waitcnt vmcnt(8)
	s_waitcnt lgkmcnt(0)
	s_barrier
	v_mfma_f32_16x16x32_bf16 v[128:131], v[146:149], v[202:205], v[128:131]
	v_mfma_f32_16x16x32_bf16 v[124:127], v[154:157], v[202:205], v[124:127]
	v_mfma_f32_16x16x32_bf16 v[120:123], v[146:149], v[210:213], v[120:123]
	v_mfma_f32_16x16x32_bf16 v[116:119], v[154:157], v[210:213], v[116:119]
	v_mfma_f32_16x16x32_bf16 v[104:107], v[146:149], v[218:221], v[104:107]
	v_mfma_f32_16x16x32_bf16 v[100:103], v[154:157], v[218:221], v[100:103]
	v_mfma_f32_16x16x32_bf16 v[88:91], v[146:149], v[234:237], v[88:91]
	v_mfma_f32_16x16x32_bf16 v[84:87], v[154:157], v[234:237], v[84:87]
	v_mfma_f32_16x16x32_bf16 v[128:131], v[150:153], v[206:209], v[128:131]
	v_mfma_f32_16x16x32_bf16 v[124:127], v[158:161], v[206:209], v[124:127]
	v_mfma_f32_16x16x32_bf16 v[120:123], v[150:153], v[214:217], v[120:123]
	v_mfma_f32_16x16x32_bf16 v[116:119], v[158:161], v[214:217], v[116:119]
	v_mfma_f32_16x16x32_bf16 v[104:107], v[150:153], v[222:225], v[104:107]
	v_mfma_f32_16x16x32_bf16 v[100:103], v[158:161], v[222:225], v[100:103]
	v_mfma_f32_16x16x32_bf16 v[88:91], v[150:153], v[238:241], v[88:91]
	v_mfma_f32_16x16x32_bf16 v[84:87], v[158:161], v[238:241], v[84:87]
	v_mfma_f32_16x16x32_bf16 v[112:115], v[186:189], v[202:205], v[112:115]
	v_mfma_f32_16x16x32_bf16 v[108:111], v[194:197], v[202:205], v[108:111]
	v_mfma_f32_16x16x32_bf16 v[96:99], v[186:189], v[210:213], v[96:99]
	v_mfma_f32_16x16x32_bf16 v[92:95], v[194:197], v[210:213], v[92:95]
	v_mfma_f32_16x16x32_bf16 v[80:83], v[186:189], v[218:221], v[80:83]
	v_mfma_f32_16x16x32_bf16 v[76:79], v[194:197], v[218:221], v[76:79]
	v_mfma_f32_16x16x32_bf16 v[72:75], v[186:189], v[234:237], v[72:75]
	v_mfma_f32_16x16x32_bf16 v[68:71], v[194:197], v[234:237], v[68:71]
	v_mfma_f32_16x16x32_bf16 v[112:115], v[190:193], v[206:209], v[112:115]
	v_mfma_f32_16x16x32_bf16 v[108:111], v[198:201], v[206:209], v[108:111]
	v_mfma_f32_16x16x32_bf16 v[96:99], v[190:193], v[214:217], v[96:99]
	v_mfma_f32_16x16x32_bf16 v[92:95], v[198:201], v[214:217], v[92:95]
	v_mfma_f32_16x16x32_bf16 v[80:83], v[190:193], v[222:225], v[80:83]
	v_mfma_f32_16x16x32_bf16 v[76:79], v[198:201], v[222:225], v[76:79]
	v_mfma_f32_16x16x32_bf16 v[72:75], v[190:193], v[238:241], v[72:75]
	v_mfma_f32_16x16x32_bf16 v[68:71], v[198:201], v[238:241], v[68:71]
	s_barrier
	s_add_i32 s42, s67, s15
	s_mov_b32 m0, s42
	ds_read_b128 v[202:205], v145 offset:16384
	ds_read_b128 v[206:209], v145 offset:17408
	ds_read_b128 v[210:213], v145 offset:18432
	ds_read_b128 v[214:217], v145 offset:19456
	ds_read_b128 v[218:221], v145 offset:20480
	ds_read_b128 v[222:225], v145 offset:21504
	ds_read_b128 v[234:237], v145 offset:22528
	ds_read_b128 v[238:241], v145 offset:23552
	global_load_lds_dwordx4 v34, s[50:51]
	s_add_i32 m0, s42, 0x2000
	s_add_u32 s42, s50, 0x160000
	s_addc_u32 s43, s51, 0
	s_add_u32 s98, s50, 0x80
	s_addc_u32 s99, s51, 0
	s_add_i32 s67, s68, s15
	global_load_lds_dwordx4 v136, s[50:51]
	s_mov_b32 m0, s67
	s_nop 0
	global_load_lds_dwordx4 v34, s[42:43]
	s_add_i32 m0, s67, 0x2000
	s_nop 0
	global_load_lds_dwordx4 v136, s[42:43]
	s_mov_b32 m0, s34
	s_nop 0
	global_load_lds_dwordx4 v132, s[52:53]
	s_mov_b32 m0, s35
	s_nop 0
	global_load_lds_dwordx4 v134, s[52:53]
	s_waitcnt vmcnt(8)
	s_waitcnt lgkmcnt(0)
	s_barrier
	v_mfma_f32_16x16x32_bf16 v[64:67], v[146:149], v[202:205], v[64:67]
	v_mfma_f32_16x16x32_bf16 v[60:63], v[154:157], v[202:205], v[60:63]
	v_mfma_f32_16x16x32_bf16 v[56:59], v[146:149], v[210:213], v[56:59]
	v_mfma_f32_16x16x32_bf16 v[52:55], v[154:157], v[210:213], v[52:55]
	v_mfma_f32_16x16x32_bf16 v[40:43], v[146:149], v[218:221], v[40:43]
	v_mfma_f32_16x16x32_bf16 v[36:39], v[154:157], v[218:221], v[36:39]
	v_mfma_f32_16x16x32_bf16 v[22:25], v[146:149], v[234:237], v[22:25]
	v_mfma_f32_16x16x32_bf16 v[18:21], v[154:157], v[234:237], v[18:21]
	v_mfma_f32_16x16x32_bf16 v[64:67], v[150:153], v[206:209], v[64:67]
	v_mfma_f32_16x16x32_bf16 v[60:63], v[158:161], v[206:209], v[60:63]
	v_mfma_f32_16x16x32_bf16 v[56:59], v[150:153], v[214:217], v[56:59]
	v_mfma_f32_16x16x32_bf16 v[52:55], v[158:161], v[214:217], v[52:55]
	v_mfma_f32_16x16x32_bf16 v[40:43], v[150:153], v[222:225], v[40:43]
	v_mfma_f32_16x16x32_bf16 v[36:39], v[158:161], v[222:225], v[36:39]
	v_mfma_f32_16x16x32_bf16 v[22:25], v[150:153], v[238:241], v[22:25]
	v_mfma_f32_16x16x32_bf16 v[18:21], v[158:161], v[238:241], v[18:21]
	v_mfma_f32_16x16x32_bf16 v[48:51], v[186:189], v[202:205], v[48:51]
	v_mfma_f32_16x16x32_bf16 v[44:47], v[194:197], v[202:205], v[44:47]
	v_mfma_f32_16x16x32_bf16 v[30:33], v[186:189], v[210:213], v[30:33]
	v_mfma_f32_16x16x32_bf16 v[26:29], v[194:197], v[210:213], v[26:29]
	v_mfma_f32_16x16x32_bf16 v[14:17], v[186:189], v[218:221], v[14:17]
	v_mfma_f32_16x16x32_bf16 v[10:13], v[194:197], v[218:221], v[10:13]
	v_mfma_f32_16x16x32_bf16 v[6:9], v[186:189], v[234:237], v[6:9]
	v_mfma_f32_16x16x32_bf16 v[2:5], v[194:197], v[234:237], v[2:5]
	v_mfma_f32_16x16x32_bf16 v[48:51], v[190:193], v[206:209], v[48:51]
	v_mfma_f32_16x16x32_bf16 v[44:47], v[198:201], v[206:209], v[44:47]
	v_mfma_f32_16x16x32_bf16 v[30:33], v[190:193], v[214:217], v[30:33]
	v_mfma_f32_16x16x32_bf16 v[26:29], v[198:201], v[214:217], v[26:29]
	v_mfma_f32_16x16x32_bf16 v[14:17], v[190:193], v[222:225], v[14:17]
	v_mfma_f32_16x16x32_bf16 v[10:13], v[198:201], v[222:225], v[10:13]
	v_mfma_f32_16x16x32_bf16 v[6:9], v[190:193], v[238:241], v[6:9]
	v_mfma_f32_16x16x32_bf16 v[2:5], v[198:201], v[238:241], v[2:5]
	s_barrier
; #define PG8_STAGE(bufoff, gbase, voff) do { _Pragma("unroll") for (int _i = 0; _i < 2; ++_i) \
;         __builtin_amdgcn_global_load_lds((const unsigned*)((const char*)(gbase) + (voff)[_i]), (PG8_LAS unsigned*)(lds + (bufoff) + ldsw + _i * 8192), 16, 0, 0); } while (0)
; #define PG8_LDA(dst, b, h) do { _Pragma("unroll") for (int m = 0; m < 4; ++m) _Pragma("unroll") for (int k = 0; k < 2; ++k) dst[m][k] = *(const PG8_LAS bf16x8*)(lds + PG8_SA(b, h) + aoff + m * 2048 + k * 1024); } while (0)
; #define PG8_LDB(dst, b, h) do { _Pragma("unroll") for (int n = 0; n < 2; ++n) _Pragma("unroll") for (int k = 0; k < 2; ++k) dst[n][k] = *(const PG8_LAS bf16x8*)(lds + PG8_SB(b, h) + boff + n * 2048 + k * 1024); } while (0)
; #define PG8_WAIT_V(n) asm volatile("s_waitcnt vmcnt(" #n ")" ::: "memory")
; #define PG8_WAIT_L(n) asm volatile("s_waitcnt lgkmcnt(" #n ")" ::: "memory")
; #define PG8_BAR __builtin_amdgcn_s_barrier()
; #define PG8_SCHED __builtin_amdgcn_sched_barrier(0)
;     ...
;         for (int t = 0; t < nt; t += 2) {
;             const bool last = (t == nt - 2);
;             const char* a1 = cA + (size_t)(t + 1) * kstep;
;             const char* a2 = last ? nA : cA + (size_t)(t + 2) * kstep; const char* b2 = last ? nB : cB + (size_t)(t + 2) * kstep;
;     ...
;             PG8_LDB(B0, 1, 0); PG8_LDB(B1, 1, 1); PG8_SCHED; PG8_LDA(At, 1, 0); PG8_STAGE(PG8_SA(0, 1), a2 + hstepA, voffA);
;             PG8_WAIT_V(8); PG8_WAIT_L(0); PG8_BAR; PG8_MMA(0, 0, At, B0); PG8_MMA(0, 1, At, B1); PG8_BAR; PG8_SCHED;
;             PG8_LDA(At, 1, 1); PG8_STAGE(PG8_SB(1, 0), b3, voffB); PG8_STAGE(PG8_SB(1, 1), b3 + hstepB, voffB); PG8_STAGE(PG8_SA(1, 0), a3, voffA);
;             PG8_WAIT_V(8); PG8_WAIT_L(0); PG8_BAR; PG8_MMA(1, 0, At, B0); PG8_MMA(1, 1, At, B1); PG8_BAR; PG8_SCHED;
	s_add_i32 s67, 0, 0x18000
	s_add_i32 s68, 0, 0x1c000
	ds_read_b128 v[146:149], v163 offset:32768
	ds_read_b128 v[150:153], v163 offset:33792
	ds_read_b128 v[154:157], v163 offset:34816
	ds_read_b128 v[158:161], v163 offset:35840
	ds_read_b128 v[186:189], v163 offset:49152
	ds_read_b128 v[190:193], v163 offset:50176
	ds_read_b128 v[194:197], v163 offset:51200
	ds_read_b128 v[198:201], v163 offset:52224
	s_add_u32 s42, s52, 0x160000
	s_addc_u32 s43, s53, 0
	s_mov_b32 m0, s54
	ds_read_b128 v[202:205], v145 offset:32768
	ds_read_b128 v[206:209], v145 offset:33792
	ds_read_b128 v[210:213], v145 offset:34816
	ds_read_b128 v[214:217], v145 offset:35840
	ds_read_b128 v[218:221], v145 offset:36864
	ds_read_b128 v[222:225], v145 offset:37888
	ds_read_b128 v[234:237], v145 offset:38912
	ds_read_b128 v[238:241], v145 offset:39936
	global_load_lds_dwordx4 v132, s[42:43]
	s_mov_b32 m0, s55
	s_nop 0
	global_load_lds_dwordx4 v134, s[42:43]
	s_waitcnt vmcnt(8)
	s_waitcnt lgkmcnt(0)
	s_barrier
	v_mfma_f32_16x16x32_bf16 v[128:131], v[146:149], v[202:205], v[128:131]
	v_mfma_f32_16x16x32_bf16 v[124:127], v[154:157], v[202:205], v[124:127]
	v_mfma_f32_16x16x32_bf16 v[120:123], v[146:149], v[210:213], v[120:123]
	v_mfma_f32_16x16x32_bf16 v[116:119], v[154:157], v[210:213], v[116:119]
	v_mfma_f32_16x16x32_bf16 v[104:107], v[146:149], v[218:221], v[104:107]
	v_mfma_f32_16x16x32_bf16 v[100:103], v[154:157], v[218:221], v[100:103]
	v_mfma_f32_16x16x32_bf16 v[88:91], v[146:149], v[234:237], v[88:91]
	v_mfma_f32_16x16x32_bf16 v[84:87], v[154:157], v[234:237], v[84:87]
	v_mfma_f32_16x16x32_bf16 v[128:131], v[150:153], v[206:209], v[128:131]
	v_mfma_f32_16x16x32_bf16 v[124:127], v[158:161], v[206:209], v[124:127]
	v_mfma_f32_16x16x32_bf16 v[120:123], v[150:153], v[214:217], v[120:123]
	v_mfma_f32_16x16x32_bf16 v[116:119], v[158:161], v[214:217], v[116:119]
	v_mfma_f32_16x16x32_bf16 v[104:107], v[150:153], v[222:225], v[104:107]
	v_mfma_f32_16x16x32_bf16 v[100:103], v[158:161], v[222:225], v[100:103]
	v_mfma_f32_16x16x32_bf16 v[88:91], v[150:153], v[238:241], v[88:91]
	v_mfma_f32_16x16x32_bf16 v[84:87], v[158:161], v[238:241], v[84:87]
	v_mfma_f32_16x16x32_bf16 v[112:115], v[186:189], v[202:205], v[112:115]
	v_mfma_f32_16x16x32_bf16 v[108:111], v[194:197], v[202:205], v[108:111]
	v_mfma_f32_16x16x32_bf16 v[96:99], v[186:189], v[210:213], v[96:99]
	v_mfma_f32_16x16x32_bf16 v[92:95], v[194:197], v[210:213], v[92:95]
	v_mfma_f32_16x16x32_bf16 v[80:83], v[186:189], v[218:221], v[80:83]
	v_mfma_f32_16x16x32_bf16 v[76:79], v[194:197], v[218:221], v[76:79]
	v_mfma_f32_16x16x32_bf16 v[72:75], v[186:189], v[234:237], v[72:75]
	v_mfma_f32_16x16x32_bf16 v[68:71], v[194:197], v[234:237], v[68:71]
	v_mfma_f32_16x16x32_bf16 v[112:115], v[190:193], v[206:209], v[112:115]
	v_mfma_f32_16x16x32_bf16 v[108:111], v[198:201], v[206:209], v[108:111]
	v_mfma_f32_16x16x32_bf16 v[96:99], v[190:193], v[214:217], v[96:99]
	v_mfma_f32_16x16x32_bf16 v[92:95], v[198:201], v[214:217], v[92:95]
	v_mfma_f32_16x16x32_bf16 v[80:83], v[190:193], v[222:225], v[80:83]
	v_mfma_f32_16x16x32_bf16 v[76:79], v[198:201], v[222:225], v[76:79]
	v_mfma_f32_16x16x32_bf16 v[72:75], v[190:193], v[238:241], v[72:75]
	v_mfma_f32_16x16x32_bf16 v[68:71], v[198:201], v[238:241], v[68:71]
	s_barrier
	s_add_i32 s42, s67, s15
	s_mov_b32 m0, s42
	ds_read_b128 v[202:205], v145 offset:49152
	ds_read_b128 v[206:209], v145 offset:50176
	ds_read_b128 v[210:213], v145 offset:51200
	ds_read_b128 v[214:217], v145 offset:52224
	ds_read_b128 v[218:221], v145 offset:53248
	ds_read_b128 v[222:225], v145 offset:54272
	ds_read_b128 v[234:237], v145 offset:55296
	ds_read_b128 v[238:241], v145 offset:56320
	s_add_u32 vcc_lo, s50, 0x80
	s_addc_u32 vcc_hi, s51, 0
	global_load_lds_dwordx4 v34, vcc
	s_add_i32 m0, s42, 0x2000
	s_add_u32 s42, s50, 0x160080
	s_addc_u32 s43, s51, 0
	s_add_i32 s50, s68, s15
	global_load_lds_dwordx4 v136, s[98:99]
	s_mov_b32 m0, s50
	s_nop 0
	global_load_lds_dwordx4 v34, s[42:43]
	s_add_i32 m0, s50, 0x2000
	s_nop 0
	global_load_lds_dwordx4 v136, s[42:43]
	s_mov_b32 m0, s56
	s_nop 0
	s_add_u32 vcc_lo, s52, 0x80
	s_addc_u32 vcc_hi, s53, 0
	global_load_lds_dwordx4 v132, vcc
	s_mov_b32 m0, s57
	s_nop 0
	s_add_u32 vcc_lo, s52, 0x80
	s_addc_u32 vcc_hi, s53, 0
	global_load_lds_dwordx4 v134, vcc
	s_waitcnt vmcnt(8)
	s_waitcnt lgkmcnt(0)
	s_barrier
	v_mfma_f32_16x16x32_bf16 v[64:67], v[146:149], v[202:205], v[64:67]
	v_mfma_f32_16x16x32_bf16 v[60:63], v[154:157], v[202:205], v[60:63]
	v_mfma_f32_16x16x32_bf16 v[56:59], v[146:149], v[210:213], v[56:59]
	v_mfma_f32_16x16x32_bf16 v[52:55], v[154:157], v[210:213], v[52:55]
	v_mfma_f32_16x16x32_bf16 v[40:43], v[146:149], v[218:221], v[40:43]
	v_mfma_f32_16x16x32_bf16 v[36:39], v[154:157], v[218:221], v[36:39]
	v_mfma_f32_16x16x32_bf16 v[22:25], v[146:149], v[234:237], v[22:25]
	v_mfma_f32_16x16x32_bf16 v[18:21], v[154:157], v[234:237], v[18:21]
	v_mfma_f32_16x16x32_bf16 v[64:67], v[150:153], v[206:209], v[64:67]
	v_mfma_f32_16x16x32_bf16 v[60:63], v[158:161], v[206:209], v[60:63]
	v_mfma_f32_16x16x32_bf16 v[56:59], v[150:153], v[214:217], v[56:59]
	v_mfma_f32_16x16x32_bf16 v[52:55], v[158:161], v[214:217], v[52:55]
	v_mfma_f32_16x16x32_bf16 v[40:43], v[150:153], v[222:225], v[40:43]
	v_mfma_f32_16x16x32_bf16 v[36:39], v[158:161], v[222:225], v[36:39]
	v_mfma_f32_16x16x32_bf16 v[22:25], v[150:153], v[238:241], v[22:25]
	v_mfma_f32_16x16x32_bf16 v[18:21], v[158:161], v[238:241], v[18:21]
	v_mfma_f32_16x16x32_bf16 v[48:51], v[186:189], v[202:205], v[48:51]
	v_mfma_f32_16x16x32_bf16 v[44:47], v[194:197], v[202:205], v[44:47]
	v_mfma_f32_16x16x32_bf16 v[30:33], v[186:189], v[210:213], v[30:33]
	v_mfma_f32_16x16x32_bf16 v[26:29], v[194:197], v[210:213], v[26:29]
	v_mfma_f32_16x16x32_bf16 v[14:17], v[186:189], v[218:221], v[14:17]
	v_mfma_f32_16x16x32_bf16 v[10:13], v[194:197], v[218:221], v[10:13]
	v_mfma_f32_16x16x32_bf16 v[6:9], v[186:189], v[234:237], v[6:9]
	v_mfma_f32_16x16x32_bf16 v[2:5], v[194:197], v[234:237], v[2:5]
	v_mfma_f32_16x16x32_bf16 v[48:51], v[190:193], v[206:209], v[48:51]
	v_mfma_f32_16x16x32_bf16 v[44:47], v[198:201], v[206:209], v[44:47]
	v_mfma_f32_16x16x32_bf16 v[30:33], v[190:193], v[214:217], v[30:33]
	v_mfma_f32_16x16x32_bf16 v[26:29], v[198:201], v[214:217], v[26:29]
	v_mfma_f32_16x16x32_bf16 v[14:17], v[190:193], v[222:225], v[14:17]
	v_mfma_f32_16x16x32_bf16 v[10:13], v[198:201], v[222:225], v[10:13]
	v_mfma_f32_16x16x32_bf16 v[6:9], v[190:193], v[238:241], v[6:9]
	v_mfma_f32_16x16x32_bf16 v[2:5], v[198:201], v[238:241], v[2:5]
	s_barrier
	s_add_i32 s66, s66, 2
	s_add_u32 s64, s64, 0x100
	s_addc_u32 s65, s65, 0
	s_cmpk_gt_u32 s66, 0x55
	s_mov_b64 s[42:43], s[44:45]
	s_cbranch_scc0 .LBB0_694
	s_and_b64 vcc, exec, s[30:31]
	s_cbranch_vccz .LBB0_697
	s_barrier

; #define PG8_STAGE(bufoff, gbase, voff) do { _Pragma("unroll") for (int _i = 0; _i < 2; ++_i) \
;         __builtin_amdgcn_global_load_lds((const unsigned*)((const char*)(gbase) + (voff)[_i]), (PG8_LAS unsigned*)(lds + (bufoff) + ldsw + _i * 8192), 16, 0, 0); } while (0)
; #define PG8_LDA(dst, b, h) do { _Pragma("unroll") for (int m = 0; m < 4; ++m) _Pragma("unroll") for (int k = 0; k < 2; ++k) dst[m][k] = *(const PG8_LAS bf16x8*)(lds + PG8_SA(b, h) + aoff + m * 2048 + k * 1024); } while (0)
; #define PG8_LDB(dst, b, h) do { _Pragma("unroll") for (int n = 0; n < 2; ++n) _Pragma("unroll") for (int k = 0; k < 2; ++k) dst[n][k] = *(const PG8_LAS bf16x8*)(lds + PG8_SB(b, h) + boff + n * 2048 + k * 1024); } while (0)
; #define PG8_WAIT_V(n) asm volatile("s_waitcnt vmcnt(" #n ")" ::: "memory")
; #define PG8_WAIT_L(n) asm volatile("s_waitcnt lgkmcnt(" #n ")" ::: "memory")
; #define PG8_BAR __builtin_amdgcn_s_barrier()
; #define PG8_SCHED __builtin_amdgcn_sched_barrier(0)
; __device__ __forceinline__ void mfma_fp8_acc(f32x4& acc, const i32x8 b, const i32x8 a) { asm volatile("v_mfma_f32_16x16x128_f8f6f4 %0, %1, %2, %0" : "+v"(acc) : "v"(b), "v"(a)); }
;     ...
;         for (int t = 0; t < nt; t += 2) {
;             const bool last = (t == nt - 2);
;             const char* a1 = cA + (size_t)(t + 1) * kstep;
;             const char* a2 = last ? nA : cA + (size_t)(t + 2) * kstep; const char* b2 = last ? nB : cB + (size_t)(t + 2) * kstep;
;             const char* a3 = a2 + kstep; const char* b3 = b2 + kstep;
;             if (last && has_next) S.a_ready(nxt);
;             if constexpr (SP2) {
;             PG8_LDB(B0, 0, 0); PG8_LDB(B1, 0, 1); PG8_SCHED; PG8_LDA(At, 0, 0); PG8_STAGE(PG8_SA(1, 1), a1 + hstepA, voffA);
;             PG8_WAIT_V(8); PG8_WAIT_L(0); PG8_BAR; PG8_MMA(0, 0, At, B0); PG8_MMA(0, 1, At, B1); PG8_BAR; PG8_SCHED;
;             PG8_LDA(At, 0, 1); PG8_STAGE(PG8_SB(0, 0), b2, voffB); PG8_STAGE(PG8_SB(0, 1), b2 + hstepB, voffB); PG8_STAGE(PG8_SA(0, 0), a2, voffA);
;             PG8_WAIT_V(8); PG8_WAIT_L(0); PG8_BAR; PG8_MMA(1, 0, At, B0); PG8_MMA(1, 1, At, B1); PG8_BAR; PG8_SCHED;
.LBB0_726:
	v_add_u32_e32 v250, 0x10000, v209
	s_add_u32 s40, s42, 0x100
	s_addc_u32 s41, s43, 0
	s_add_i32 s64, 0, 0x10000
	s_cmp_eq_u32 s63, 40
	s_cselect_b32 s51, s31, s41
	s_cselect_b32 s50, s30, s40
	s_cselect_b32 s45, s37, s62
	s_cselect_b32 s44, s36, s61
	s_add_i32 s65, 0, 0x14000
	ds_read_b128 v[26:29], v250
	ds_read_b128 v[30:33], v250 offset:1024
	ds_read_b128 v[18:21], v250 offset:2048
	ds_read_b128 v[22:25], v250 offset:3072
	ds_read_b128 v[10:13], v250 offset:16384
	ds_read_b128 v[14:17], v250 offset:17408
	ds_read_b128 v[2:5], v250 offset:18432
	ds_read_b128 v[6:9], v250 offset:19456
	s_add_i32 m0, s21, 0xc000
	ds_read_b128 v[200:203], v211
	ds_read_b128 v[204:207], v211 offset:1024
	ds_read_b128 v[212:215], v211 offset:2048
	ds_read_b128 v[216:219], v211 offset:3072
	ds_read_b128 v[220:223], v211 offset:4096
	ds_read_b128 v[224:227], v211 offset:5120
	ds_read_b128 v[234:237], v211 offset:6144
	ds_read_b128 v[238:241], v211 offset:7168
	global_load_lds_dwordx4 v196, s[42:43]
	s_add_i32 m0, s21, 0xe000
	s_nop 0
	global_load_lds_dwordx4 v198, s[42:43]
	s_waitcnt vmcnt(8)
	s_waitcnt lgkmcnt(0)
	s_barrier
	v_mfma_f32_16x16x128_f8f6f4 v[160:163], v[26:33], v[200:207], v[160:163]
	v_mfma_f32_16x16x128_f8f6f4 v[156:159], v[18:25], v[200:207], v[156:159]
	v_mfma_f32_16x16x128_f8f6f4 v[152:155], v[26:33], v[212:219], v[152:155]
	v_mfma_f32_16x16x128_f8f6f4 v[144:147], v[18:25], v[212:219], v[144:147]
	v_mfma_f32_16x16x128_f8f6f4 v[136:139], v[26:33], v[220:227], v[136:139]
	v_mfma_f32_16x16x128_f8f6f4 v[128:131], v[18:25], v[220:227], v[128:131]
	v_mfma_f32_16x16x128_f8f6f4 v[120:123], v[26:33], v[234:241], v[120:123]
	v_mfma_f32_16x16x128_f8f6f4 v[112:115], v[18:25], v[234:241], v[112:115]
	v_mfma_f32_16x16x128_f8f6f4 v[148:151], v[10:17], v[200:207], v[148:151]
	v_mfma_f32_16x16x128_f8f6f4 v[140:143], v[2:9], v[200:207], v[140:143]
	v_mfma_f32_16x16x128_f8f6f4 v[132:135], v[10:17], v[212:219], v[132:135]
	v_mfma_f32_16x16x128_f8f6f4 v[124:127], v[2:9], v[212:219], v[124:127]
	v_mfma_f32_16x16x128_f8f6f4 v[116:119], v[10:17], v[220:227], v[116:119]
	v_mfma_f32_16x16x128_f8f6f4 v[108:111], v[2:9], v[220:227], v[108:111]
	v_mfma_f32_16x16x128_f8f6f4 v[104:107], v[10:17], v[234:241], v[104:107]
	v_mfma_f32_16x16x128_f8f6f4 v[100:103], v[2:9], v[234:241], v[100:103]
	s_barrier
	s_add_i32 s42, s64, s15
	s_mov_b32 m0, s42
	ds_read_b128 v[212:215], v211 offset:16384
	ds_read_b128 v[216:219], v211 offset:17408
	ds_read_b128 v[220:223], v211 offset:18432
	ds_read_b128 v[224:227], v211 offset:19456
	ds_read_b128 v[234:237], v211 offset:20480
	ds_read_b128 v[238:241], v211 offset:21504
	ds_read_b128 v[242:245], v211 offset:22528
	ds_read_b128 v[246:249], v211 offset:23552
	global_load_lds_dwordx4 v34, s[44:45]
	s_add_i32 m0, s42, 0x2000
	s_add_u32 s42, s44, 0xb0000
	s_addc_u32 s43, s45, 0
	s_add_u32 s98, s44, 0x80
	s_addc_u32 s99, s45, 0
	s_add_i32 s64, s65, s15
	global_load_lds_dwordx4 v190, s[44:45]
	s_mov_b32 m0, s64
	s_nop 0
	global_load_lds_dwordx4 v34, s[42:43]
	s_add_i32 m0, s64, 0x2000
	s_nop 0
	global_load_lds_dwordx4 v190, s[42:43]
	s_mov_b32 m0, s21
	s_nop 0
	global_load_lds_dwordx4 v186, s[50:51]
	s_mov_b32 m0, s34
	s_nop 0
	global_load_lds_dwordx4 v188, s[50:51]
	s_waitcnt vmcnt(8)
	s_waitcnt lgkmcnt(0)
	s_barrier
	v_mfma_f32_16x16x128_f8f6f4 v[96:99], v[26:33], v[212:219], v[96:99]
	v_mfma_f32_16x16x128_f8f6f4 v[92:95], v[18:25], v[212:219], v[92:95]
	v_mfma_f32_16x16x128_f8f6f4 v[88:91], v[26:33], v[220:227], v[88:91]
	v_mfma_f32_16x16x128_f8f6f4 v[80:83], v[18:25], v[220:227], v[80:83]
	v_mfma_f32_16x16x128_f8f6f4 v[72:75], v[26:33], v[234:241], v[72:75]
	v_mfma_f32_16x16x128_f8f6f4 v[64:67], v[18:25], v[234:241], v[64:67]
	v_mfma_f32_16x16x128_f8f6f4 v[56:59], v[26:33], v[242:249], v[56:59]
	v_mfma_f32_16x16x128_f8f6f4 v[48:51], v[18:25], v[242:249], v[48:51]
	v_mfma_f32_16x16x128_f8f6f4 v[84:87], v[10:17], v[212:219], v[84:87]
	v_mfma_f32_16x16x128_f8f6f4 v[76:79], v[2:9], v[212:219], v[76:79]
	v_mfma_f32_16x16x128_f8f6f4 v[68:71], v[10:17], v[220:227], v[68:71]
	v_mfma_f32_16x16x128_f8f6f4 v[60:63], v[2:9], v[220:227], v[60:63]
	v_mfma_f32_16x16x128_f8f6f4 v[52:55], v[10:17], v[234:241], v[52:55]
	v_mfma_f32_16x16x128_f8f6f4 v[44:47], v[2:9], v[234:241], v[44:47]
	v_mfma_f32_16x16x128_f8f6f4 v[40:43], v[10:17], v[242:249], v[40:43]
	v_mfma_f32_16x16x128_f8f6f4 v[36:39], v[2:9], v[242:249], v[36:39]
	s_barrier
; #define PG8_STAGE(bufoff, gbase, voff) do { _Pragma("unroll") for (int _i = 0; _i < 2; ++_i) \
;         __builtin_amdgcn_global_load_lds((const unsigned*)((const char*)(gbase) + (voff)[_i]), (PG8_LAS unsigned*)(lds + (bufoff) + ldsw + _i * 8192), 16, 0, 0); } while (0)
; #define PG8_LDA(dst, b, h) do { _Pragma("unroll") for (int m = 0; m < 4; ++m) _Pragma("unroll") for (int k = 0; k < 2; ++k) dst[m][k] = *(const PG8_LAS bf16x8*)(lds + PG8_SA(b, h) + aoff + m * 2048 + k * 1024); } while (0)
; #define PG8_LDB(dst, b, h) do { _Pragma("unroll") for (int n = 0; n < 2; ++n) _Pragma("unroll") for (int k = 0; k < 2; ++k) dst[n][k] = *(const PG8_LAS bf16x8*)(lds + PG8_SB(b, h) + boff + n * 2048 + k * 1024); } while (0)
; #define PG8_WAIT_V(n) asm volatile("s_waitcnt vmcnt(" #n ")" ::: "memory")
; #define PG8_WAIT_L(n) asm volatile("s_waitcnt lgkmcnt(" #n ")" ::: "memory")
; #define PG8_BAR __builtin_amdgcn_s_barrier()
; #define PG8_SCHED __builtin_amdgcn_sched_barrier(0)
;     ...
;         for (int t = 0; t < nt; t += 2) {
;             const bool last = (t == nt - 2);
;             const char* a1 = cA + (size_t)(t + 1) * kstep;
;             const char* a2 = last ? nA : cA + (size_t)(t + 2) * kstep; const char* b2 = last ? nB : cB + (size_t)(t + 2) * kstep;
;     ...
;             PG8_LDB(B0, 1, 0); PG8_LDB(B1, 1, 1); PG8_SCHED; PG8_LDA(At, 1, 0); PG8_STAGE(PG8_SA(0, 1), a2 + hstepA, voffA);
;             PG8_WAIT_V(8); PG8_WAIT_L(0); PG8_BAR; PG8_MMA(0, 0, At, B0); PG8_MMA(0, 1, At, B1); PG8_BAR; PG8_SCHED;
;             PG8_LDA(At, 1, 1); PG8_STAGE(PG8_SB(1, 0), b3, voffB); PG8_STAGE(PG8_SB(1, 1), b3 + hstepB, voffB); PG8_STAGE(PG8_SA(1, 0), a3, voffA);
;             PG8_WAIT_V(8); PG8_WAIT_L(0); PG8_BAR; PG8_MMA(1, 0, At, B0); PG8_MMA(1, 1, At, B1); PG8_BAR; PG8_SCHED;
	s_add_i32 s64, 0, 0x18000
	s_add_i32 s65, 0, 0x1c000
	ds_read_b128 v[2:5], v250 offset:32768
	ds_read_b128 v[6:9], v250 offset:33792
	ds_read_b128 v[10:13], v250 offset:34816
	ds_read_b128 v[14:17], v250 offset:35840
	ds_read_b128 v[18:21], v250 offset:49152
	ds_read_b128 v[22:25], v250 offset:50176
	ds_read_b128 v[26:29], v250 offset:51200
	ds_read_b128 v[30:33], v250 offset:52224
	s_add_u32 s42, s50, 0xb0000
	s_addc_u32 s43, s51, 0
	s_mov_b32 m0, s35
	ds_read_b128 v[212:215], v211 offset:32768
	ds_read_b128 v[216:219], v211 offset:33792
	ds_read_b128 v[220:223], v211 offset:34816
	ds_read_b128 v[224:227], v211 offset:35840
	ds_read_b128 v[234:237], v211 offset:36864
	ds_read_b128 v[238:241], v211 offset:37888
	ds_read_b128 v[242:245], v211 offset:38912
	ds_read_b128 v[246:249], v211 offset:39936
	global_load_lds_dwordx4 v186, s[42:43]
	s_mov_b32 m0, s52
	s_nop 0
	global_load_lds_dwordx4 v188, s[42:43]
	s_waitcnt vmcnt(8)
	s_waitcnt lgkmcnt(0)
	s_barrier
	v_mfma_f32_16x16x128_f8f6f4 v[160:163], v[2:9], v[212:219], v[160:163]
	v_mfma_f32_16x16x128_f8f6f4 v[156:159], v[10:17], v[212:219], v[156:159]
	v_mfma_f32_16x16x128_f8f6f4 v[152:155], v[2:9], v[220:227], v[152:155]
	v_mfma_f32_16x16x128_f8f6f4 v[144:147], v[10:17], v[220:227], v[144:147]
	v_mfma_f32_16x16x128_f8f6f4 v[136:139], v[2:9], v[234:241], v[136:139]
	v_mfma_f32_16x16x128_f8f6f4 v[128:131], v[10:17], v[234:241], v[128:131]
	v_mfma_f32_16x16x128_f8f6f4 v[120:123], v[2:9], v[242:249], v[120:123]
	v_mfma_f32_16x16x128_f8f6f4 v[112:115], v[10:17], v[242:249], v[112:115]
	v_mfma_f32_16x16x128_f8f6f4 v[148:151], v[18:25], v[212:219], v[148:151]
	v_mfma_f32_16x16x128_f8f6f4 v[140:143], v[26:33], v[212:219], v[140:143]
	v_mfma_f32_16x16x128_f8f6f4 v[132:135], v[18:25], v[220:227], v[132:135]
	v_mfma_f32_16x16x128_f8f6f4 v[124:127], v[26:33], v[220:227], v[124:127]
	v_mfma_f32_16x16x128_f8f6f4 v[116:119], v[18:25], v[234:241], v[116:119]
	v_mfma_f32_16x16x128_f8f6f4 v[108:111], v[26:33], v[234:241], v[108:111]
	v_mfma_f32_16x16x128_f8f6f4 v[104:107], v[18:25], v[242:249], v[104:107]
	v_mfma_f32_16x16x128_f8f6f4 v[100:103], v[26:33], v[242:249], v[100:103]
	s_barrier
	s_add_i32 s42, s64, s15
	s_mov_b32 m0, s42
	ds_read_b128 v[212:215], v211 offset:49152
	ds_read_b128 v[216:219], v211 offset:50176
	ds_read_b128 v[220:223], v211 offset:51200
	ds_read_b128 v[224:227], v211 offset:52224
	ds_read_b128 v[234:237], v211 offset:53248
	ds_read_b128 v[238:241], v211 offset:54272
	ds_read_b128 v[242:245], v211 offset:55296
	ds_read_b128 v[246:249], v211 offset:56320
	s_add_u32 vcc_lo, s44, 0x80
	s_addc_u32 vcc_hi, s45, 0
	global_load_lds_dwordx4 v34, vcc
	s_add_i32 m0, s42, 0x2000
	s_add_u32 s42, s44, 0xb0080
	s_addc_u32 s43, s45, 0
	s_add_i32 s44, s65, s15
	global_load_lds_dwordx4 v190, s[98:99]
	s_mov_b32 m0, s44
	s_nop 0
	global_load_lds_dwordx4 v34, s[42:43]
	s_add_i32 m0, s44, 0x2000
	s_nop 0
	global_load_lds_dwordx4 v190, s[42:43]
	s_mov_b32 m0, s53
	s_nop 0
	s_add_u32 vcc_lo, s50, 0x80
	s_addc_u32 vcc_hi, s51, 0
	global_load_lds_dwordx4 v186, vcc
	s_mov_b32 m0, s54
	s_nop 0
	s_add_u32 vcc_lo, s50, 0x80
	s_addc_u32 vcc_hi, s51, 0
	global_load_lds_dwordx4 v188, vcc
	s_waitcnt vmcnt(8)
	s_waitcnt lgkmcnt(0)
	s_barrier
	v_mfma_f32_16x16x128_f8f6f4 v[96:99], v[2:9], v[212:219], v[96:99]
	v_mfma_f32_16x16x128_f8f6f4 v[92:95], v[10:17], v[212:219], v[92:95]
	v_mfma_f32_16x16x128_f8f6f4 v[88:91], v[2:9], v[220:227], v[88:91]
	v_mfma_f32_16x16x128_f8f6f4 v[80:83], v[10:17], v[220:227], v[80:83]
	v_mfma_f32_16x16x128_f8f6f4 v[72:75], v[2:9], v[234:241], v[72:75]
	v_mfma_f32_16x16x128_f8f6f4 v[64:67], v[10:17], v[234:241], v[64:67]
	v_mfma_f32_16x16x128_f8f6f4 v[56:59], v[2:9], v[242:249], v[56:59]
	v_mfma_f32_16x16x128_f8f6f4 v[48:51], v[10:17], v[242:249], v[48:51]
	v_mfma_f32_16x16x128_f8f6f4 v[84:87], v[18:25], v[212:219], v[84:87]
	v_mfma_f32_16x16x128_f8f6f4 v[76:79], v[26:33], v[212:219], v[76:79]
	v_mfma_f32_16x16x128_f8f6f4 v[68:71], v[18:25], v[220:227], v[68:71]
	v_mfma_f32_16x16x128_f8f6f4 v[60:63], v[26:33], v[220:227], v[60:63]
	v_mfma_f32_16x16x128_f8f6f4 v[52:55], v[18:25], v[234:241], v[52:55]
	v_mfma_f32_16x16x128_f8f6f4 v[44:47], v[26:33], v[234:241], v[44:47]
	v_mfma_f32_16x16x128_f8f6f4 v[40:43], v[18:25], v[242:249], v[40:43]
	v_mfma_f32_16x16x128_f8f6f4 v[36:39], v[26:33], v[242:249], v[36:39]
	s_barrier
	s_add_i32 s63, s63, 2
	s_add_u32 s61, s61, 0x100
	s_addc_u32 s62, s62, 0
	s_cmp_gt_u32 s63, 41
	s_mov_b64 s[42:43], s[40:41]
	s_cbranch_scc0 .LBB0_726
	s_and_b64 vcc, exec, s[28:29]
	s_cbranch_vccz .LBB0_729
	s_barrier

; #define PG8_STAGE(bufoff, gbase, voff) do { _Pragma("unroll") for (int _i = 0; _i < 2; ++_i) \
;         __builtin_amdgcn_global_load_lds((const unsigned*)((const char*)(gbase) + (voff)[_i]), (PG8_LAS unsigned*)(lds + (bufoff) + ldsw + _i * 8192), 16, 0, 0); } while (0)
; #define PG8_LDA(dst, b, h) do { _Pragma("unroll") for (int m = 0; m < 4; ++m) _Pragma("unroll") for (int k = 0; k < 2; ++k) dst[m][k] = *(const PG8_LAS bf16x8*)(lds + PG8_SA(b, h) + aoff + m * 2048 + k * 1024); } while (0)
; #define PG8_LDB(dst, b, h) do { _Pragma("unroll") for (int n = 0; n < 2; ++n) _Pragma("unroll") for (int k = 0; k < 2; ++k) dst[n][k] = *(const PG8_LAS bf16x8*)(lds + PG8_SB(b, h) + boff + n * 2048 + k * 1024); } while (0)
; #define PG8_WAIT_V(n) asm volatile("s_waitcnt vmcnt(" #n ")" ::: "memory")
; #define PG8_WAIT_L(n) asm volatile("s_waitcnt lgkmcnt(" #n ")" ::: "memory")
; #define PG8_BAR __builtin_amdgcn_s_barrier()
; #define PG8_SCHED __builtin_amdgcn_sched_barrier(0)
;     ...
;         for (int t = 0; t < nt; t += 2) {
;             const bool last = (t == nt - 2);
;             const char* a1 = cA + (size_t)(t + 1) * kstep;
;             const char* a2 = last ? nA : cA + (size_t)(t + 2) * kstep; const char* b2 = last ? nB : cB + (size_t)(t + 2) * kstep;
;             const char* a3 = a2 + kstep; const char* b3 = b2 + kstep;
;             if (last && has_next) S.a_ready(nxt);
;             if constexpr (SP2) {
;             PG8_LDB(B0, 0, 0); PG8_LDB(B1, 0, 1); PG8_SCHED; PG8_LDA(At, 0, 0); PG8_STAGE(PG8_SA(1, 1), a1 + hstepA, voffA);
;             PG8_WAIT_V(8); PG8_WAIT_L(0); PG8_BAR; PG8_MMA(0, 0, At, B0); PG8_MMA(0, 1, At, B1); PG8_BAR; PG8_SCHED;
;             PG8_LDA(At, 0, 1); PG8_STAGE(PG8_SB(0, 0), b2, voffB); PG8_STAGE(PG8_SB(0, 1), b2 + hstepB, voffB); PG8_STAGE(PG8_SA(0, 0), a2, voffA);
;             PG8_WAIT_V(8); PG8_WAIT_L(0); PG8_BAR; PG8_MMA(1, 0, At, B0); PG8_MMA(1, 1, At, B1); PG8_BAR; PG8_SCHED;
.LBB0_923:
	v_add_u32_e32 v226, 0x10000, v153
	s_add_u32 s56, s52, 0xfff80080
	s_addc_u32 s57, s53, -1
	s_add_i32 s68, 0, 0x10000
	s_cmp_eq_u32 s47, 28
	s_cselect_b32 s59, s6, s57
	s_cselect_b32 s58, s15, s56
	s_cselect_b32 s57, s34, s41
	s_cselect_b32 s56, s35, s37
	s_add_i32 s76, 0, 0x14000
	s_waitcnt vmcnt(0)
	ds_read_b128 v[132:135], v226
	ds_read_b128 v[136:139], v226 offset:1024
	ds_read_b128 v[156:159], v226 offset:2048
	ds_read_b128 v[160:163], v226 offset:3072
	ds_read_b128 v[186:189], v226 offset:16384
	ds_read_b128 v[190:193], v226 offset:17408
	ds_read_b128 v[194:197], v226 offset:18432
	ds_read_b128 v[198:201], v226 offset:19456
	s_add_i32 m0, s10, 0xc000
	ds_read_b128 v[202:205], v155
	ds_read_b128 v[206:209], v155 offset:1024
	ds_read_b128 v[210:213], v155 offset:2048
	ds_read_b128 v[214:217], v155 offset:3072
	ds_read_b128 v[218:221], v155 offset:4096
	ds_read_b128 v[222:225], v155 offset:5120
	ds_read_b128 v[234:237], v155 offset:6144
	ds_read_b128 v[238:241], v155 offset:7168
	global_load_lds_dwordx4 v148, s[52:53]
	s_add_i32 m0, s10, 0xe000
	s_nop 0
	global_load_lds_dwordx4 v150, s[52:53]
	s_waitcnt vmcnt(8)
	s_waitcnt lgkmcnt(0)
	s_barrier
	v_mfma_f32_16x16x32_bf16 v[128:131], v[132:135], v[202:205], v[128:131]
	v_mfma_f32_16x16x32_bf16 v[124:127], v[156:159], v[202:205], v[124:127]
	v_mfma_f32_16x16x32_bf16 v[112:115], v[132:135], v[210:213], v[112:115]
	v_mfma_f32_16x16x32_bf16 v[108:111], v[156:159], v[210:213], v[108:111]
	v_mfma_f32_16x16x32_bf16 v[96:99], v[132:135], v[218:221], v[96:99]
	v_mfma_f32_16x16x32_bf16 v[92:95], v[156:159], v[218:221], v[92:95]
	v_mfma_f32_16x16x32_bf16 v[80:83], v[132:135], v[234:237], v[80:83]
	v_mfma_f32_16x16x32_bf16 v[76:79], v[156:159], v[234:237], v[76:79]
	v_mfma_f32_16x16x32_bf16 v[128:131], v[136:139], v[206:209], v[128:131]
	v_mfma_f32_16x16x32_bf16 v[124:127], v[160:163], v[206:209], v[124:127]
	v_mfma_f32_16x16x32_bf16 v[112:115], v[136:139], v[214:217], v[112:115]
	v_mfma_f32_16x16x32_bf16 v[108:111], v[160:163], v[214:217], v[108:111]
	v_mfma_f32_16x16x32_bf16 v[96:99], v[136:139], v[222:225], v[96:99]
	v_mfma_f32_16x16x32_bf16 v[92:95], v[160:163], v[222:225], v[92:95]
	v_mfma_f32_16x16x32_bf16 v[80:83], v[136:139], v[238:241], v[80:83]
	v_mfma_f32_16x16x32_bf16 v[76:79], v[160:163], v[238:241], v[76:79]
	v_mfma_f32_16x16x32_bf16 v[120:123], v[186:189], v[202:205], v[120:123]
	v_mfma_f32_16x16x32_bf16 v[116:119], v[194:197], v[202:205], v[116:119]
	v_mfma_f32_16x16x32_bf16 v[104:107], v[186:189], v[210:213], v[104:107]
	v_mfma_f32_16x16x32_bf16 v[100:103], v[194:197], v[210:213], v[100:103]
	v_mfma_f32_16x16x32_bf16 v[88:91], v[186:189], v[218:221], v[88:91]
	v_mfma_f32_16x16x32_bf16 v[84:87], v[194:197], v[218:221], v[84:87]
	v_mfma_f32_16x16x32_bf16 v[72:75], v[186:189], v[234:237], v[72:75]
	v_mfma_f32_16x16x32_bf16 v[68:71], v[194:197], v[234:237], v[68:71]
	v_mfma_f32_16x16x32_bf16 v[120:123], v[190:193], v[206:209], v[120:123]
	v_mfma_f32_16x16x32_bf16 v[116:119], v[198:201], v[206:209], v[116:119]
	v_mfma_f32_16x16x32_bf16 v[104:107], v[190:193], v[214:217], v[104:107]
	v_mfma_f32_16x16x32_bf16 v[100:103], v[198:201], v[214:217], v[100:103]
	v_mfma_f32_16x16x32_bf16 v[88:91], v[190:193], v[222:225], v[88:91]
	v_mfma_f32_16x16x32_bf16 v[84:87], v[198:201], v[222:225], v[84:87]
	v_mfma_f32_16x16x32_bf16 v[72:75], v[190:193], v[238:241], v[72:75]
	v_mfma_f32_16x16x32_bf16 v[68:71], v[198:201], v[238:241], v[68:71]
	s_barrier
	s_add_i32 s68, s68, s9
	s_mov_b32 m0, s68
	ds_read_b128 v[202:205], v155 offset:16384
	ds_read_b128 v[206:209], v155 offset:17408
	ds_read_b128 v[210:213], v155 offset:18432
	ds_read_b128 v[214:217], v155 offset:19456
	ds_read_b128 v[218:221], v155 offset:20480
	ds_read_b128 v[222:225], v155 offset:21504
	ds_read_b128 v[234:237], v155 offset:22528
	ds_read_b128 v[238:241], v155 offset:23552
	global_load_lds_dwordx4 v142, s[56:57]
	s_add_i32 m0, s68, 0x2000
	s_add_u32 s70, s56, 0x80000
	s_addc_u32 s71, s57, 0
	s_add_i32 s68, s76, s9
	global_load_lds_dwordx4 v146, s[56:57]
	s_mov_b32 m0, s68
	s_add_u32 s98, s58, 0x80
	s_addc_u32 s99, s59, 0
	global_load_lds_dwordx4 v142, s[70:71]
	s_add_i32 m0, s68, 0x2000
	s_nop 0
	global_load_lds_dwordx4 v146, s[70:71]
	s_mov_b32 m0, s10
	s_nop 0
	global_load_lds_dwordx4 v140, s[58:59]
	s_mov_b32 m0, s11
	s_nop 0
	global_load_lds_dwordx4 v144, s[58:59]
	s_waitcnt vmcnt(8)
	s_waitcnt lgkmcnt(0)
	s_barrier
	v_mfma_f32_16x16x32_bf16 v[64:67], v[132:135], v[202:205], v[64:67]
	v_mfma_f32_16x16x32_bf16 v[60:63], v[156:159], v[202:205], v[60:63]
	v_mfma_f32_16x16x32_bf16 v[48:51], v[132:135], v[210:213], v[48:51]
	v_mfma_f32_16x16x32_bf16 v[44:47], v[156:159], v[210:213], v[44:47]
	v_mfma_f32_16x16x32_bf16 v[30:33], v[132:135], v[218:221], v[30:33]
	v_mfma_f32_16x16x32_bf16 v[26:29], v[156:159], v[218:221], v[26:29]
	v_mfma_f32_16x16x32_bf16 v[14:17], v[132:135], v[234:237], v[14:17]
	v_mfma_f32_16x16x32_bf16 v[10:13], v[156:159], v[234:237], v[10:13]
	v_mfma_f32_16x16x32_bf16 v[64:67], v[136:139], v[206:209], v[64:67]
	v_mfma_f32_16x16x32_bf16 v[60:63], v[160:163], v[206:209], v[60:63]
	v_mfma_f32_16x16x32_bf16 v[48:51], v[136:139], v[214:217], v[48:51]
	v_mfma_f32_16x16x32_bf16 v[44:47], v[160:163], v[214:217], v[44:47]
	v_mfma_f32_16x16x32_bf16 v[30:33], v[136:139], v[222:225], v[30:33]
	v_mfma_f32_16x16x32_bf16 v[26:29], v[160:163], v[222:225], v[26:29]
	v_mfma_f32_16x16x32_bf16 v[14:17], v[136:139], v[238:241], v[14:17]
	v_mfma_f32_16x16x32_bf16 v[10:13], v[160:163], v[238:241], v[10:13]
	v_mfma_f32_16x16x32_bf16 v[56:59], v[186:189], v[202:205], v[56:59]
	v_mfma_f32_16x16x32_bf16 v[52:55], v[194:197], v[202:205], v[52:55]
	v_mfma_f32_16x16x32_bf16 v[40:43], v[186:189], v[210:213], v[40:43]
	v_mfma_f32_16x16x32_bf16 v[36:39], v[194:197], v[210:213], v[36:39]
	v_mfma_f32_16x16x32_bf16 v[22:25], v[186:189], v[218:221], v[22:25]
	v_mfma_f32_16x16x32_bf16 v[18:21], v[194:197], v[218:221], v[18:21]
	v_mfma_f32_16x16x32_bf16 v[6:9], v[186:189], v[234:237], v[6:9]
	v_mfma_f32_16x16x32_bf16 v[2:5], v[194:197], v[234:237], v[2:5]
	v_mfma_f32_16x16x32_bf16 v[56:59], v[190:193], v[206:209], v[56:59]
	v_mfma_f32_16x16x32_bf16 v[52:55], v[198:201], v[206:209], v[52:55]
	v_mfma_f32_16x16x32_bf16 v[40:43], v[190:193], v[214:217], v[40:43]
	v_mfma_f32_16x16x32_bf16 v[36:39], v[198:201], v[214:217], v[36:39]
	v_mfma_f32_16x16x32_bf16 v[22:25], v[190:193], v[222:225], v[22:25]
	v_mfma_f32_16x16x32_bf16 v[18:21], v[198:201], v[222:225], v[18:21]
	v_mfma_f32_16x16x32_bf16 v[6:9], v[190:193], v[238:241], v[6:9]
	v_mfma_f32_16x16x32_bf16 v[2:5], v[198:201], v[238:241], v[2:5]
	s_barrier
; #define PG8_STAGE(bufoff, gbase, voff) do { _Pragma("unroll") for (int _i = 0; _i < 2; ++_i) \
;         __builtin_amdgcn_global_load_lds((const unsigned*)((const char*)(gbase) + (voff)[_i]), (PG8_LAS unsigned*)(lds + (bufoff) + ldsw + _i * 8192), 16, 0, 0); } while (0)
; #define PG8_LDA(dst, b, h) do { _Pragma("unroll") for (int m = 0; m < 4; ++m) _Pragma("unroll") for (int k = 0; k < 2; ++k) dst[m][k] = *(const PG8_LAS bf16x8*)(lds + PG8_SA(b, h) + aoff + m * 2048 + k * 1024); } while (0)
; #define PG8_LDB(dst, b, h) do { _Pragma("unroll") for (int n = 0; n < 2; ++n) _Pragma("unroll") for (int k = 0; k < 2; ++k) dst[n][k] = *(const PG8_LAS bf16x8*)(lds + PG8_SB(b, h) + boff + n * 2048 + k * 1024); } while (0)
; #define PG8_WAIT_V(n) asm volatile("s_waitcnt vmcnt(" #n ")" ::: "memory")
; #define PG8_WAIT_L(n) asm volatile("s_waitcnt lgkmcnt(" #n ")" ::: "memory")
; #define PG8_BAR __builtin_amdgcn_s_barrier()
; #define PG8_SCHED __builtin_amdgcn_sched_barrier(0)
;     ...
;         for (int t = 0; t < nt; t += 2) {
;             const bool last = (t == nt - 2);
;             const char* a1 = cA + (size_t)(t + 1) * kstep;
;             const char* a2 = last ? nA : cA + (size_t)(t + 2) * kstep; const char* b2 = last ? nB : cB + (size_t)(t + 2) * kstep;
;     ...
;             PG8_LDB(B0, 1, 0); PG8_LDB(B1, 1, 1); PG8_SCHED; PG8_LDA(At, 1, 0); PG8_STAGE(PG8_SA(0, 1), a2 + hstepA, voffA);
;             PG8_WAIT_V(8); PG8_WAIT_L(0); PG8_BAR; PG8_MMA(0, 0, At, B0); PG8_MMA(0, 1, At, B1); PG8_BAR; PG8_SCHED;
;             PG8_LDA(At, 1, 1); PG8_STAGE(PG8_SB(1, 0), b3, voffB); PG8_STAGE(PG8_SB(1, 1), b3 + hstepB, voffB); PG8_STAGE(PG8_SA(1, 0), a3, voffA);
;             PG8_WAIT_V(8); PG8_WAIT_L(0); PG8_BAR; PG8_MMA(1, 0, At, B0); PG8_MMA(1, 1, At, B1); PG8_BAR; PG8_SCHED;
	s_add_i32 s68, 0, 0x18000
	s_add_i32 s70, 0, 0x1c000
	ds_read_b128 v[132:135], v226 offset:32768
	ds_read_b128 v[136:139], v226 offset:33792
	ds_read_b128 v[156:159], v226 offset:34816
	ds_read_b128 v[160:163], v226 offset:35840
	ds_read_b128 v[186:189], v226 offset:49152
	ds_read_b128 v[190:193], v226 offset:50176
	ds_read_b128 v[194:197], v226 offset:51200
	ds_read_b128 v[198:201], v226 offset:52224
	s_add_u32 s58, s58, 0x80000
	s_addc_u32 s59, s59, 0
	s_mov_b32 m0, s12
	ds_read_b128 v[202:205], v155 offset:32768
	ds_read_b128 v[206:209], v155 offset:33792
	ds_read_b128 v[210:213], v155 offset:34816
	ds_read_b128 v[214:217], v155 offset:35840
	ds_read_b128 v[218:221], v155 offset:36864
	ds_read_b128 v[222:225], v155 offset:37888
	ds_read_b128 v[234:237], v155 offset:38912
	ds_read_b128 v[238:241], v155 offset:39936
	global_load_lds_dwordx4 v140, s[58:59]
	s_mov_b32 m0, s13
	s_nop 0
	global_load_lds_dwordx4 v144, s[58:59]
	s_waitcnt vmcnt(8)
	s_waitcnt lgkmcnt(0)
	s_barrier
	v_mfma_f32_16x16x32_bf16 v[128:131], v[132:135], v[202:205], v[128:131]
	v_mfma_f32_16x16x32_bf16 v[124:127], v[156:159], v[202:205], v[124:127]
	v_mfma_f32_16x16x32_bf16 v[112:115], v[132:135], v[210:213], v[112:115]
	v_mfma_f32_16x16x32_bf16 v[108:111], v[156:159], v[210:213], v[108:111]
	v_mfma_f32_16x16x32_bf16 v[96:99], v[132:135], v[218:221], v[96:99]
	v_mfma_f32_16x16x32_bf16 v[92:95], v[156:159], v[218:221], v[92:95]
	v_mfma_f32_16x16x32_bf16 v[80:83], v[132:135], v[234:237], v[80:83]
	v_mfma_f32_16x16x32_bf16 v[76:79], v[156:159], v[234:237], v[76:79]
	v_mfma_f32_16x16x32_bf16 v[128:131], v[136:139], v[206:209], v[128:131]
	v_mfma_f32_16x16x32_bf16 v[124:127], v[160:163], v[206:209], v[124:127]
	v_mfma_f32_16x16x32_bf16 v[112:115], v[136:139], v[214:217], v[112:115]
	v_mfma_f32_16x16x32_bf16 v[108:111], v[160:163], v[214:217], v[108:111]
	v_mfma_f32_16x16x32_bf16 v[96:99], v[136:139], v[222:225], v[96:99]
	v_mfma_f32_16x16x32_bf16 v[92:95], v[160:163], v[222:225], v[92:95]
	v_mfma_f32_16x16x32_bf16 v[80:83], v[136:139], v[238:241], v[80:83]
	v_mfma_f32_16x16x32_bf16 v[76:79], v[160:163], v[238:241], v[76:79]
	v_mfma_f32_16x16x32_bf16 v[120:123], v[186:189], v[202:205], v[120:123]
	v_mfma_f32_16x16x32_bf16 v[116:119], v[194:197], v[202:205], v[116:119]
	v_mfma_f32_16x16x32_bf16 v[104:107], v[186:189], v[210:213], v[104:107]
	v_mfma_f32_16x16x32_bf16 v[100:103], v[194:197], v[210:213], v[100:103]
	v_mfma_f32_16x16x32_bf16 v[88:91], v[186:189], v[218:221], v[88:91]
	v_mfma_f32_16x16x32_bf16 v[84:87], v[194:197], v[218:221], v[84:87]
	v_mfma_f32_16x16x32_bf16 v[72:75], v[186:189], v[234:237], v[72:75]
	v_mfma_f32_16x16x32_bf16 v[68:71], v[194:197], v[234:237], v[68:71]
	v_mfma_f32_16x16x32_bf16 v[120:123], v[190:193], v[206:209], v[120:123]
	v_mfma_f32_16x16x32_bf16 v[116:119], v[198:201], v[206:209], v[116:119]
	v_mfma_f32_16x16x32_bf16 v[104:107], v[190:193], v[214:217], v[104:107]
	v_mfma_f32_16x16x32_bf16 v[100:103], v[198:201], v[214:217], v[100:103]
	v_mfma_f32_16x16x32_bf16 v[88:91], v[190:193], v[222:225], v[88:91]
	v_mfma_f32_16x16x32_bf16 v[84:87], v[198:201], v[222:225], v[84:87]
	v_mfma_f32_16x16x32_bf16 v[72:75], v[190:193], v[238:241], v[72:75]
	v_mfma_f32_16x16x32_bf16 v[68:71], v[198:201], v[238:241], v[68:71]
	s_barrier
	s_add_i32 s58, s68, s9
	s_mov_b32 m0, s58
	ds_read_b128 v[202:205], v155 offset:49152
	ds_read_b128 v[206:209], v155 offset:50176
	ds_read_b128 v[210:213], v155 offset:51200
	ds_read_b128 v[214:217], v155 offset:52224
	ds_read_b128 v[218:221], v155 offset:53248
	ds_read_b128 v[222:225], v155 offset:54272
	ds_read_b128 v[234:237], v155 offset:55296
	ds_read_b128 v[238:241], v155 offset:56320
	s_add_u32 vcc_lo, s56, 0x80
	s_addc_u32 vcc_hi, s57, 0
	global_load_lds_dwordx4 v142, vcc
	s_add_i32 m0, s58, 0x2000
	s_add_u32 s56, s56, 0x80080
	s_addc_u32 s57, s57, 0
	s_add_i32 s58, s70, s9
	s_add_u32 vcc_lo, s56, 0xfff80000
	s_addc_u32 vcc_hi, s57, -1
	global_load_lds_dwordx4 v146, vcc
	s_mov_b32 m0, s58
	s_nop 0
	global_load_lds_dwordx4 v142, s[56:57]
	s_add_i32 m0, s58, 0x2000
	s_nop 0
	global_load_lds_dwordx4 v146, s[56:57]
	s_mov_b32 m0, s55
	s_nop 0
	global_load_lds_dwordx4 v140, s[98:99]
	s_mov_b32 m0, s66
	s_nop 0
	global_load_lds_dwordx4 v144, s[98:99]
	s_waitcnt vmcnt(8)
	s_waitcnt lgkmcnt(0)
	s_barrier
	v_mfma_f32_16x16x32_bf16 v[64:67], v[132:135], v[202:205], v[64:67]
	v_mfma_f32_16x16x32_bf16 v[60:63], v[156:159], v[202:205], v[60:63]
	v_mfma_f32_16x16x32_bf16 v[48:51], v[132:135], v[210:213], v[48:51]
	v_mfma_f32_16x16x32_bf16 v[44:47], v[156:159], v[210:213], v[44:47]
	v_mfma_f32_16x16x32_bf16 v[30:33], v[132:135], v[218:221], v[30:33]
	v_mfma_f32_16x16x32_bf16 v[26:29], v[156:159], v[218:221], v[26:29]
	v_mfma_f32_16x16x32_bf16 v[14:17], v[132:135], v[234:237], v[14:17]
	v_mfma_f32_16x16x32_bf16 v[10:13], v[156:159], v[234:237], v[10:13]
	v_mfma_f32_16x16x32_bf16 v[64:67], v[136:139], v[206:209], v[64:67]
	v_mfma_f32_16x16x32_bf16 v[60:63], v[160:163], v[206:209], v[60:63]
	v_mfma_f32_16x16x32_bf16 v[48:51], v[136:139], v[214:217], v[48:51]
	v_mfma_f32_16x16x32_bf16 v[44:47], v[160:163], v[214:217], v[44:47]
	v_mfma_f32_16x16x32_bf16 v[30:33], v[136:139], v[222:225], v[30:33]
	v_mfma_f32_16x16x32_bf16 v[26:29], v[160:163], v[222:225], v[26:29]
	v_mfma_f32_16x16x32_bf16 v[14:17], v[136:139], v[238:241], v[14:17]
	v_mfma_f32_16x16x32_bf16 v[10:13], v[160:163], v[238:241], v[10:13]
	v_mfma_f32_16x16x32_bf16 v[56:59], v[186:189], v[202:205], v[56:59]
	v_mfma_f32_16x16x32_bf16 v[52:55], v[194:197], v[202:205], v[52:55]
	v_mfma_f32_16x16x32_bf16 v[40:43], v[186:189], v[210:213], v[40:43]
	v_mfma_f32_16x16x32_bf16 v[36:39], v[194:197], v[210:213], v[36:39]
	v_mfma_f32_16x16x32_bf16 v[22:25], v[186:189], v[218:221], v[22:25]
	v_mfma_f32_16x16x32_bf16 v[18:21], v[194:197], v[218:221], v[18:21]
	v_mfma_f32_16x16x32_bf16 v[6:9], v[186:189], v[234:237], v[6:9]
	v_mfma_f32_16x16x32_bf16 v[2:5], v[194:197], v[234:237], v[2:5]
	v_mfma_f32_16x16x32_bf16 v[56:59], v[190:193], v[206:209], v[56:59]
	v_mfma_f32_16x16x32_bf16 v[52:55], v[198:201], v[206:209], v[52:55]
	v_mfma_f32_16x16x32_bf16 v[40:43], v[190:193], v[214:217], v[40:43]
	v_mfma_f32_16x16x32_bf16 v[36:39], v[198:201], v[214:217], v[36:39]
	v_mfma_f32_16x16x32_bf16 v[22:25], v[190:193], v[222:225], v[22:25]
	v_mfma_f32_16x16x32_bf16 v[18:21], v[198:201], v[222:225], v[18:21]
	v_mfma_f32_16x16x32_bf16 v[6:9], v[190:193], v[238:241], v[6:9]
	v_mfma_f32_16x16x32_bf16 v[2:5], v[198:201], v[238:241], v[2:5]
	s_barrier
	s_add_i32 s47, s47, 2
	s_add_u32 s52, s52, 0x100
	s_addc_u32 s53, s53, 0
	s_add_u32 s37, s37, 0x100
	s_addc_u32 s41, s41, 0
	s_cmp_gt_u32 s47, 29
	s_cbranch_scc0 .LBB0_923
	s_and_b64 vcc, exec, s[30:31]
	s_cbranch_vccz .LBB0_926
	s_barrier

; #define PG8_STAGE(bufoff, gbase, voff) do { _Pragma("unroll") for (int _i = 0; _i < 2; ++_i) \
;         __builtin_amdgcn_global_load_lds((const unsigned*)((const char*)(gbase) + (voff)[_i]), (PG8_LAS unsigned*)(lds + (bufoff) + ldsw + _i * 8192), 16, 0, 0); } while (0)
; #define PG8_LDA(dst, b, h) do { _Pragma("unroll") for (int m = 0; m < 4; ++m) _Pragma("unroll") for (int k = 0; k < 2; ++k) dst[m][k] = *(const PG8_LAS bf16x8*)(lds + PG8_SA(b, h) + aoff + m * 2048 + k * 1024); } while (0)
; #define PG8_LDB(dst, b, h) do { _Pragma("unroll") for (int n = 0; n < 2; ++n) _Pragma("unroll") for (int k = 0; k < 2; ++k) dst[n][k] = *(const PG8_LAS bf16x8*)(lds + PG8_SB(b, h) + boff + n * 2048 + k * 1024); } while (0)
; #define PG8_WAIT_V(n) asm volatile("s_waitcnt vmcnt(" #n ")" ::: "memory")
; #define PG8_WAIT_L(n) asm volatile("s_waitcnt lgkmcnt(" #n ")" ::: "memory")
; #define PG8_BAR __builtin_amdgcn_s_barrier()
; #define PG8_SCHED __builtin_amdgcn_sched_barrier(0)
; __device__ __forceinline__ void mfma_fp8_acc(f32x4& acc, const i32x8 b, const i32x8 a) { asm volatile("v_mfma_f32_16x16x128_f8f6f4 %0, %1, %2, %0" : "+v"(acc) : "v"(b), "v"(a)); }
;     ...
;         for (int t = 0; t < nt; t += 2) {
;             const bool last = (t == nt - 2);
;             const char* a1 = cA + (size_t)(t + 1) * kstep;
;             const char* a2 = last ? nA : cA + (size_t)(t + 2) * kstep; const char* b2 = last ? nB : cB + (size_t)(t + 2) * kstep;
;             const char* a3 = a2 + kstep; const char* b3 = b2 + kstep;
;             if (last && has_next) S.a_ready(nxt);
;             if constexpr (SP2) {
;             PG8_LDB(B0, 0, 0); PG8_LDB(B1, 0, 1); PG8_SCHED; PG8_LDA(At, 0, 0); PG8_STAGE(PG8_SA(1, 1), a1 + hstepA, voffA);
;             PG8_WAIT_V(8); PG8_WAIT_L(0); PG8_BAR; PG8_MMA(0, 0, At, B0); PG8_MMA(0, 1, At, B1); PG8_BAR; PG8_SCHED;
;             PG8_LDA(At, 0, 1); PG8_STAGE(PG8_SB(0, 0), b2, voffB); PG8_STAGE(PG8_SB(0, 1), b2 + hstepB, voffB); PG8_STAGE(PG8_SA(0, 0), a2, voffA);
;             PG8_WAIT_V(8); PG8_WAIT_L(0); PG8_BAR; PG8_MMA(1, 0, At, B0); PG8_MMA(1, 1, At, B1); PG8_BAR; PG8_SCHED;
.LBB0_1133:
	v_add_u32_e32 v226, 0x10000, v208
	s_add_u32 s52, s50, 0xfffc0080
	s_addc_u32 s53, s51, -1
	s_add_i32 s75, 0, 0x10000
	s_cmp_eq_u32 s74, 12
	s_cselect_b32 s55, s37, s53
	s_cselect_b32 s54, s67, s52
	s_cselect_b32 s53, s31, s71
	s_cselect_b32 s52, s68, s70
	s_add_i32 s76, 0, 0x14000
	ds_read_b128 v[26:29], v226
	ds_read_b128 v[30:33], v226 offset:1024
	ds_read_b128 v[18:21], v226 offset:2048
	ds_read_b128 v[22:25], v226 offset:3072
	ds_read_b128 v[10:13], v226 offset:16384
	ds_read_b128 v[14:17], v226 offset:17408
	ds_read_b128 v[2:5], v226 offset:18432
	ds_read_b128 v[6:9], v226 offset:19456
	s_add_i32 m0, s57, 0xc000
	ds_read_b128 v[198:201], v209
	ds_read_b128 v[202:205], v209 offset:1024
	ds_read_b128 v[210:213], v209 offset:2048
	ds_read_b128 v[214:217], v209 offset:3072
	ds_read_b128 v[218:221], v209 offset:4096
	ds_read_b128 v[222:225], v209 offset:5120
	ds_read_b128 v[234:237], v209 offset:6144
	ds_read_b128 v[238:241], v209 offset:7168
	global_load_lds_dwordx4 v194, s[50:51]
	s_add_i32 m0, s57, 0xe000
	s_nop 0
	global_load_lds_dwordx4 v196, s[50:51]
	s_waitcnt vmcnt(8)
	s_waitcnt lgkmcnt(0)
	s_barrier
	v_mfma_f32_16x16x128_f8f6f4 v[160:163], v[26:33], v[198:205], v[160:163]
	v_mfma_f32_16x16x128_f8f6f4 v[156:159], v[18:25], v[198:205], v[156:159]
	v_mfma_f32_16x16x128_f8f6f4 v[144:147], v[26:33], v[210:217], v[144:147]
	v_mfma_f32_16x16x128_f8f6f4 v[140:143], v[18:25], v[210:217], v[140:143]
	v_mfma_f32_16x16x128_f8f6f4 v[128:131], v[26:33], v[218:225], v[128:131]
	v_mfma_f32_16x16x128_f8f6f4 v[124:127], v[18:25], v[218:225], v[124:127]
	v_mfma_f32_16x16x128_f8f6f4 v[112:115], v[26:33], v[234:241], v[112:115]
	v_mfma_f32_16x16x128_f8f6f4 v[108:111], v[18:25], v[234:241], v[108:111]
	v_mfma_f32_16x16x128_f8f6f4 v[152:155], v[10:17], v[198:205], v[152:155]
	v_mfma_f32_16x16x128_f8f6f4 v[148:151], v[2:9], v[198:205], v[148:151]
	v_mfma_f32_16x16x128_f8f6f4 v[136:139], v[10:17], v[210:217], v[136:139]
	v_mfma_f32_16x16x128_f8f6f4 v[132:135], v[2:9], v[210:217], v[132:135]
	v_mfma_f32_16x16x128_f8f6f4 v[120:123], v[10:17], v[218:225], v[120:123]
	v_mfma_f32_16x16x128_f8f6f4 v[116:119], v[2:9], v[218:225], v[116:119]
	v_mfma_f32_16x16x128_f8f6f4 v[104:107], v[10:17], v[234:241], v[104:107]
	v_mfma_f32_16x16x128_f8f6f4 v[100:103], v[2:9], v[234:241], v[100:103]
	s_barrier
	s_add_i32 s75, s75, s11
	s_mov_b32 m0, s75
	ds_read_b128 v[210:213], v209 offset:16384
	ds_read_b128 v[214:217], v209 offset:17408
	ds_read_b128 v[218:221], v209 offset:18432
	ds_read_b128 v[222:225], v209 offset:19456
	ds_read_b128 v[234:237], v209 offset:20480
	ds_read_b128 v[238:241], v209 offset:21504
	ds_read_b128 v[242:245], v209 offset:22528
	ds_read_b128 v[246:249], v209 offset:23552
	global_load_lds_dwordx4 v34, s[52:53]
	s_add_i32 m0, s75, 0x2000
	s_add_u32 s78, s52, 0x40000
	s_addc_u32 s79, s53, 0
	s_add_i32 s75, s76, s11
	global_load_lds_dwordx4 v186, s[52:53]
	s_mov_b32 m0, s75
	s_add_u32 s98, s54, 0x80
	s_addc_u32 s99, s55, 0
	global_load_lds_dwordx4 v34, s[78:79]
	s_add_i32 m0, s75, 0x2000
	s_nop 0
	global_load_lds_dwordx4 v186, s[78:79]
	s_mov_b32 m0, s57
	s_nop 0
	global_load_lds_dwordx4 v190, s[54:55]
	s_mov_b32 m0, s6
	s_nop 0
	global_load_lds_dwordx4 v188, s[54:55]
	s_waitcnt vmcnt(8)
	s_waitcnt lgkmcnt(0)
	s_barrier
	v_mfma_f32_16x16x128_f8f6f4 v[96:99], v[26:33], v[210:217], v[96:99]
	v_mfma_f32_16x16x128_f8f6f4 v[92:95], v[18:25], v[210:217], v[92:95]
	v_mfma_f32_16x16x128_f8f6f4 v[80:83], v[26:33], v[218:225], v[80:83]
	v_mfma_f32_16x16x128_f8f6f4 v[76:79], v[18:25], v[218:225], v[76:79]
	v_mfma_f32_16x16x128_f8f6f4 v[64:67], v[26:33], v[234:241], v[64:67]
	v_mfma_f32_16x16x128_f8f6f4 v[60:63], v[18:25], v[234:241], v[60:63]
	v_mfma_f32_16x16x128_f8f6f4 v[48:51], v[26:33], v[242:249], v[48:51]
	v_mfma_f32_16x16x128_f8f6f4 v[44:47], v[18:25], v[242:249], v[44:47]
	v_mfma_f32_16x16x128_f8f6f4 v[88:91], v[10:17], v[210:217], v[88:91]
	v_mfma_f32_16x16x128_f8f6f4 v[84:87], v[2:9], v[210:217], v[84:87]
	v_mfma_f32_16x16x128_f8f6f4 v[72:75], v[10:17], v[218:225], v[72:75]
	v_mfma_f32_16x16x128_f8f6f4 v[68:71], v[2:9], v[218:225], v[68:71]
	v_mfma_f32_16x16x128_f8f6f4 v[56:59], v[10:17], v[234:241], v[56:59]
	v_mfma_f32_16x16x128_f8f6f4 v[52:55], v[2:9], v[234:241], v[52:55]
	v_mfma_f32_16x16x128_f8f6f4 v[40:43], v[10:17], v[242:249], v[40:43]
	v_mfma_f32_16x16x128_f8f6f4 v[36:39], v[2:9], v[242:249], v[36:39]
	s_barrier
; #define PG8_STAGE(bufoff, gbase, voff) do { _Pragma("unroll") for (int _i = 0; _i < 2; ++_i) \
;         __builtin_amdgcn_global_load_lds((const unsigned*)((const char*)(gbase) + (voff)[_i]), (PG8_LAS unsigned*)(lds + (bufoff) + ldsw + _i * 8192), 16, 0, 0); } while (0)
; #define PG8_LDA(dst, b, h) do { _Pragma("unroll") for (int m = 0; m < 4; ++m) _Pragma("unroll") for (int k = 0; k < 2; ++k) dst[m][k] = *(const PG8_LAS bf16x8*)(lds + PG8_SA(b, h) + aoff + m * 2048 + k * 1024); } while (0)
; #define PG8_LDB(dst, b, h) do { _Pragma("unroll") for (int n = 0; n < 2; ++n) _Pragma("unroll") for (int k = 0; k < 2; ++k) dst[n][k] = *(const PG8_LAS bf16x8*)(lds + PG8_SB(b, h) + boff + n * 2048 + k * 1024); } while (0)
; #define PG8_WAIT_V(n) asm volatile("s_waitcnt vmcnt(" #n ")" ::: "memory")
; #define PG8_WAIT_L(n) asm volatile("s_waitcnt lgkmcnt(" #n ")" ::: "memory")
; #define PG8_BAR __builtin_amdgcn_s_barrier()
; #define PG8_SCHED __builtin_amdgcn_sched_barrier(0)
;     ...
;         for (int t = 0; t < nt; t += 2) {
;             const bool last = (t == nt - 2);
;             const char* a1 = cA + (size_t)(t + 1) * kstep;
;             const char* a2 = last ? nA : cA + (size_t)(t + 2) * kstep; const char* b2 = last ? nB : cB + (size_t)(t + 2) * kstep;
;     ...
;             PG8_LDB(B0, 1, 0); PG8_LDB(B1, 1, 1); PG8_SCHED; PG8_LDA(At, 1, 0); PG8_STAGE(PG8_SA(0, 1), a2 + hstepA, voffA);
;             PG8_WAIT_V(8); PG8_WAIT_L(0); PG8_BAR; PG8_MMA(0, 0, At, B0); PG8_MMA(0, 1, At, B1); PG8_BAR; PG8_SCHED;
;             PG8_LDA(At, 1, 1); PG8_STAGE(PG8_SB(1, 0), b3, voffB); PG8_STAGE(PG8_SB(1, 1), b3 + hstepB, voffB); PG8_STAGE(PG8_SA(1, 0), a3, voffA);
;             PG8_WAIT_V(8); PG8_WAIT_L(0); PG8_BAR; PG8_MMA(1, 0, At, B0); PG8_MMA(1, 1, At, B1); PG8_BAR; PG8_SCHED;
	s_add_i32 s75, 0, 0x18000
	s_add_i32 s76, 0, 0x1c000
	ds_read_b128 v[2:5], v226 offset:32768
	ds_read_b128 v[6:9], v226 offset:33792
	ds_read_b128 v[10:13], v226 offset:34816
	ds_read_b128 v[14:17], v226 offset:35840
	ds_read_b128 v[18:21], v226 offset:49152
	ds_read_b128 v[22:25], v226 offset:50176
	ds_read_b128 v[26:29], v226 offset:51200
	ds_read_b128 v[30:33], v226 offset:52224
	s_add_u32 s54, s54, 0x40000
	s_addc_u32 s55, s55, 0
	s_mov_b32 m0, s15
	ds_read_b128 v[210:213], v209 offset:32768
	ds_read_b128 v[214:217], v209 offset:33792
	ds_read_b128 v[218:221], v209 offset:34816
	ds_read_b128 v[222:225], v209 offset:35840
	ds_read_b128 v[234:237], v209 offset:36864
	ds_read_b128 v[238:241], v209 offset:37888
	ds_read_b128 v[242:245], v209 offset:38912
	ds_read_b128 v[246:249], v209 offset:39936
	global_load_lds_dwordx4 v190, s[54:55]
	s_mov_b32 m0, s34
	s_nop 0
	global_load_lds_dwordx4 v188, s[54:55]
	s_waitcnt vmcnt(8)
	s_waitcnt lgkmcnt(0)
	s_barrier
	v_mfma_f32_16x16x128_f8f6f4 v[160:163], v[2:9], v[210:217], v[160:163]
	v_mfma_f32_16x16x128_f8f6f4 v[156:159], v[10:17], v[210:217], v[156:159]
	v_mfma_f32_16x16x128_f8f6f4 v[144:147], v[2:9], v[218:225], v[144:147]
	v_mfma_f32_16x16x128_f8f6f4 v[140:143], v[10:17], v[218:225], v[140:143]
	v_mfma_f32_16x16x128_f8f6f4 v[128:131], v[2:9], v[234:241], v[128:131]
	v_mfma_f32_16x16x128_f8f6f4 v[124:127], v[10:17], v[234:241], v[124:127]
	v_mfma_f32_16x16x128_f8f6f4 v[112:115], v[2:9], v[242:249], v[112:115]
	v_mfma_f32_16x16x128_f8f6f4 v[108:111], v[10:17], v[242:249], v[108:111]
	v_mfma_f32_16x16x128_f8f6f4 v[152:155], v[18:25], v[210:217], v[152:155]
	v_mfma_f32_16x16x128_f8f6f4 v[148:151], v[26:33], v[210:217], v[148:151]
	v_mfma_f32_16x16x128_f8f6f4 v[136:139], v[18:25], v[218:225], v[136:139]
	v_mfma_f32_16x16x128_f8f6f4 v[132:135], v[26:33], v[218:225], v[132:135]
	v_mfma_f32_16x16x128_f8f6f4 v[120:123], v[18:25], v[234:241], v[120:123]
	v_mfma_f32_16x16x128_f8f6f4 v[116:119], v[26:33], v[234:241], v[116:119]
	v_mfma_f32_16x16x128_f8f6f4 v[104:107], v[18:25], v[242:249], v[104:107]
	v_mfma_f32_16x16x128_f8f6f4 v[100:103], v[26:33], v[242:249], v[100:103]
	s_barrier
	s_add_i32 s54, s75, s11
	s_mov_b32 m0, s54
	ds_read_b128 v[210:213], v209 offset:49152
	ds_read_b128 v[214:217], v209 offset:50176
	ds_read_b128 v[218:221], v209 offset:51200
	ds_read_b128 v[222:225], v209 offset:52224
	ds_read_b128 v[234:237], v209 offset:53248
	ds_read_b128 v[238:241], v209 offset:54272
	ds_read_b128 v[242:245], v209 offset:55296
	ds_read_b128 v[246:249], v209 offset:56320
	s_add_u32 vcc_lo, s52, 0x80
	s_addc_u32 vcc_hi, s53, 0
	global_load_lds_dwordx4 v34, vcc
	s_add_i32 m0, s54, 0x2000
	s_add_u32 s52, s52, 0x40080
	s_addc_u32 s53, s53, 0
	s_add_i32 s54, s76, s11
	s_add_u32 vcc_lo, s52, 0xfffc0000
	s_addc_u32 vcc_hi, s53, -1
	global_load_lds_dwordx4 v186, vcc
	s_mov_b32 m0, s54
	s_nop 0
	global_load_lds_dwordx4 v34, s[52:53]
	s_add_i32 m0, s54, 0x2000
	s_nop 0
	global_load_lds_dwordx4 v186, s[52:53]
	s_mov_b32 m0, s35
	s_nop 0
	global_load_lds_dwordx4 v190, s[98:99]
	s_mov_b32 m0, s58
	s_nop 0
	global_load_lds_dwordx4 v188, s[98:99]
	s_waitcnt vmcnt(8)
	s_waitcnt lgkmcnt(0)
	s_barrier
	v_mfma_f32_16x16x128_f8f6f4 v[96:99], v[2:9], v[210:217], v[96:99]
	v_mfma_f32_16x16x128_f8f6f4 v[92:95], v[10:17], v[210:217], v[92:95]
	v_mfma_f32_16x16x128_f8f6f4 v[80:83], v[2:9], v[218:225], v[80:83]
	v_mfma_f32_16x16x128_f8f6f4 v[76:79], v[10:17], v[218:225], v[76:79]
	v_mfma_f32_16x16x128_f8f6f4 v[64:67], v[2:9], v[234:241], v[64:67]
	v_mfma_f32_16x16x128_f8f6f4 v[60:63], v[10:17], v[234:241], v[60:63]
	v_mfma_f32_16x16x128_f8f6f4 v[48:51], v[2:9], v[242:249], v[48:51]
	v_mfma_f32_16x16x128_f8f6f4 v[44:47], v[10:17], v[242:249], v[44:47]
	v_mfma_f32_16x16x128_f8f6f4 v[88:91], v[18:25], v[210:217], v[88:91]
	v_mfma_f32_16x16x128_f8f6f4 v[84:87], v[26:33], v[210:217], v[84:87]
	v_mfma_f32_16x16x128_f8f6f4 v[72:75], v[18:25], v[218:225], v[72:75]
	v_mfma_f32_16x16x128_f8f6f4 v[68:71], v[26:33], v[218:225], v[68:71]
	v_mfma_f32_16x16x128_f8f6f4 v[56:59], v[18:25], v[234:241], v[56:59]
	v_mfma_f32_16x16x128_f8f6f4 v[52:55], v[26:33], v[234:241], v[52:55]
	v_mfma_f32_16x16x128_f8f6f4 v[40:43], v[18:25], v[242:249], v[40:43]
	v_mfma_f32_16x16x128_f8f6f4 v[36:39], v[26:33], v[242:249], v[36:39]
	s_barrier
	s_add_i32 s74, s74, 2
	s_add_u32 s50, s50, 0x100
	s_addc_u32 s51, s51, 0
	s_add_u32 s70, s70, 0x100
	s_addc_u32 s71, s71, 0
	s_cmp_gt_u32 s74, 13
	s_cbranch_scc0 .LBB0_1133
	s_and_b64 vcc, exec, s[28:29]
	s_cbranch_vccz .LBB0_1136
	s_barrier

; #define PG8_STAGE(bufoff, gbase, voff) do { _Pragma("unroll") for (int _i = 0; _i < 2; ++_i) \
;         __builtin_amdgcn_global_load_lds((const unsigned*)((const char*)(gbase) + (voff)[_i]), (PG8_LAS unsigned*)(lds + (bufoff) + ldsw + _i * 8192), 16, 0, 0); } while (0)
; #define PG8_LDA(dst, b, h) do { _Pragma("unroll") for (int m = 0; m < 4; ++m) _Pragma("unroll") for (int k = 0; k < 2; ++k) dst[m][k] = *(const PG8_LAS bf16x8*)(lds + PG8_SA(b, h) + aoff + m * 2048 + k * 1024); } while (0)
; #define PG8_LDB(dst, b, h) do { _Pragma("unroll") for (int n = 0; n < 2; ++n) _Pragma("unroll") for (int k = 0; k < 2; ++k) dst[n][k] = *(const PG8_LAS bf16x8*)(lds + PG8_SB(b, h) + boff + n * 2048 + k * 1024); } while (0)
; #define PG8_WAIT_V(n) asm volatile("s_waitcnt vmcnt(" #n ")" ::: "memory")
; #define PG8_WAIT_L(n) asm volatile("s_waitcnt lgkmcnt(" #n ")" ::: "memory")
; #define PG8_BAR __builtin_amdgcn_s_barrier()
; #define PG8_SCHED __builtin_amdgcn_sched_barrier(0)
;     ...
;         for (int t = 0; t < nt; t += 2) {
;             const bool last = (t == nt - 2);
;             const char* a1 = cA + (size_t)(t + 1) * kstep;
;             const char* a2 = last ? nA : cA + (size_t)(t + 2) * kstep; const char* b2 = last ? nB : cB + (size_t)(t + 2) * kstep;
;             const char* a3 = a2 + kstep; const char* b3 = b2 + kstep;
;             if (last && has_next) S.a_ready(nxt);
;             if constexpr (SP2) {
;             PG8_LDB(B0, 0, 0); PG8_LDB(B1, 0, 1); PG8_SCHED; PG8_LDA(At, 0, 0); PG8_STAGE(PG8_SA(1, 1), a1 + hstepA, voffA);
;             PG8_WAIT_V(8); PG8_WAIT_L(0); PG8_BAR; PG8_MMA(0, 0, At, B0); PG8_MMA(0, 1, At, B1); PG8_BAR; PG8_SCHED;
;             PG8_LDA(At, 0, 1); PG8_STAGE(PG8_SB(0, 0), b2, voffB); PG8_STAGE(PG8_SB(0, 1), b2 + hstepB, voffB); PG8_STAGE(PG8_SA(0, 0), a2, voffA);
;             PG8_WAIT_V(8); PG8_WAIT_L(0); PG8_BAR; PG8_MMA(1, 0, At, B0); PG8_MMA(1, 1, At, B1); PG8_BAR; PG8_SCHED;
.LBB0_1153:
	v_add_u32_e32 v162, 0x10000, v155
	s_add_u32 s34, s26, 0xfff80080
	s_addc_u32 s35, s27, -1
	s_add_i32 s37, 0, 0x10000
	s_cmp_eq_u32 s19, 28
	s_cselect_b32 s57, s6, s35
	s_cselect_b32 s56, s10, s34
	s_cselect_b32 s41, s11, s15
	s_cselect_b32 s40, s12, s13
	s_add_i32 s49, 0, 0x14000
	ds_read_b128 v[132:135], v162
	ds_read_b128 v[136:139], v162 offset:1024
	s_waitcnt vmcnt(0)
	ds_read_b128 v[158:161], v162 offset:2048
	ds_read_b128 v[186:189], v162 offset:3072
	ds_read_b128 v[190:193], v162 offset:16384
	ds_read_b128 v[194:197], v162 offset:17408
	ds_read_b128 v[198:201], v162 offset:18432
	ds_read_b128 v[202:205], v162 offset:19456
	s_add_i32 m0, s8, 0xc000
	ds_read_b128 v[206:209], v157
	ds_read_b128 v[210:213], v157 offset:1024
	ds_read_b128 v[214:217], v157 offset:2048
	ds_read_b128 v[218:221], v157 offset:3072
	ds_read_b128 v[222:225], v157 offset:4096
	ds_read_b128 v[234:237], v157 offset:5120
	ds_read_b128 v[238:241], v157 offset:6144
	ds_read_b128 v[242:245], v157 offset:7168
	global_load_lds_dwordx4 v150, s[26:27]
	s_add_i32 m0, s8, 0xe000
	s_nop 0
	global_load_lds_dwordx4 v152, s[26:27]
	s_waitcnt vmcnt(8)
	s_waitcnt lgkmcnt(0)
	s_barrier
	v_mfma_f32_16x16x32_bf16 v[128:131], v[132:135], v[206:209], v[128:131]
	v_mfma_f32_16x16x32_bf16 v[124:127], v[158:161], v[206:209], v[124:127]
	v_mfma_f32_16x16x32_bf16 v[112:115], v[132:135], v[214:217], v[112:115]
	v_mfma_f32_16x16x32_bf16 v[108:111], v[158:161], v[214:217], v[108:111]
	v_mfma_f32_16x16x32_bf16 v[96:99], v[132:135], v[222:225], v[96:99]
	v_mfma_f32_16x16x32_bf16 v[92:95], v[158:161], v[222:225], v[92:95]
	v_mfma_f32_16x16x32_bf16 v[80:83], v[132:135], v[238:241], v[80:83]
	v_mfma_f32_16x16x32_bf16 v[76:79], v[158:161], v[238:241], v[76:79]
	v_mfma_f32_16x16x32_bf16 v[128:131], v[136:139], v[210:213], v[128:131]
	v_mfma_f32_16x16x32_bf16 v[124:127], v[186:189], v[210:213], v[124:127]
	v_mfma_f32_16x16x32_bf16 v[112:115], v[136:139], v[218:221], v[112:115]
	v_mfma_f32_16x16x32_bf16 v[108:111], v[186:189], v[218:221], v[108:111]
	v_mfma_f32_16x16x32_bf16 v[96:99], v[136:139], v[234:237], v[96:99]
	v_mfma_f32_16x16x32_bf16 v[92:95], v[186:189], v[234:237], v[92:95]
	v_mfma_f32_16x16x32_bf16 v[80:83], v[136:139], v[242:245], v[80:83]
	v_mfma_f32_16x16x32_bf16 v[76:79], v[186:189], v[242:245], v[76:79]
	v_mfma_f32_16x16x32_bf16 v[120:123], v[190:193], v[206:209], v[120:123]
	v_mfma_f32_16x16x32_bf16 v[116:119], v[198:201], v[206:209], v[116:119]
	v_mfma_f32_16x16x32_bf16 v[104:107], v[190:193], v[214:217], v[104:107]
	v_mfma_f32_16x16x32_bf16 v[100:103], v[198:201], v[214:217], v[100:103]
	v_mfma_f32_16x16x32_bf16 v[88:91], v[190:193], v[222:225], v[88:91]
	v_mfma_f32_16x16x32_bf16 v[84:87], v[198:201], v[222:225], v[84:87]
	v_mfma_f32_16x16x32_bf16 v[72:75], v[190:193], v[238:241], v[72:75]
	v_mfma_f32_16x16x32_bf16 v[68:71], v[198:201], v[238:241], v[68:71]
	v_mfma_f32_16x16x32_bf16 v[120:123], v[194:197], v[210:213], v[120:123]
	v_mfma_f32_16x16x32_bf16 v[116:119], v[202:205], v[210:213], v[116:119]
	v_mfma_f32_16x16x32_bf16 v[104:107], v[194:197], v[218:221], v[104:107]
	v_mfma_f32_16x16x32_bf16 v[100:103], v[202:205], v[218:221], v[100:103]
	v_mfma_f32_16x16x32_bf16 v[88:91], v[194:197], v[234:237], v[88:91]
	v_mfma_f32_16x16x32_bf16 v[84:87], v[202:205], v[234:237], v[84:87]
	v_mfma_f32_16x16x32_bf16 v[72:75], v[194:197], v[242:245], v[72:75]
	v_mfma_f32_16x16x32_bf16 v[68:71], v[202:205], v[242:245], v[68:71]
	s_barrier
	s_add_i32 s34, s37, s7
	s_mov_b32 m0, s34
	ds_read_b128 v[206:209], v157 offset:16384
	ds_read_b128 v[210:213], v157 offset:17408
	ds_read_b128 v[214:217], v157 offset:18432
	ds_read_b128 v[218:221], v157 offset:19456
	ds_read_b128 v[222:225], v157 offset:20480
	ds_read_b128 v[234:237], v157 offset:21504
	ds_read_b128 v[238:241], v157 offset:22528
	ds_read_b128 v[242:245], v157 offset:23552
	global_load_lds_dwordx4 v142, s[40:41]
	s_add_i32 m0, s34, 0x2000
	s_add_u32 s34, s40, 0x80000
	s_addc_u32 s35, s41, 0
	s_add_i32 s37, s49, s7
	global_load_lds_dwordx4 v146, s[40:41]
	s_mov_b32 m0, s37
	s_nop 0
	global_load_lds_dwordx4 v142, s[34:35]
	s_add_i32 m0, s37, 0x2000
	s_nop 0
	global_load_lds_dwordx4 v146, s[34:35]
	s_mov_b32 m0, s8
	s_nop 0
	global_load_lds_dwordx4 v140, s[56:57]
	s_mov_b32 m0, s9
	s_nop 0
	global_load_lds_dwordx4 v144, s[56:57]
	s_waitcnt vmcnt(8)
	s_waitcnt lgkmcnt(0)
	s_barrier
	v_mfma_f32_16x16x32_bf16 v[64:67], v[132:135], v[206:209], v[64:67]
	v_mfma_f32_16x16x32_bf16 v[60:63], v[158:161], v[206:209], v[60:63]
	v_mfma_f32_16x16x32_bf16 v[48:51], v[132:135], v[214:217], v[48:51]
	v_mfma_f32_16x16x32_bf16 v[44:47], v[158:161], v[214:217], v[44:47]
	v_mfma_f32_16x16x32_bf16 v[30:33], v[132:135], v[222:225], v[30:33]
	v_mfma_f32_16x16x32_bf16 v[26:29], v[158:161], v[222:225], v[26:29]
	v_mfma_f32_16x16x32_bf16 v[14:17], v[132:135], v[238:241], v[14:17]
	v_mfma_f32_16x16x32_bf16 v[10:13], v[158:161], v[238:241], v[10:13]
	v_mfma_f32_16x16x32_bf16 v[64:67], v[136:139], v[210:213], v[64:67]
	v_mfma_f32_16x16x32_bf16 v[60:63], v[186:189], v[210:213], v[60:63]
	v_mfma_f32_16x16x32_bf16 v[48:51], v[136:139], v[218:221], v[48:51]
	v_mfma_f32_16x16x32_bf16 v[44:47], v[186:189], v[218:221], v[44:47]
	v_mfma_f32_16x16x32_bf16 v[30:33], v[136:139], v[234:237], v[30:33]
	v_mfma_f32_16x16x32_bf16 v[26:29], v[186:189], v[234:237], v[26:29]
	v_mfma_f32_16x16x32_bf16 v[14:17], v[136:139], v[242:245], v[14:17]
	v_mfma_f32_16x16x32_bf16 v[10:13], v[186:189], v[242:245], v[10:13]
	v_mfma_f32_16x16x32_bf16 v[56:59], v[190:193], v[206:209], v[56:59]
	v_mfma_f32_16x16x32_bf16 v[52:55], v[198:201], v[206:209], v[52:55]
	v_mfma_f32_16x16x32_bf16 v[40:43], v[190:193], v[214:217], v[40:43]
	v_mfma_f32_16x16x32_bf16 v[36:39], v[198:201], v[214:217], v[36:39]
	v_mfma_f32_16x16x32_bf16 v[22:25], v[190:193], v[222:225], v[22:25]
	v_mfma_f32_16x16x32_bf16 v[18:21], v[198:201], v[222:225], v[18:21]
	v_mfma_f32_16x16x32_bf16 v[6:9], v[190:193], v[238:241], v[6:9]
	v_mfma_f32_16x16x32_bf16 v[2:5], v[198:201], v[238:241], v[2:5]
	v_mfma_f32_16x16x32_bf16 v[56:59], v[194:197], v[210:213], v[56:59]
	v_mfma_f32_16x16x32_bf16 v[52:55], v[202:205], v[210:213], v[52:55]
	v_mfma_f32_16x16x32_bf16 v[40:43], v[194:197], v[218:221], v[40:43]
	v_mfma_f32_16x16x32_bf16 v[36:39], v[202:205], v[218:221], v[36:39]
	v_mfma_f32_16x16x32_bf16 v[22:25], v[194:197], v[234:237], v[22:25]
	v_mfma_f32_16x16x32_bf16 v[18:21], v[202:205], v[234:237], v[18:21]
	v_mfma_f32_16x16x32_bf16 v[6:9], v[194:197], v[242:245], v[6:9]
	v_mfma_f32_16x16x32_bf16 v[2:5], v[202:205], v[242:245], v[2:5]
	s_barrier
; #define PG8_STAGE(bufoff, gbase, voff) do { _Pragma("unroll") for (int _i = 0; _i < 2; ++_i) \
;         __builtin_amdgcn_global_load_lds((const unsigned*)((const char*)(gbase) + (voff)[_i]), (PG8_LAS unsigned*)(lds + (bufoff) + ldsw + _i * 8192), 16, 0, 0); } while (0)
; #define PG8_LDA(dst, b, h) do { _Pragma("unroll") for (int m = 0; m < 4; ++m) _Pragma("unroll") for (int k = 0; k < 2; ++k) dst[m][k] = *(const PG8_LAS bf16x8*)(lds + PG8_SA(b, h) + aoff + m * 2048 + k * 1024); } while (0)
; #define PG8_LDB(dst, b, h) do { _Pragma("unroll") for (int n = 0; n < 2; ++n) _Pragma("unroll") for (int k = 0; k < 2; ++k) dst[n][k] = *(const PG8_LAS bf16x8*)(lds + PG8_SB(b, h) + boff + n * 2048 + k * 1024); } while (0)
; #define PG8_WAIT_V(n) asm volatile("s_waitcnt vmcnt(" #n ")" ::: "memory")
; #define PG8_WAIT_L(n) asm volatile("s_waitcnt lgkmcnt(" #n ")" ::: "memory")
; #define PG8_BAR __builtin_amdgcn_s_barrier()
; #define PG8_SCHED __builtin_amdgcn_sched_barrier(0)
;     ...
;         for (int t = 0; t < nt; t += 2) {
;             const bool last = (t == nt - 2);
;             const char* a1 = cA + (size_t)(t + 1) * kstep;
;             const char* a2 = last ? nA : cA + (size_t)(t + 2) * kstep; const char* b2 = last ? nB : cB + (size_t)(t + 2) * kstep;
;     ...
;             PG8_LDB(B0, 1, 0); PG8_LDB(B1, 1, 1); PG8_SCHED; PG8_LDA(At, 1, 0); PG8_STAGE(PG8_SA(0, 1), a2 + hstepA, voffA);
;             PG8_WAIT_V(8); PG8_WAIT_L(0); PG8_BAR; PG8_MMA(0, 0, At, B0); PG8_MMA(0, 1, At, B1); PG8_BAR; PG8_SCHED;
;             PG8_LDA(At, 1, 1); PG8_STAGE(PG8_SB(1, 0), b3, voffB); PG8_STAGE(PG8_SB(1, 1), b3 + hstepB, voffB); PG8_STAGE(PG8_SA(1, 0), a3, voffA);
;             PG8_WAIT_V(8); PG8_WAIT_L(0); PG8_BAR; PG8_MMA(1, 0, At, B0); PG8_MMA(1, 1, At, B1); PG8_BAR; PG8_SCHED;
	s_add_i32 s37, 0, 0x18000
	s_add_i32 s49, 0, 0x1c000
	ds_read_b128 v[132:135], v162 offset:32768
	ds_read_b128 v[136:139], v162 offset:33792
	ds_read_b128 v[158:161], v162 offset:34816
	ds_read_b128 v[186:189], v162 offset:35840
	ds_read_b128 v[190:193], v162 offset:49152
	ds_read_b128 v[194:197], v162 offset:50176
	ds_read_b128 v[198:201], v162 offset:51200
	ds_read_b128 v[202:205], v162 offset:52224
	s_add_u32 s34, s56, 0x80000
	s_addc_u32 s35, s57, 0
	s_mov_b32 m0, s58
	ds_read_b128 v[206:209], v157 offset:32768
	ds_read_b128 v[210:213], v157 offset:33792
	ds_read_b128 v[214:217], v157 offset:34816
	ds_read_b128 v[218:221], v157 offset:35840
	ds_read_b128 v[222:225], v157 offset:36864
	ds_read_b128 v[234:237], v157 offset:37888
	ds_read_b128 v[238:241], v157 offset:38912
	ds_read_b128 v[242:245], v157 offset:39936
	global_load_lds_dwordx4 v140, s[34:35]
	s_mov_b32 m0, s59
	s_nop 0
	global_load_lds_dwordx4 v144, s[34:35]
	s_waitcnt vmcnt(8)
	s_waitcnt lgkmcnt(0)
	s_barrier
	v_mfma_f32_16x16x32_bf16 v[128:131], v[132:135], v[206:209], v[128:131]
	v_mfma_f32_16x16x32_bf16 v[124:127], v[158:161], v[206:209], v[124:127]
	v_mfma_f32_16x16x32_bf16 v[112:115], v[132:135], v[214:217], v[112:115]
	v_mfma_f32_16x16x32_bf16 v[108:111], v[158:161], v[214:217], v[108:111]
	v_mfma_f32_16x16x32_bf16 v[96:99], v[132:135], v[222:225], v[96:99]
	v_mfma_f32_16x16x32_bf16 v[92:95], v[158:161], v[222:225], v[92:95]
	v_mfma_f32_16x16x32_bf16 v[80:83], v[132:135], v[238:241], v[80:83]
	v_mfma_f32_16x16x32_bf16 v[76:79], v[158:161], v[238:241], v[76:79]
	v_mfma_f32_16x16x32_bf16 v[128:131], v[136:139], v[210:213], v[128:131]
	v_mfma_f32_16x16x32_bf16 v[124:127], v[186:189], v[210:213], v[124:127]
	v_mfma_f32_16x16x32_bf16 v[112:115], v[136:139], v[218:221], v[112:115]
	v_mfma_f32_16x16x32_bf16 v[108:111], v[186:189], v[218:221], v[108:111]
	v_mfma_f32_16x16x32_bf16 v[96:99], v[136:139], v[234:237], v[96:99]
	v_mfma_f32_16x16x32_bf16 v[92:95], v[186:189], v[234:237], v[92:95]
	v_mfma_f32_16x16x32_bf16 v[80:83], v[136:139], v[242:245], v[80:83]
	v_mfma_f32_16x16x32_bf16 v[76:79], v[186:189], v[242:245], v[76:79]
	v_mfma_f32_16x16x32_bf16 v[120:123], v[190:193], v[206:209], v[120:123]
	v_mfma_f32_16x16x32_bf16 v[116:119], v[198:201], v[206:209], v[116:119]
	v_mfma_f32_16x16x32_bf16 v[104:107], v[190:193], v[214:217], v[104:107]
	v_mfma_f32_16x16x32_bf16 v[100:103], v[198:201], v[214:217], v[100:103]
	v_mfma_f32_16x16x32_bf16 v[88:91], v[190:193], v[222:225], v[88:91]
	v_mfma_f32_16x16x32_bf16 v[84:87], v[198:201], v[222:225], v[84:87]
	v_mfma_f32_16x16x32_bf16 v[72:75], v[190:193], v[238:241], v[72:75]
	v_mfma_f32_16x16x32_bf16 v[68:71], v[198:201], v[238:241], v[68:71]
	v_mfma_f32_16x16x32_bf16 v[120:123], v[194:197], v[210:213], v[120:123]
	v_mfma_f32_16x16x32_bf16 v[116:119], v[202:205], v[210:213], v[116:119]
	v_mfma_f32_16x16x32_bf16 v[104:107], v[194:197], v[218:221], v[104:107]
	v_mfma_f32_16x16x32_bf16 v[100:103], v[202:205], v[218:221], v[100:103]
	v_mfma_f32_16x16x32_bf16 v[88:91], v[194:197], v[234:237], v[88:91]
	v_mfma_f32_16x16x32_bf16 v[84:87], v[202:205], v[234:237], v[84:87]
	v_mfma_f32_16x16x32_bf16 v[72:75], v[194:197], v[242:245], v[72:75]
	v_mfma_f32_16x16x32_bf16 v[68:71], v[202:205], v[242:245], v[68:71]
	s_barrier
	s_add_i32 s34, s37, s7
	s_mov_b32 m0, s34
	ds_read_b128 v[206:209], v157 offset:49152
	ds_read_b128 v[210:213], v157 offset:50176
	ds_read_b128 v[214:217], v157 offset:51200
	ds_read_b128 v[218:221], v157 offset:52224
	ds_read_b128 v[222:225], v157 offset:53248
	ds_read_b128 v[234:237], v157 offset:54272
	ds_read_b128 v[238:241], v157 offset:55296
	ds_read_b128 v[242:245], v157 offset:56320
	s_add_u32 vcc_lo, s40, 0x80
	s_addc_u32 vcc_hi, s41, 0
	global_load_lds_dwordx4 v142, vcc
	s_add_i32 m0, s34, 0x2000
	s_add_u32 s34, s40, 0x80080
	s_addc_u32 s35, s41, 0
	s_add_i32 s37, s49, s7
	s_add_u32 vcc_lo, s40, 0x80
	s_addc_u32 vcc_hi, s41, 0
	global_load_lds_dwordx4 v146, vcc
	s_mov_b32 m0, s37
	s_nop 0
	global_load_lds_dwordx4 v142, s[34:35]
	s_add_i32 m0, s37, 0x2000
	s_nop 0
	global_load_lds_dwordx4 v146, s[34:35]
	s_mov_b32 m0, s66
	s_nop 0
	s_add_u32 vcc_lo, s56, 0x80
	s_addc_u32 vcc_hi, s57, 0
	global_load_lds_dwordx4 v140, vcc
	s_mov_b32 m0, s67
	s_nop 0
	s_add_u32 vcc_lo, s56, 0x80
	s_addc_u32 vcc_hi, s57, 0
	global_load_lds_dwordx4 v144, vcc
	s_waitcnt vmcnt(8)
	s_waitcnt lgkmcnt(0)
	s_barrier
	v_mfma_f32_16x16x32_bf16 v[64:67], v[132:135], v[206:209], v[64:67]
	v_mfma_f32_16x16x32_bf16 v[60:63], v[158:161], v[206:209], v[60:63]
	v_mfma_f32_16x16x32_bf16 v[48:51], v[132:135], v[214:217], v[48:51]
	v_mfma_f32_16x16x32_bf16 v[44:47], v[158:161], v[214:217], v[44:47]
	v_mfma_f32_16x16x32_bf16 v[30:33], v[132:135], v[222:225], v[30:33]
	v_mfma_f32_16x16x32_bf16 v[26:29], v[158:161], v[222:225], v[26:29]
	v_mfma_f32_16x16x32_bf16 v[14:17], v[132:135], v[238:241], v[14:17]
	v_mfma_f32_16x16x32_bf16 v[10:13], v[158:161], v[238:241], v[10:13]
	v_mfma_f32_16x16x32_bf16 v[64:67], v[136:139], v[210:213], v[64:67]
	v_mfma_f32_16x16x32_bf16 v[60:63], v[186:189], v[210:213], v[60:63]
	v_mfma_f32_16x16x32_bf16 v[48:51], v[136:139], v[218:221], v[48:51]
	v_mfma_f32_16x16x32_bf16 v[44:47], v[186:189], v[218:221], v[44:47]
	v_mfma_f32_16x16x32_bf16 v[30:33], v[136:139], v[234:237], v[30:33]
	v_mfma_f32_16x16x32_bf16 v[26:29], v[186:189], v[234:237], v[26:29]
	v_mfma_f32_16x16x32_bf16 v[14:17], v[136:139], v[242:245], v[14:17]
	v_mfma_f32_16x16x32_bf16 v[10:13], v[186:189], v[242:245], v[10:13]
	v_mfma_f32_16x16x32_bf16 v[56:59], v[190:193], v[206:209], v[56:59]
	v_mfma_f32_16x16x32_bf16 v[52:55], v[198:201], v[206:209], v[52:55]
	v_mfma_f32_16x16x32_bf16 v[40:43], v[190:193], v[214:217], v[40:43]
	v_mfma_f32_16x16x32_bf16 v[36:39], v[198:201], v[214:217], v[36:39]
	v_mfma_f32_16x16x32_bf16 v[22:25], v[190:193], v[222:225], v[22:25]
	v_mfma_f32_16x16x32_bf16 v[18:21], v[198:201], v[222:225], v[18:21]
	v_mfma_f32_16x16x32_bf16 v[6:9], v[190:193], v[238:241], v[6:9]
	v_mfma_f32_16x16x32_bf16 v[2:5], v[198:201], v[238:241], v[2:5]
	v_mfma_f32_16x16x32_bf16 v[56:59], v[194:197], v[210:213], v[56:59]
	v_mfma_f32_16x16x32_bf16 v[52:55], v[202:205], v[210:213], v[52:55]
	v_mfma_f32_16x16x32_bf16 v[40:43], v[194:197], v[218:221], v[40:43]
	v_mfma_f32_16x16x32_bf16 v[36:39], v[202:205], v[218:221], v[36:39]
	v_mfma_f32_16x16x32_bf16 v[22:25], v[194:197], v[234:237], v[22:25]
	v_mfma_f32_16x16x32_bf16 v[18:21], v[202:205], v[234:237], v[18:21]
	v_mfma_f32_16x16x32_bf16 v[6:9], v[194:197], v[242:245], v[6:9]
	v_mfma_f32_16x16x32_bf16 v[2:5], v[202:205], v[242:245], v[2:5]
	s_barrier
	s_add_i32 s19, s19, 2
	s_add_u32 s26, s26, 0x100
	s_addc_u32 s27, s27, 0
	s_add_u32 s13, s13, 0x100
	s_addc_u32 s15, s15, 0
	s_cmp_gt_u32 s19, 29
	s_cbranch_scc0 .LBB0_1153
	s_and_b64 vcc, exec, s[46:47]
	s_cbranch_vccz .LBB0_1156
	s_barrier

; #define PG8_STAGE(bufoff, gbase, voff) do { _Pragma("unroll") for (int _i = 0; _i < 2; ++_i) \
;         __builtin_amdgcn_global_load_lds((const unsigned*)((const char*)(gbase) + (voff)[_i]), (PG8_LAS unsigned*)(lds + (bufoff) + ldsw + _i * 8192), 16, 0, 0); } while (0)
; #define PG8_LDA(dst, b, h) do { _Pragma("unroll") for (int m = 0; m < 4; ++m) _Pragma("unroll") for (int k = 0; k < 2; ++k) dst[m][k] = *(const PG8_LAS bf16x8*)(lds + PG8_SA(b, h) + aoff + m * 2048 + k * 1024); } while (0)
; #define PG8_LDB(dst, b, h) do { _Pragma("unroll") for (int n = 0; n < 2; ++n) _Pragma("unroll") for (int k = 0; k < 2; ++k) dst[n][k] = *(const PG8_LAS bf16x8*)(lds + PG8_SB(b, h) + boff + n * 2048 + k * 1024); } while (0)
; #define PG8_WAIT_V(n) asm volatile("s_waitcnt vmcnt(" #n ")" ::: "memory")
; #define PG8_WAIT_L(n) asm volatile("s_waitcnt lgkmcnt(" #n ")" ::: "memory")
; #define PG8_BAR __builtin_amdgcn_s_barrier()
; #define PG8_SCHED __builtin_amdgcn_sched_barrier(0)
;     ...
;         for (int t = 0; t < nt; t += 2) {
;             const bool last = (t == nt - 2);
;             const char* a1 = cA + (size_t)(t + 1) * kstep;
;             const char* a2 = last ? nA : cA + (size_t)(t + 2) * kstep; const char* b2 = last ? nB : cB + (size_t)(t + 2) * kstep;
;             const char* a3 = a2 + kstep; const char* b3 = b2 + kstep;
;             if (last && has_next) S.a_ready(nxt);
;             if constexpr (SP2) {
;             PG8_LDB(B0, 0, 0); PG8_LDB(B1, 0, 1); PG8_SCHED; PG8_LDA(At, 0, 0); PG8_STAGE(PG8_SA(1, 1), a1 + hstepA, voffA);
;             PG8_WAIT_V(8); PG8_WAIT_L(0); PG8_BAR; PG8_MMA(0, 0, At, B0); PG8_MMA(0, 1, At, B1); PG8_BAR; PG8_SCHED;
;             PG8_LDA(At, 0, 1); PG8_STAGE(PG8_SB(0, 0), b2, voffB); PG8_STAGE(PG8_SB(0, 1), b2 + hstepB, voffB); PG8_STAGE(PG8_SA(0, 0), a2, voffA);
.LBB0_1503:
	s_add_i32 s70, s58, 2
	s_add_u32 s71, s40, 0xfffc0080
	s_addc_u32 s59, s41, -1
	s_add_i32 s76, 0, 0x10000
	s_cmp_eq_u32 s63, s58
	s_cselect_b32 s59, s51, s59
	s_cselect_b32 s58, s68, s71
	s_cselect_b32 s75, s53, s61
	s_cselect_b32 s74, s52, s60
	s_add_i32 s71, 0, 0x14000
	v_add_u32_e32 v128, s76, v187
	v_add_u32_e32 v189, s71, v187
	ds_read_b128 v[108:111], v128
	ds_read_b128 v[112:115], v128 offset:1024
	ds_read_b128 v[124:127], v128 offset:2048
	ds_read_b128 v[128:131], v128 offset:3072
	ds_read_b128 v[160:163], v189
	ds_read_b128 v[190:193], v189 offset:1024
	ds_read_b128 v[194:197], v189 offset:2048
	ds_read_b128 v[198:201], v189 offset:3072
	s_add_i32 m0, s13, 0xc000
	ds_read_b128 v[202:205], v188
	ds_read_b128 v[206:209], v188 offset:1024
	ds_read_b128 v[210:213], v188 offset:2048
	ds_read_b128 v[214:217], v188 offset:3072
	ds_read_b128 v[218:221], v188 offset:4096
	ds_read_b128 v[222:225], v188 offset:5120
	ds_read_b128 v[234:237], v188 offset:6144
	ds_read_b128 v[238:241], v188 offset:7168
	global_load_lds_dwordx4 v156, s[40:41]
	s_add_i32 m0, s13, 0xe000
	s_nop 0
	global_load_lds_dwordx4 v158, s[40:41]
	s_waitcnt vmcnt(8)
	s_waitcnt lgkmcnt(0)
	s_barrier
	v_mfma_f32_16x16x32_bf16 v[144:147], v[108:111], v[202:205], v[144:147]
	v_mfma_f32_16x16x32_bf16 v[140:143], v[124:127], v[202:205], v[140:143]
	v_mfma_f32_16x16x32_bf16 v[120:123], v[108:111], v[210:213], v[120:123]
	v_mfma_f32_16x16x32_bf16 v[116:119], v[124:127], v[210:213], v[116:119]
	v_mfma_f32_16x16x32_bf16 v[96:99], v[108:111], v[218:221], v[96:99]
	v_mfma_f32_16x16x32_bf16 v[92:95], v[124:127], v[218:221], v[92:95]
	v_mfma_f32_16x16x32_bf16 v[80:83], v[108:111], v[234:237], v[80:83]
	v_mfma_f32_16x16x32_bf16 v[76:79], v[124:127], v[234:237], v[76:79]
	v_mfma_f32_16x16x32_bf16 v[144:147], v[112:115], v[206:209], v[144:147]
	v_mfma_f32_16x16x32_bf16 v[140:143], v[128:131], v[206:209], v[140:143]
	v_mfma_f32_16x16x32_bf16 v[120:123], v[112:115], v[214:217], v[120:123]
	v_mfma_f32_16x16x32_bf16 v[116:119], v[128:131], v[214:217], v[116:119]
	v_mfma_f32_16x16x32_bf16 v[96:99], v[112:115], v[222:225], v[96:99]
	v_mfma_f32_16x16x32_bf16 v[92:95], v[128:131], v[222:225], v[92:95]
	v_mfma_f32_16x16x32_bf16 v[80:83], v[112:115], v[238:241], v[80:83]
	v_mfma_f32_16x16x32_bf16 v[76:79], v[128:131], v[238:241], v[76:79]
	v_mfma_f32_16x16x32_bf16 v[136:139], v[160:163], v[202:205], v[136:139]
	v_mfma_f32_16x16x32_bf16 v[132:135], v[194:197], v[202:205], v[132:135]
	v_mfma_f32_16x16x32_bf16 v[104:107], v[160:163], v[210:213], v[104:107]
	v_mfma_f32_16x16x32_bf16 v[100:103], v[194:197], v[210:213], v[100:103]
	v_mfma_f32_16x16x32_bf16 v[88:91], v[160:163], v[218:221], v[88:91]
	v_mfma_f32_16x16x32_bf16 v[84:87], v[194:197], v[218:221], v[84:87]
	v_mfma_f32_16x16x32_bf16 v[72:75], v[160:163], v[234:237], v[72:75]
	v_mfma_f32_16x16x32_bf16 v[68:71], v[194:197], v[234:237], v[68:71]
	v_mfma_f32_16x16x32_bf16 v[136:139], v[190:193], v[206:209], v[136:139]
	v_mfma_f32_16x16x32_bf16 v[132:135], v[198:201], v[206:209], v[132:135]
	v_mfma_f32_16x16x32_bf16 v[104:107], v[190:193], v[214:217], v[104:107]
	v_mfma_f32_16x16x32_bf16 v[100:103], v[198:201], v[214:217], v[100:103]
	v_mfma_f32_16x16x32_bf16 v[88:91], v[190:193], v[222:225], v[88:91]
	v_mfma_f32_16x16x32_bf16 v[84:87], v[198:201], v[222:225], v[84:87]
	v_mfma_f32_16x16x32_bf16 v[72:75], v[190:193], v[238:241], v[72:75]
	v_mfma_f32_16x16x32_bf16 v[68:71], v[198:201], v[238:241], v[68:71]
	s_barrier
	s_add_i32 s76, s76, s12
	v_lshl_add_u64 v[226:227], s[74:75], 0, v[34:35]
	s_mov_b32 m0, s76
	ds_read_b128 v[202:205], v188 offset:16384
	ds_read_b128 v[206:209], v188 offset:17408
	ds_read_b128 v[210:213], v188 offset:18432
	ds_read_b128 v[214:217], v188 offset:19456
	ds_read_b128 v[218:221], v188 offset:20480
	ds_read_b128 v[222:225], v188 offset:21504
	ds_read_b128 v[234:237], v188 offset:22528
	ds_read_b128 v[238:241], v188 offset:23552
	global_load_lds_dwordx4 v34, s[74:75]
	s_add_i32 m0, s76, 0x2000
	v_lshl_add_u64 v[242:243], s[74:75], 0, v[152:153]
	s_add_u32 s74, s74, s28
	s_addc_u32 s75, s75, s29
	s_add_i32 s71, s71, s12
	global_load_lds_dwordx4 v[242:243], off
	v_lshl_add_u64 v[244:245], s[74:75], 0, v[34:35]
	s_mov_b32 m0, s71
	v_lshl_add_u64 v[246:247], s[74:75], 0, v[152:153]
	global_load_lds_dwordx4 v34, s[74:75]
	s_add_i32 m0, s71, 0x2000
	v_lshl_add_u64 v[248:249], s[58:59], 0, v[148:149]
	global_load_lds_dwordx4 v152, s[74:75]
	s_mov_b32 m0, s13
	v_lshl_add_u64 v[250:251], s[58:59], 0, v[150:151]
	global_load_lds_dwordx4 v148, s[58:59]
	s_mov_b32 m0, s15
	s_nop 0
	global_load_lds_dwordx4 v150, s[58:59]
	s_waitcnt vmcnt(8)
	s_waitcnt lgkmcnt(0)
	s_barrier
; #define PG8_STAGE(bufoff, gbase, voff) do { _Pragma("unroll") for (int _i = 0; _i < 2; ++_i) \
;         __builtin_amdgcn_global_load_lds((const unsigned*)((const char*)(gbase) + (voff)[_i]), (PG8_LAS unsigned*)(lds + (bufoff) + ldsw + _i * 8192), 16, 0, 0); } while (0)
; #define PG8_LDA(dst, b, h) do { _Pragma("unroll") for (int m = 0; m < 4; ++m) _Pragma("unroll") for (int k = 0; k < 2; ++k) dst[m][k] = *(const PG8_LAS bf16x8*)(lds + PG8_SA(b, h) + aoff + m * 2048 + k * 1024); } while (0)
; #define PG8_LDB(dst, b, h) do { _Pragma("unroll") for (int n = 0; n < 2; ++n) _Pragma("unroll") for (int k = 0; k < 2; ++k) dst[n][k] = *(const PG8_LAS bf16x8*)(lds + PG8_SB(b, h) + boff + n * 2048 + k * 1024); } while (0)
; #define PG8_WAIT_V(n) asm volatile("s_waitcnt vmcnt(" #n ")" ::: "memory")
; #define PG8_WAIT_L(n) asm volatile("s_waitcnt lgkmcnt(" #n ")" ::: "memory")
; #define PG8_BAR __builtin_amdgcn_s_barrier()
; #define PG8_SCHED __builtin_amdgcn_sched_barrier(0)
;     ...
;             PG8_WAIT_V(8); PG8_WAIT_L(0); PG8_BAR; PG8_MMA(1, 0, At, B0); PG8_MMA(1, 1, At, B1); PG8_BAR; PG8_SCHED;
;             PG8_LDB(B0, 1, 0); PG8_LDB(B1, 1, 1); PG8_SCHED; PG8_LDA(At, 1, 0); PG8_STAGE(PG8_SA(0, 1), a2 + hstepA, voffA);
;             PG8_WAIT_V(8); PG8_WAIT_L(0); PG8_BAR; PG8_MMA(0, 0, At, B0); PG8_MMA(0, 1, At, B1); PG8_BAR; PG8_SCHED;
	v_mfma_f32_16x16x32_bf16 v[64:67], v[108:111], v[202:205], v[64:67]
	v_mfma_f32_16x16x32_bf16 v[60:63], v[124:127], v[202:205], v[60:63]
	v_mfma_f32_16x16x32_bf16 v[48:51], v[108:111], v[210:213], v[48:51]
	v_mfma_f32_16x16x32_bf16 v[44:47], v[124:127], v[210:213], v[44:47]
	v_mfma_f32_16x16x32_bf16 v[30:33], v[108:111], v[218:221], v[30:33]
	v_mfma_f32_16x16x32_bf16 v[26:29], v[124:127], v[218:221], v[26:29]
	v_mfma_f32_16x16x32_bf16 v[14:17], v[108:111], v[234:237], v[14:17]
	v_mfma_f32_16x16x32_bf16 v[10:13], v[124:127], v[234:237], v[10:13]
	v_mfma_f32_16x16x32_bf16 v[64:67], v[112:115], v[206:209], v[64:67]
	v_mfma_f32_16x16x32_bf16 v[60:63], v[128:131], v[206:209], v[60:63]
	v_mfma_f32_16x16x32_bf16 v[48:51], v[112:115], v[214:217], v[48:51]
	v_mfma_f32_16x16x32_bf16 v[44:47], v[128:131], v[214:217], v[44:47]
	v_mfma_f32_16x16x32_bf16 v[30:33], v[112:115], v[222:225], v[30:33]
	v_mfma_f32_16x16x32_bf16 v[26:29], v[128:131], v[222:225], v[26:29]
	v_mfma_f32_16x16x32_bf16 v[14:17], v[112:115], v[238:241], v[14:17]
	v_mfma_f32_16x16x32_bf16 v[10:13], v[128:131], v[238:241], v[10:13]
	v_mfma_f32_16x16x32_bf16 v[56:59], v[160:163], v[202:205], v[56:59]
	v_mfma_f32_16x16x32_bf16 v[52:55], v[194:197], v[202:205], v[52:55]
	v_mfma_f32_16x16x32_bf16 v[40:43], v[160:163], v[210:213], v[40:43]
	v_mfma_f32_16x16x32_bf16 v[36:39], v[194:197], v[210:213], v[36:39]
	v_mfma_f32_16x16x32_bf16 v[22:25], v[160:163], v[218:221], v[22:25]
	v_mfma_f32_16x16x32_bf16 v[18:21], v[194:197], v[218:221], v[18:21]
	v_mfma_f32_16x16x32_bf16 v[6:9], v[160:163], v[234:237], v[6:9]
	v_mfma_f32_16x16x32_bf16 v[2:5], v[194:197], v[234:237], v[2:5]
	v_mfma_f32_16x16x32_bf16 v[56:59], v[190:193], v[206:209], v[56:59]
	v_mfma_f32_16x16x32_bf16 v[52:55], v[198:201], v[206:209], v[52:55]
	v_mfma_f32_16x16x32_bf16 v[40:43], v[190:193], v[214:217], v[40:43]
	v_mfma_f32_16x16x32_bf16 v[36:39], v[198:201], v[214:217], v[36:39]
	v_mfma_f32_16x16x32_bf16 v[22:25], v[190:193], v[222:225], v[22:25]
	v_mfma_f32_16x16x32_bf16 v[18:21], v[198:201], v[222:225], v[18:21]
	v_mfma_f32_16x16x32_bf16 v[6:9], v[190:193], v[238:241], v[6:9]
	v_mfma_f32_16x16x32_bf16 v[2:5], v[198:201], v[238:241], v[2:5]
	s_barrier
	s_add_i32 s71, 0, 0x18000
	s_add_i32 s74, 0, 0x1c000
	v_add_u32_e32 v128, s71, v187
	v_add_u32_e32 v189, s74, v187
	ds_read_b128 v[108:111], v128
	ds_read_b128 v[112:115], v128 offset:1024
	ds_read_b128 v[124:127], v128 offset:2048
	ds_read_b128 v[128:131], v128 offset:3072
	ds_read_b128 v[160:163], v189
	ds_read_b128 v[190:193], v189 offset:1024
	ds_read_b128 v[194:197], v189 offset:2048
	ds_read_b128 v[198:201], v189 offset:3072
	s_add_u32 s58, s58, 0x40000
	s_addc_u32 s59, s59, 0
	s_mov_b32 m0, s21
	ds_read_b128 v[202:205], v188 offset:32768
	ds_read_b128 v[206:209], v188 offset:33792
	ds_read_b128 v[210:213], v188 offset:34816
	ds_read_b128 v[214:217], v188 offset:35840
	ds_read_b128 v[218:221], v188 offset:36864
	ds_read_b128 v[222:225], v188 offset:37888
	ds_read_b128 v[234:237], v188 offset:38912
	ds_read_b128 v[238:241], v188 offset:39936
	global_load_lds_dwordx4 v148, s[58:59]
	s_mov_b32 m0, s34
	s_nop 0
	global_load_lds_dwordx4 v150, s[58:59]
	s_waitcnt vmcnt(8)
	s_waitcnt lgkmcnt(0)
	s_barrier
	v_mfma_f32_16x16x32_bf16 v[144:147], v[108:111], v[202:205], v[144:147]
	v_mfma_f32_16x16x32_bf16 v[140:143], v[124:127], v[202:205], v[140:143]
	v_mfma_f32_16x16x32_bf16 v[120:123], v[108:111], v[210:213], v[120:123]
	v_mfma_f32_16x16x32_bf16 v[116:119], v[124:127], v[210:213], v[116:119]
	v_mfma_f32_16x16x32_bf16 v[96:99], v[108:111], v[218:221], v[96:99]
	v_mfma_f32_16x16x32_bf16 v[92:95], v[124:127], v[218:221], v[92:95]
	v_mfma_f32_16x16x32_bf16 v[80:83], v[108:111], v[234:237], v[80:83]
	v_mfma_f32_16x16x32_bf16 v[76:79], v[124:127], v[234:237], v[76:79]
	v_mfma_f32_16x16x32_bf16 v[144:147], v[112:115], v[206:209], v[144:147]
	v_mfma_f32_16x16x32_bf16 v[140:143], v[128:131], v[206:209], v[140:143]
	v_mfma_f32_16x16x32_bf16 v[120:123], v[112:115], v[214:217], v[120:123]
	v_mfma_f32_16x16x32_bf16 v[116:119], v[128:131], v[214:217], v[116:119]
	v_mfma_f32_16x16x32_bf16 v[96:99], v[112:115], v[222:225], v[96:99]
	v_mfma_f32_16x16x32_bf16 v[92:95], v[128:131], v[222:225], v[92:95]
	v_mfma_f32_16x16x32_bf16 v[80:83], v[112:115], v[238:241], v[80:83]
	v_mfma_f32_16x16x32_bf16 v[76:79], v[128:131], v[238:241], v[76:79]
	v_mfma_f32_16x16x32_bf16 v[136:139], v[160:163], v[202:205], v[136:139]
	v_mfma_f32_16x16x32_bf16 v[132:135], v[194:197], v[202:205], v[132:135]
	v_mfma_f32_16x16x32_bf16 v[104:107], v[160:163], v[210:213], v[104:107]
	v_mfma_f32_16x16x32_bf16 v[100:103], v[194:197], v[210:213], v[100:103]
	v_mfma_f32_16x16x32_bf16 v[88:91], v[160:163], v[218:221], v[88:91]
	v_mfma_f32_16x16x32_bf16 v[84:87], v[194:197], v[218:221], v[84:87]
	v_mfma_f32_16x16x32_bf16 v[72:75], v[160:163], v[234:237], v[72:75]
	v_mfma_f32_16x16x32_bf16 v[68:71], v[194:197], v[234:237], v[68:71]
	v_mfma_f32_16x16x32_bf16 v[136:139], v[190:193], v[206:209], v[136:139]
	v_mfma_f32_16x16x32_bf16 v[132:135], v[198:201], v[206:209], v[132:135]
	v_mfma_f32_16x16x32_bf16 v[104:107], v[190:193], v[214:217], v[104:107]
	v_mfma_f32_16x16x32_bf16 v[100:103], v[198:201], v[214:217], v[100:103]
	v_mfma_f32_16x16x32_bf16 v[88:91], v[190:193], v[222:225], v[88:91]
	v_mfma_f32_16x16x32_bf16 v[84:87], v[198:201], v[222:225], v[84:87]
	v_mfma_f32_16x16x32_bf16 v[72:75], v[190:193], v[238:241], v[72:75]
	v_mfma_f32_16x16x32_bf16 v[68:71], v[198:201], v[238:241], v[68:71]
	s_barrier
; #define PG8_STAGE(bufoff, gbase, voff) do { _Pragma("unroll") for (int _i = 0; _i < 2; ++_i) \
;         __builtin_amdgcn_global_load_lds((const unsigned*)((const char*)(gbase) + (voff)[_i]), (PG8_LAS unsigned*)(lds + (bufoff) + ldsw + _i * 8192), 16, 0, 0); } while (0)
; #define PG8_LDA(dst, b, h) do { _Pragma("unroll") for (int m = 0; m < 4; ++m) _Pragma("unroll") for (int k = 0; k < 2; ++k) dst[m][k] = *(const PG8_LAS bf16x8*)(lds + PG8_SA(b, h) + aoff + m * 2048 + k * 1024); } while (0)
; #define PG8_WAIT_V(n) asm volatile("s_waitcnt vmcnt(" #n ")" ::: "memory")
; #define PG8_WAIT_L(n) asm volatile("s_waitcnt lgkmcnt(" #n ")" ::: "memory")
; #define PG8_BAR __builtin_amdgcn_s_barrier()
; #define PG8_SCHED __builtin_amdgcn_sched_barrier(0)
;     ...
;             PG8_LDA(At, 1, 1); PG8_STAGE(PG8_SB(1, 0), b3, voffB); PG8_STAGE(PG8_SB(1, 1), b3 + hstepB, voffB); PG8_STAGE(PG8_SA(1, 0), a3, voffA);
;             PG8_WAIT_V(8); PG8_WAIT_L(0); PG8_BAR; PG8_MMA(1, 0, At, B0); PG8_MMA(1, 1, At, B1); PG8_BAR; PG8_SCHED;
	s_add_i32 s58, s71, s12
	v_lshl_add_u64 v[226:227], v[226:227], 0, s[22:23]
	s_mov_b32 m0, s58
	ds_read_b128 v[202:205], v188 offset:49152
	ds_read_b128 v[206:209], v188 offset:50176
	ds_read_b128 v[210:213], v188 offset:51200
	ds_read_b128 v[214:217], v188 offset:52224
	ds_read_b128 v[218:221], v188 offset:53248
	ds_read_b128 v[222:225], v188 offset:54272
	ds_read_b128 v[234:237], v188 offset:55296
	ds_read_b128 v[238:241], v188 offset:56320
	global_load_lds_dwordx4 v[226:227], off
	v_lshl_add_u64 v[226:227], v[242:243], 0, s[22:23]
	s_add_i32 m0, s58, 0x2000
	s_add_i32 s58, s74, s12
	global_load_lds_dwordx4 v[226:227], off
	v_lshl_add_u64 v[226:227], v[244:245], 0, s[22:23]
	s_mov_b32 m0, s58
	s_nop 0
	global_load_lds_dwordx4 v[226:227], off
	v_lshl_add_u64 v[226:227], v[246:247], 0, s[22:23]
	s_add_i32 m0, s58, 0x2000
	s_nop 0
	global_load_lds_dwordx4 v[226:227], off
	v_lshl_add_u64 v[226:227], v[248:249], 0, s[22:23]
	s_mov_b32 m0, s57
	s_nop 0
	global_load_lds_dwordx4 v[226:227], off
	v_lshl_add_u64 v[226:227], v[250:251], 0, s[22:23]
	s_mov_b32 m0, s62
	s_nop 0
	global_load_lds_dwordx4 v[226:227], off
	s_waitcnt vmcnt(8)
	s_waitcnt lgkmcnt(0)
	s_barrier
	v_mfma_f32_16x16x32_bf16 v[64:67], v[108:111], v[202:205], v[64:67]
	v_mfma_f32_16x16x32_bf16 v[60:63], v[124:127], v[202:205], v[60:63]
	v_mfma_f32_16x16x32_bf16 v[48:51], v[108:111], v[210:213], v[48:51]
	v_mfma_f32_16x16x32_bf16 v[44:47], v[124:127], v[210:213], v[44:47]
	v_mfma_f32_16x16x32_bf16 v[30:33], v[108:111], v[218:221], v[30:33]
	v_mfma_f32_16x16x32_bf16 v[26:29], v[124:127], v[218:221], v[26:29]
	v_mfma_f32_16x16x32_bf16 v[14:17], v[108:111], v[234:237], v[14:17]
	v_mfma_f32_16x16x32_bf16 v[10:13], v[124:127], v[234:237], v[10:13]
	v_mfma_f32_16x16x32_bf16 v[64:67], v[112:115], v[206:209], v[64:67]
	v_mfma_f32_16x16x32_bf16 v[60:63], v[128:131], v[206:209], v[60:63]
	v_mfma_f32_16x16x32_bf16 v[48:51], v[112:115], v[214:217], v[48:51]
	v_mfma_f32_16x16x32_bf16 v[44:47], v[128:131], v[214:217], v[44:47]
	v_mfma_f32_16x16x32_bf16 v[30:33], v[112:115], v[222:225], v[30:33]
	v_mfma_f32_16x16x32_bf16 v[26:29], v[128:131], v[222:225], v[26:29]
	v_mfma_f32_16x16x32_bf16 v[14:17], v[112:115], v[238:241], v[14:17]
	v_mfma_f32_16x16x32_bf16 v[10:13], v[128:131], v[238:241], v[10:13]
	v_mfma_f32_16x16x32_bf16 v[56:59], v[160:163], v[202:205], v[56:59]
	v_mfma_f32_16x16x32_bf16 v[52:55], v[194:197], v[202:205], v[52:55]
	v_mfma_f32_16x16x32_bf16 v[40:43], v[160:163], v[210:213], v[40:43]
	v_mfma_f32_16x16x32_bf16 v[36:39], v[194:197], v[210:213], v[36:39]
	v_mfma_f32_16x16x32_bf16 v[22:25], v[160:163], v[218:221], v[22:25]
	v_mfma_f32_16x16x32_bf16 v[18:21], v[194:197], v[218:221], v[18:21]
	v_mfma_f32_16x16x32_bf16 v[6:9], v[160:163], v[234:237], v[6:9]
	v_mfma_f32_16x16x32_bf16 v[2:5], v[194:197], v[234:237], v[2:5]
	v_mfma_f32_16x16x32_bf16 v[56:59], v[190:193], v[206:209], v[56:59]
	v_mfma_f32_16x16x32_bf16 v[52:55], v[198:201], v[206:209], v[52:55]
	v_mfma_f32_16x16x32_bf16 v[40:43], v[190:193], v[214:217], v[40:43]
	v_mfma_f32_16x16x32_bf16 v[36:39], v[198:201], v[214:217], v[36:39]
	v_mfma_f32_16x16x32_bf16 v[22:25], v[190:193], v[222:225], v[22:25]
	v_mfma_f32_16x16x32_bf16 v[18:21], v[198:201], v[222:225], v[18:21]
	v_mfma_f32_16x16x32_bf16 v[6:9], v[190:193], v[238:241], v[6:9]
	v_mfma_f32_16x16x32_bf16 v[2:5], v[198:201], v[238:241], v[2:5]
	s_barrier
	s_add_u32 s40, s40, 0x100
	s_addc_u32 s41, s41, 0
	s_add_u32 s60, s60, 0x100
	s_addc_u32 s61, s61, 0
	s_cmp_ge_i32 s70, s35
	s_mov_b32 s58, s70
	s_cbranch_scc0 .LBB0_1503
	s_movk_i32 s71, 0x6ff

; #define PG8_STAGE(bufoff, gbase, voff) do { _Pragma("unroll") for (int _i = 0; _i < 2; ++_i) \
;         __builtin_amdgcn_global_load_lds((const unsigned*)((const char*)(gbase) + (voff)[_i]), (PG8_LAS unsigned*)(lds + (bufoff) + ldsw + _i * 8192), 16, 0, 0); } while (0)
; #define PG8_LDA(dst, b, h) do { _Pragma("unroll") for (int m = 0; m < 4; ++m) _Pragma("unroll") for (int k = 0; k < 2; ++k) dst[m][k] = *(const PG8_LAS bf16x8*)(lds + PG8_SA(b, h) + aoff + m * 2048 + k * 1024); } while (0)
; #define PG8_LDB(dst, b, h) do { _Pragma("unroll") for (int n = 0; n < 2; ++n) _Pragma("unroll") for (int k = 0; k < 2; ++k) dst[n][k] = *(const PG8_LAS bf16x8*)(lds + PG8_SB(b, h) + boff + n * 2048 + k * 1024); } while (0)
; #define PG8_WAIT_V(n) asm volatile("s_waitcnt vmcnt(" #n ")" ::: "memory")
; #define PG8_WAIT_L(n) asm volatile("s_waitcnt lgkmcnt(" #n ")" ::: "memory")
; #define PG8_BAR __builtin_amdgcn_s_barrier()
; #define PG8_SCHED __builtin_amdgcn_sched_barrier(0)
;     ...
;             PG8_LDB(B0, 0, 0); PG8_LDB(B1, 0, 1); PG8_SCHED; PG8_LDA(At, 0, 0); PG8_STAGE(PG8_SA(1, 1), a1 + hstepA, voffA);
;             PG8_WAIT_V(8); PG8_WAIT_L(0); PG8_BAR; PG8_MMA(0, 0, At, B0); PG8_MMA(0, 1, At, B1); PG8_BAR; PG8_SCHED;
;             PG8_LDA(At, 0, 1); PG8_STAGE(PG8_SB(0, 0), b2, voffB); PG8_STAGE(PG8_SB(0, 1), b2 + hstepB, voffB); PG8_STAGE(PG8_SA(0, 0), a2, voffA);
;             PG8_WAIT_V(8); PG8_WAIT_L(0); PG8_BAR; PG8_MMA(1, 0, At, B0); PG8_MMA(1, 1, At, B1); PG8_BAR; PG8_SCHED;
.LBB0_2023:
	v_add_u32_e32 v163, 0x10000, v235
	s_add_u32 s35, s40, 0xfffc0080
	s_addc_u32 s37, s41, -1
	s_add_i32 s43, 0, 0x10000
	s_cmp_eq_u32 s34, 12
	s_cselect_b32 s57, s49, s37
	s_cselect_b32 s56, s48, s35
	s_cselect_b32 s55, s51, s24
	s_cselect_b32 s54, s50, s15
	s_add_i32 s35, 0, 0x14000
	ds_read_b128 v[142:145], v163
	ds_read_b128 v[146:149], v163 offset:1024
	ds_read_b128 v[150:153], v163 offset:2048
	ds_read_b128 v[154:157], v163 offset:3072
	ds_read_b128 v[158:161], v163 offset:16384
	ds_read_b128 v[186:189], v163 offset:17408
	ds_read_b128 v[190:193], v163 offset:18432
	ds_read_b128 v[194:197], v163 offset:19456
	s_add_i32 m0, s53, 0xc000
	ds_read_b128 v[198:201], v237
	ds_read_b128 v[202:205], v237 offset:1024
	ds_read_b128 v[206:209], v237 offset:2048
	ds_read_b128 v[210:213], v237 offset:3072
	ds_read_b128 v[214:217], v237 offset:4096
	ds_read_b128 v[218:221], v237 offset:5120
	ds_read_b128 v[222:225], v237 offset:6144
	ds_read_b128 v[238:241], v237 offset:7168
	global_load_lds_dwordx4 v138, s[40:41]
	s_add_i32 m0, s53, 0xe000
	s_nop 0
	global_load_lds_dwordx4 v140, s[40:41]
	s_waitcnt vmcnt(8)
	s_waitcnt lgkmcnt(0)
	s_barrier
	v_mfma_f32_16x16x32_bf16 v[128:131], v[142:145], v[198:201], v[128:131]
	v_mfma_f32_16x16x32_bf16 v[124:127], v[150:153], v[198:201], v[124:127]
	v_mfma_f32_16x16x32_bf16 v[120:123], v[142:145], v[206:209], v[120:123]
	v_mfma_f32_16x16x32_bf16 v[116:119], v[150:153], v[206:209], v[116:119]
	v_mfma_f32_16x16x32_bf16 v[112:115], v[142:145], v[214:217], v[112:115]
	v_mfma_f32_16x16x32_bf16 v[108:111], v[150:153], v[214:217], v[108:111]
	v_mfma_f32_16x16x32_bf16 v[104:107], v[142:145], v[222:225], v[104:107]
	v_mfma_f32_16x16x32_bf16 v[100:103], v[150:153], v[222:225], v[100:103]
	v_mfma_f32_16x16x32_bf16 v[128:131], v[146:149], v[202:205], v[128:131]
	v_mfma_f32_16x16x32_bf16 v[124:127], v[154:157], v[202:205], v[124:127]
	v_mfma_f32_16x16x32_bf16 v[120:123], v[146:149], v[210:213], v[120:123]
	v_mfma_f32_16x16x32_bf16 v[116:119], v[154:157], v[210:213], v[116:119]
	v_mfma_f32_16x16x32_bf16 v[112:115], v[146:149], v[218:221], v[112:115]
	v_mfma_f32_16x16x32_bf16 v[108:111], v[154:157], v[218:221], v[108:111]
	v_mfma_f32_16x16x32_bf16 v[104:107], v[146:149], v[238:241], v[104:107]
	v_mfma_f32_16x16x32_bf16 v[100:103], v[154:157], v[238:241], v[100:103]
	v_mfma_f32_16x16x32_bf16 v[96:99], v[158:161], v[198:201], v[96:99]
	v_mfma_f32_16x16x32_bf16 v[92:95], v[190:193], v[198:201], v[92:95]
	v_mfma_f32_16x16x32_bf16 v[88:91], v[158:161], v[206:209], v[88:91]
	v_mfma_f32_16x16x32_bf16 v[84:87], v[190:193], v[206:209], v[84:87]
	v_mfma_f32_16x16x32_bf16 v[80:83], v[158:161], v[214:217], v[80:83]
	v_mfma_f32_16x16x32_bf16 v[76:79], v[190:193], v[214:217], v[76:79]
	v_mfma_f32_16x16x32_bf16 v[72:75], v[158:161], v[222:225], v[72:75]
	v_mfma_f32_16x16x32_bf16 v[68:71], v[190:193], v[222:225], v[68:71]
	v_mfma_f32_16x16x32_bf16 v[96:99], v[186:189], v[202:205], v[96:99]
	v_mfma_f32_16x16x32_bf16 v[92:95], v[194:197], v[202:205], v[92:95]
	v_mfma_f32_16x16x32_bf16 v[88:91], v[186:189], v[210:213], v[88:91]
	v_mfma_f32_16x16x32_bf16 v[84:87], v[194:197], v[210:213], v[84:87]
	v_mfma_f32_16x16x32_bf16 v[80:83], v[186:189], v[218:221], v[80:83]
	v_mfma_f32_16x16x32_bf16 v[76:79], v[194:197], v[218:221], v[76:79]
	v_mfma_f32_16x16x32_bf16 v[72:75], v[186:189], v[238:241], v[72:75]
	v_mfma_f32_16x16x32_bf16 v[68:71], v[194:197], v[238:241], v[68:71]
	s_barrier
	s_add_i32 s37, s43, s21
	s_mov_b32 m0, s37
	ds_read_b128 v[198:201], v237 offset:16384
	ds_read_b128 v[202:205], v237 offset:17408
	ds_read_b128 v[206:209], v237 offset:18432
	ds_read_b128 v[210:213], v237 offset:19456
	ds_read_b128 v[214:217], v237 offset:20480
	ds_read_b128 v[218:221], v237 offset:21504
	ds_read_b128 v[222:225], v237 offset:22528
	ds_read_b128 v[238:241], v237 offset:23552
	global_load_lds_dwordx4 v34, s[54:55]
	s_add_i32 m0, s37, 0x2000
	s_add_u32 s66, s54, 0x40000
	s_addc_u32 s67, s55, 0
	s_add_i32 s35, s35, s21
	global_load_lds_dwordx4 v136, s[54:55]
	s_mov_b32 m0, s35
	s_nop 0
	global_load_lds_dwordx4 v34, s[66:67]
	s_add_i32 m0, s35, 0x2000
	s_nop 0
	global_load_lds_dwordx4 v136, s[66:67]
	s_mov_b32 m0, s53
	s_nop 0
	global_load_lds_dwordx4 v132, s[56:57]
	s_mov_b32 m0, s58
	s_nop 0
	global_load_lds_dwordx4 v134, s[56:57]
	s_waitcnt vmcnt(8)
	s_waitcnt lgkmcnt(0)
	s_barrier
	v_mfma_f32_16x16x32_bf16 v[64:67], v[142:145], v[198:201], v[64:67]
	v_mfma_f32_16x16x32_bf16 v[60:63], v[150:153], v[198:201], v[60:63]
	v_mfma_f32_16x16x32_bf16 v[56:59], v[142:145], v[206:209], v[56:59]
	v_mfma_f32_16x16x32_bf16 v[52:55], v[150:153], v[206:209], v[52:55]
	v_mfma_f32_16x16x32_bf16 v[48:51], v[142:145], v[214:217], v[48:51]
	v_mfma_f32_16x16x32_bf16 v[44:47], v[150:153], v[214:217], v[44:47]
	v_mfma_f32_16x16x32_bf16 v[40:43], v[142:145], v[222:225], v[40:43]
	v_mfma_f32_16x16x32_bf16 v[36:39], v[150:153], v[222:225], v[36:39]
	v_mfma_f32_16x16x32_bf16 v[64:67], v[146:149], v[202:205], v[64:67]
	v_mfma_f32_16x16x32_bf16 v[60:63], v[154:157], v[202:205], v[60:63]
	v_mfma_f32_16x16x32_bf16 v[56:59], v[146:149], v[210:213], v[56:59]
	v_mfma_f32_16x16x32_bf16 v[52:55], v[154:157], v[210:213], v[52:55]
	v_mfma_f32_16x16x32_bf16 v[48:51], v[146:149], v[218:221], v[48:51]
	v_mfma_f32_16x16x32_bf16 v[44:47], v[154:157], v[218:221], v[44:47]
	v_mfma_f32_16x16x32_bf16 v[40:43], v[146:149], v[238:241], v[40:43]
	v_mfma_f32_16x16x32_bf16 v[36:39], v[154:157], v[238:241], v[36:39]
	v_mfma_f32_16x16x32_bf16 v[30:33], v[158:161], v[198:201], v[30:33]
	v_mfma_f32_16x16x32_bf16 v[26:29], v[190:193], v[198:201], v[26:29]
	v_mfma_f32_16x16x32_bf16 v[22:25], v[158:161], v[206:209], v[22:25]
	v_mfma_f32_16x16x32_bf16 v[18:21], v[190:193], v[206:209], v[18:21]
	v_mfma_f32_16x16x32_bf16 v[14:17], v[158:161], v[214:217], v[14:17]
	v_mfma_f32_16x16x32_bf16 v[10:13], v[190:193], v[214:217], v[10:13]
	v_mfma_f32_16x16x32_bf16 v[6:9], v[158:161], v[222:225], v[6:9]
	v_mfma_f32_16x16x32_bf16 v[2:5], v[190:193], v[222:225], v[2:5]
	v_mfma_f32_16x16x32_bf16 v[30:33], v[186:189], v[202:205], v[30:33]
	v_mfma_f32_16x16x32_bf16 v[26:29], v[194:197], v[202:205], v[26:29]
	v_mfma_f32_16x16x32_bf16 v[22:25], v[186:189], v[210:213], v[22:25]
	v_mfma_f32_16x16x32_bf16 v[18:21], v[194:197], v[210:213], v[18:21]
	v_mfma_f32_16x16x32_bf16 v[14:17], v[186:189], v[218:221], v[14:17]
	v_mfma_f32_16x16x32_bf16 v[10:13], v[194:197], v[218:221], v[10:13]
	v_mfma_f32_16x16x32_bf16 v[6:9], v[186:189], v[238:241], v[6:9]
	v_mfma_f32_16x16x32_bf16 v[2:5], v[194:197], v[238:241], v[2:5]
	s_barrier
; #define PG8_STAGE(bufoff, gbase, voff) do { _Pragma("unroll") for (int _i = 0; _i < 2; ++_i) \
;         __builtin_amdgcn_global_load_lds((const unsigned*)((const char*)(gbase) + (voff)[_i]), (PG8_LAS unsigned*)(lds + (bufoff) + ldsw + _i * 8192), 16, 0, 0); } while (0)
; #define PG8_LDA(dst, b, h) do { _Pragma("unroll") for (int m = 0; m < 4; ++m) _Pragma("unroll") for (int k = 0; k < 2; ++k) dst[m][k] = *(const PG8_LAS bf16x8*)(lds + PG8_SA(b, h) + aoff + m * 2048 + k * 1024); } while (0)
; #define PG8_LDB(dst, b, h) do { _Pragma("unroll") for (int n = 0; n < 2; ++n) _Pragma("unroll") for (int k = 0; k < 2; ++k) dst[n][k] = *(const PG8_LAS bf16x8*)(lds + PG8_SB(b, h) + boff + n * 2048 + k * 1024); } while (0)
; #define PG8_WAIT_V(n) asm volatile("s_waitcnt vmcnt(" #n ")" ::: "memory")
; #define PG8_WAIT_L(n) asm volatile("s_waitcnt lgkmcnt(" #n ")" ::: "memory")
; #define PG8_BAR __builtin_amdgcn_s_barrier()
; #define PG8_SCHED __builtin_amdgcn_sched_barrier(0)
;     ...
;             PG8_LDB(B0, 1, 0); PG8_LDB(B1, 1, 1); PG8_SCHED; PG8_LDA(At, 1, 0); PG8_STAGE(PG8_SA(0, 1), a2 + hstepA, voffA);
;             PG8_WAIT_V(8); PG8_WAIT_L(0); PG8_BAR; PG8_MMA(0, 0, At, B0); PG8_MMA(0, 1, At, B1); PG8_BAR; PG8_SCHED;
;             PG8_LDA(At, 1, 1); PG8_STAGE(PG8_SB(1, 0), b3, voffB); PG8_STAGE(PG8_SB(1, 1), b3 + hstepB, voffB); PG8_STAGE(PG8_SA(1, 0), a3, voffA);
;             PG8_WAIT_V(8); PG8_WAIT_L(0); PG8_BAR; PG8_MMA(1, 0, At, B0); PG8_MMA(1, 1, At, B1); PG8_BAR; PG8_SCHED;
	s_add_i32 s35, 0, 0x18000
	s_add_i32 s37, 0, 0x1c000
	ds_read_b128 v[142:145], v163 offset:32768
	ds_read_b128 v[146:149], v163 offset:33792
	ds_read_b128 v[150:153], v163 offset:34816
	ds_read_b128 v[154:157], v163 offset:35840
	ds_read_b128 v[158:161], v163 offset:49152
	ds_read_b128 v[186:189], v163 offset:50176
	ds_read_b128 v[190:193], v163 offset:51200
	ds_read_b128 v[194:197], v163 offset:52224
	s_add_u32 s56, s56, 0x40000
	s_addc_u32 s57, s57, 0
	s_mov_b32 m0, s59
	ds_read_b128 v[198:201], v237 offset:32768
	ds_read_b128 v[202:205], v237 offset:33792
	ds_read_b128 v[206:209], v237 offset:34816
	ds_read_b128 v[210:213], v237 offset:35840
	ds_read_b128 v[214:217], v237 offset:36864
	ds_read_b128 v[218:221], v237 offset:37888
	ds_read_b128 v[222:225], v237 offset:38912
	ds_read_b128 v[238:241], v237 offset:39936
	global_load_lds_dwordx4 v132, s[56:57]
	s_mov_b32 m0, s60
	s_nop 0
	global_load_lds_dwordx4 v134, s[56:57]
	s_waitcnt vmcnt(8)
	s_waitcnt lgkmcnt(0)
	s_barrier
	v_mfma_f32_16x16x32_bf16 v[128:131], v[142:145], v[198:201], v[128:131]
	v_mfma_f32_16x16x32_bf16 v[124:127], v[150:153], v[198:201], v[124:127]
	v_mfma_f32_16x16x32_bf16 v[120:123], v[142:145], v[206:209], v[120:123]
	v_mfma_f32_16x16x32_bf16 v[116:119], v[150:153], v[206:209], v[116:119]
	v_mfma_f32_16x16x32_bf16 v[112:115], v[142:145], v[214:217], v[112:115]
	v_mfma_f32_16x16x32_bf16 v[108:111], v[150:153], v[214:217], v[108:111]
	v_mfma_f32_16x16x32_bf16 v[104:107], v[142:145], v[222:225], v[104:107]
	v_mfma_f32_16x16x32_bf16 v[100:103], v[150:153], v[222:225], v[100:103]
	v_mfma_f32_16x16x32_bf16 v[128:131], v[146:149], v[202:205], v[128:131]
	v_mfma_f32_16x16x32_bf16 v[124:127], v[154:157], v[202:205], v[124:127]
	v_mfma_f32_16x16x32_bf16 v[120:123], v[146:149], v[210:213], v[120:123]
	v_mfma_f32_16x16x32_bf16 v[116:119], v[154:157], v[210:213], v[116:119]
	v_mfma_f32_16x16x32_bf16 v[112:115], v[146:149], v[218:221], v[112:115]
	v_mfma_f32_16x16x32_bf16 v[108:111], v[154:157], v[218:221], v[108:111]
	v_mfma_f32_16x16x32_bf16 v[104:107], v[146:149], v[238:241], v[104:107]
	v_mfma_f32_16x16x32_bf16 v[100:103], v[154:157], v[238:241], v[100:103]
	v_mfma_f32_16x16x32_bf16 v[96:99], v[158:161], v[198:201], v[96:99]
	v_mfma_f32_16x16x32_bf16 v[92:95], v[190:193], v[198:201], v[92:95]
	v_mfma_f32_16x16x32_bf16 v[88:91], v[158:161], v[206:209], v[88:91]
	v_mfma_f32_16x16x32_bf16 v[84:87], v[190:193], v[206:209], v[84:87]
	v_mfma_f32_16x16x32_bf16 v[80:83], v[158:161], v[214:217], v[80:83]
	v_mfma_f32_16x16x32_bf16 v[76:79], v[190:193], v[214:217], v[76:79]
	v_mfma_f32_16x16x32_bf16 v[72:75], v[158:161], v[222:225], v[72:75]
	v_mfma_f32_16x16x32_bf16 v[68:71], v[190:193], v[222:225], v[68:71]
	v_mfma_f32_16x16x32_bf16 v[96:99], v[186:189], v[202:205], v[96:99]
	v_mfma_f32_16x16x32_bf16 v[92:95], v[194:197], v[202:205], v[92:95]
	v_mfma_f32_16x16x32_bf16 v[88:91], v[186:189], v[210:213], v[88:91]
	v_mfma_f32_16x16x32_bf16 v[84:87], v[194:197], v[210:213], v[84:87]
	v_mfma_f32_16x16x32_bf16 v[80:83], v[186:189], v[218:221], v[80:83]
	v_mfma_f32_16x16x32_bf16 v[76:79], v[194:197], v[218:221], v[76:79]
	v_mfma_f32_16x16x32_bf16 v[72:75], v[186:189], v[238:241], v[72:75]
	v_mfma_f32_16x16x32_bf16 v[68:71], v[194:197], v[238:241], v[68:71]
	s_barrier
	s_add_i32 s35, s35, s21
	s_mov_b32 m0, s35
	ds_read_b128 v[198:201], v237 offset:49152
	ds_read_b128 v[202:205], v237 offset:50176
	ds_read_b128 v[206:209], v237 offset:51200
	ds_read_b128 v[210:213], v237 offset:52224
	ds_read_b128 v[214:217], v237 offset:53248
	ds_read_b128 v[218:221], v237 offset:54272
	ds_read_b128 v[222:225], v237 offset:55296
	ds_read_b128 v[238:241], v237 offset:56320
	s_add_u32 vcc_lo, s54, 0x80
	s_addc_u32 vcc_hi, s55, 0
	global_load_lds_dwordx4 v34, vcc
	s_add_i32 m0, s35, 0x2000
	s_add_u32 s54, s54, 0x40080
	s_addc_u32 s55, s55, 0
	s_add_i32 s35, s37, s21
	s_add_u32 vcc_lo, s54, 0xfffc0000
	s_addc_u32 vcc_hi, s55, -1
	global_load_lds_dwordx4 v136, vcc
	s_mov_b32 m0, s35
	s_nop 0
	global_load_lds_dwordx4 v34, s[54:55]
	s_add_i32 m0, s35, 0x2000
	s_nop 0
	global_load_lds_dwordx4 v136, s[54:55]
	s_mov_b32 m0, s61
	s_nop 0
	s_add_u32 vcc_lo, s56, 0xfffc0080
	s_addc_u32 vcc_hi, s57, -1
	global_load_lds_dwordx4 v132, vcc
	s_mov_b32 m0, s62
	s_nop 0
	s_add_u32 vcc_lo, s56, 0xfffc0080
	s_addc_u32 vcc_hi, s57, -1
	global_load_lds_dwordx4 v134, vcc
	s_waitcnt vmcnt(8)
	s_waitcnt lgkmcnt(0)
	s_barrier
	v_mfma_f32_16x16x32_bf16 v[64:67], v[142:145], v[198:201], v[64:67]
	v_mfma_f32_16x16x32_bf16 v[60:63], v[150:153], v[198:201], v[60:63]
	v_mfma_f32_16x16x32_bf16 v[56:59], v[142:145], v[206:209], v[56:59]
	v_mfma_f32_16x16x32_bf16 v[52:55], v[150:153], v[206:209], v[52:55]
	v_mfma_f32_16x16x32_bf16 v[48:51], v[142:145], v[214:217], v[48:51]
	v_mfma_f32_16x16x32_bf16 v[44:47], v[150:153], v[214:217], v[44:47]
	v_mfma_f32_16x16x32_bf16 v[40:43], v[142:145], v[222:225], v[40:43]
	v_mfma_f32_16x16x32_bf16 v[36:39], v[150:153], v[222:225], v[36:39]
	v_mfma_f32_16x16x32_bf16 v[64:67], v[146:149], v[202:205], v[64:67]
	v_mfma_f32_16x16x32_bf16 v[60:63], v[154:157], v[202:205], v[60:63]
	v_mfma_f32_16x16x32_bf16 v[56:59], v[146:149], v[210:213], v[56:59]
	v_mfma_f32_16x16x32_bf16 v[52:55], v[154:157], v[210:213], v[52:55]
	v_mfma_f32_16x16x32_bf16 v[48:51], v[146:149], v[218:221], v[48:51]
	v_mfma_f32_16x16x32_bf16 v[44:47], v[154:157], v[218:221], v[44:47]
	v_mfma_f32_16x16x32_bf16 v[40:43], v[146:149], v[238:241], v[40:43]
	v_mfma_f32_16x16x32_bf16 v[36:39], v[154:157], v[238:241], v[36:39]
	v_mfma_f32_16x16x32_bf16 v[30:33], v[158:161], v[198:201], v[30:33]
	v_mfma_f32_16x16x32_bf16 v[26:29], v[190:193], v[198:201], v[26:29]
	v_mfma_f32_16x16x32_bf16 v[22:25], v[158:161], v[206:209], v[22:25]
	v_mfma_f32_16x16x32_bf16 v[18:21], v[190:193], v[206:209], v[18:21]
	v_mfma_f32_16x16x32_bf16 v[14:17], v[158:161], v[214:217], v[14:17]
	v_mfma_f32_16x16x32_bf16 v[10:13], v[190:193], v[214:217], v[10:13]
	v_mfma_f32_16x16x32_bf16 v[6:9], v[158:161], v[222:225], v[6:9]
	v_mfma_f32_16x16x32_bf16 v[2:5], v[190:193], v[222:225], v[2:5]
	v_mfma_f32_16x16x32_bf16 v[30:33], v[186:189], v[202:205], v[30:33]
	v_mfma_f32_16x16x32_bf16 v[26:29], v[194:197], v[202:205], v[26:29]
	v_mfma_f32_16x16x32_bf16 v[22:25], v[186:189], v[210:213], v[22:25]
	v_mfma_f32_16x16x32_bf16 v[18:21], v[194:197], v[210:213], v[18:21]
	v_mfma_f32_16x16x32_bf16 v[14:17], v[186:189], v[218:221], v[14:17]
	v_mfma_f32_16x16x32_bf16 v[10:13], v[194:197], v[218:221], v[10:13]
	v_mfma_f32_16x16x32_bf16 v[6:9], v[186:189], v[238:241], v[6:9]
	v_mfma_f32_16x16x32_bf16 v[2:5], v[194:197], v[238:241], v[2:5]
	s_barrier
	s_add_i32 s34, s34, 2
	s_add_u32 s40, s40, 0x100
	s_addc_u32 s41, s41, 0
	s_add_u32 s15, s15, 0x100
	s_addc_u32 s24, s24, 0
	s_cmp_gt_u32 s34, 13
	s_cbranch_scc0 .LBB0_2023
	s_and_b64 vcc, exec, s[30:31]
	s_cbranch_vccz .LBB0_2026
	s_barrier

; #define PG8_STAGE(bufoff, gbase, voff) do { _Pragma("unroll") for (int _i = 0; _i < 2; ++_i) \
;         __builtin_amdgcn_global_load_lds((const unsigned*)((const char*)(gbase) + (voff)[_i]), (PG8_LAS unsigned*)(lds + (bufoff) + ldsw + _i * 8192), 16, 0, 0); } while (0)
; #define PG8_LDA(dst, b, h) do { _Pragma("unroll") for (int m = 0; m < 4; ++m) _Pragma("unroll") for (int k = 0; k < 2; ++k) dst[m][k] = *(const PG8_LAS bf16x8*)(lds + PG8_SA(b, h) + aoff + m * 2048 + k * 1024); } while (0)
; #define PG8_LDB(dst, b, h) do { _Pragma("unroll") for (int n = 0; n < 2; ++n) _Pragma("unroll") for (int k = 0; k < 2; ++k) dst[n][k] = *(const PG8_LAS bf16x8*)(lds + PG8_SB(b, h) + boff + n * 2048 + k * 1024); } while (0)
; #define PG8_WAIT_V(n) asm volatile("s_waitcnt vmcnt(" #n ")" ::: "memory")
; #define PG8_WAIT_L(n) asm volatile("s_waitcnt lgkmcnt(" #n ")" ::: "memory")
; #define PG8_BAR __builtin_amdgcn_s_barrier()
; #define PG8_SCHED __builtin_amdgcn_sched_barrier(0)
;     ...
;             PG8_LDB(B0, 0, 0); PG8_LDB(B1, 0, 1); PG8_SCHED; PG8_LDA(At, 0, 0); PG8_STAGE(PG8_SA(1, 1), a1 + hstepA, voffA);
;             PG8_WAIT_V(8); PG8_WAIT_L(0); PG8_BAR; PG8_MMA(0, 0, At, B0); PG8_MMA(0, 1, At, B1); PG8_BAR; PG8_SCHED;
;             PG8_LDA(At, 0, 1); PG8_STAGE(PG8_SB(0, 0), b2, voffB); PG8_STAGE(PG8_SB(0, 1), b2 + hstepB, voffB); PG8_STAGE(PG8_SA(0, 0), a2, voffA);
;             PG8_WAIT_V(8); PG8_WAIT_L(0); PG8_BAR; PG8_MMA(1, 0, At, B0); PG8_MMA(1, 1, At, B1); PG8_BAR; PG8_SCHED;
.LBB0_2138:
	v_add_u32_e32 v163, 0x10000, v143
	s_add_u32 s48, s46, 0xfff80080
	s_addc_u32 s49, s47, -1
	s_add_i32 s61, 0, 0x10000
	s_cmp_eq_u32 s60, 28
	s_cselect_b32 s51, s41, s49
	s_cselect_b32 s50, s56, s48
	s_cselect_b32 s49, s37, s59
	s_cselect_b32 s48, s57, s58
	s_add_i32 s64, 0, 0x14000
	ds_read_b128 v[146:149], v163
	ds_read_b128 v[150:153], v163 offset:1024
	ds_read_b128 v[154:157], v163 offset:2048
	ds_read_b128 v[158:161], v163 offset:3072
	ds_read_b128 v[186:189], v163 offset:16384
	ds_read_b128 v[190:193], v163 offset:17408
	ds_read_b128 v[194:197], v163 offset:18432
	ds_read_b128 v[198:201], v163 offset:19456
	s_add_i32 m0, s21, 0xc000
	ds_read_b128 v[202:205], v145
	ds_read_b128 v[206:209], v145 offset:1024
	ds_read_b128 v[210:213], v145 offset:2048
	ds_read_b128 v[214:217], v145 offset:3072
	ds_read_b128 v[218:221], v145 offset:4096
	ds_read_b128 v[222:225], v145 offset:5120
	ds_read_b128 v[234:237], v145 offset:6144
	ds_read_b128 v[238:241], v145 offset:7168
	global_load_lds_dwordx4 v138, s[46:47]
	s_add_i32 m0, s21, 0xe000
	s_nop 0
	global_load_lds_dwordx4 v140, s[46:47]
	s_waitcnt vmcnt(8)
	s_waitcnt lgkmcnt(0)
	s_barrier
	v_mfma_f32_16x16x32_bf16 v[128:131], v[146:149], v[202:205], v[128:131]
	v_mfma_f32_16x16x32_bf16 v[124:127], v[154:157], v[202:205], v[124:127]
	v_mfma_f32_16x16x32_bf16 v[120:123], v[146:149], v[210:213], v[120:123]
	v_mfma_f32_16x16x32_bf16 v[116:119], v[154:157], v[210:213], v[116:119]
	v_mfma_f32_16x16x32_bf16 v[104:107], v[146:149], v[218:221], v[104:107]
	v_mfma_f32_16x16x32_bf16 v[100:103], v[154:157], v[218:221], v[100:103]
	v_mfma_f32_16x16x32_bf16 v[88:91], v[146:149], v[234:237], v[88:91]
	v_mfma_f32_16x16x32_bf16 v[84:87], v[154:157], v[234:237], v[84:87]
	v_mfma_f32_16x16x32_bf16 v[128:131], v[150:153], v[206:209], v[128:131]
	v_mfma_f32_16x16x32_bf16 v[124:127], v[158:161], v[206:209], v[124:127]
	v_mfma_f32_16x16x32_bf16 v[120:123], v[150:153], v[214:217], v[120:123]
	v_mfma_f32_16x16x32_bf16 v[116:119], v[158:161], v[214:217], v[116:119]
	v_mfma_f32_16x16x32_bf16 v[104:107], v[150:153], v[222:225], v[104:107]
	v_mfma_f32_16x16x32_bf16 v[100:103], v[158:161], v[222:225], v[100:103]
	v_mfma_f32_16x16x32_bf16 v[88:91], v[150:153], v[238:241], v[88:91]
	v_mfma_f32_16x16x32_bf16 v[84:87], v[158:161], v[238:241], v[84:87]
	v_mfma_f32_16x16x32_bf16 v[112:115], v[186:189], v[202:205], v[112:115]
	v_mfma_f32_16x16x32_bf16 v[108:111], v[194:197], v[202:205], v[108:111]
	v_mfma_f32_16x16x32_bf16 v[96:99], v[186:189], v[210:213], v[96:99]
	v_mfma_f32_16x16x32_bf16 v[92:95], v[194:197], v[210:213], v[92:95]
	v_mfma_f32_16x16x32_bf16 v[80:83], v[186:189], v[218:221], v[80:83]
	v_mfma_f32_16x16x32_bf16 v[76:79], v[194:197], v[218:221], v[76:79]
	v_mfma_f32_16x16x32_bf16 v[72:75], v[186:189], v[234:237], v[72:75]
	v_mfma_f32_16x16x32_bf16 v[68:71], v[194:197], v[234:237], v[68:71]
	v_mfma_f32_16x16x32_bf16 v[112:115], v[190:193], v[206:209], v[112:115]
	v_mfma_f32_16x16x32_bf16 v[108:111], v[198:201], v[206:209], v[108:111]
	v_mfma_f32_16x16x32_bf16 v[96:99], v[190:193], v[214:217], v[96:99]
	v_mfma_f32_16x16x32_bf16 v[92:95], v[198:201], v[214:217], v[92:95]
	v_mfma_f32_16x16x32_bf16 v[80:83], v[190:193], v[222:225], v[80:83]
	v_mfma_f32_16x16x32_bf16 v[76:79], v[198:201], v[222:225], v[76:79]
	v_mfma_f32_16x16x32_bf16 v[72:75], v[190:193], v[238:241], v[72:75]
	v_mfma_f32_16x16x32_bf16 v[68:71], v[198:201], v[238:241], v[68:71]
	s_barrier
	s_add_i32 s61, s61, s15
	s_mov_b32 m0, s61
	ds_read_b128 v[202:205], v145 offset:16384
	ds_read_b128 v[206:209], v145 offset:17408
	ds_read_b128 v[210:213], v145 offset:18432
	ds_read_b128 v[214:217], v145 offset:19456
	ds_read_b128 v[218:221], v145 offset:20480
	ds_read_b128 v[222:225], v145 offset:21504
	ds_read_b128 v[234:237], v145 offset:22528
	ds_read_b128 v[238:241], v145 offset:23552
	global_load_lds_dwordx4 v34, s[48:49]
	s_add_i32 m0, s61, 0x2000
	s_add_u32 s62, s48, 0x80000
	s_addc_u32 s63, s49, 0
	s_add_i32 s61, s64, s15
	global_load_lds_dwordx4 v136, s[48:49]
	s_mov_b32 m0, s61
	s_add_u32 s98, s50, 0x80
	s_addc_u32 s99, s51, 0
	global_load_lds_dwordx4 v34, s[62:63]
	s_add_i32 m0, s61, 0x2000
	s_nop 0
	global_load_lds_dwordx4 v136, s[62:63]
	s_mov_b32 m0, s21
	s_nop 0
	global_load_lds_dwordx4 v132, s[50:51]
	s_mov_b32 m0, s34
	s_nop 0
	global_load_lds_dwordx4 v134, s[50:51]
	s_waitcnt vmcnt(8)
	s_waitcnt lgkmcnt(0)
	s_barrier
	v_mfma_f32_16x16x32_bf16 v[64:67], v[146:149], v[202:205], v[64:67]
	v_mfma_f32_16x16x32_bf16 v[60:63], v[154:157], v[202:205], v[60:63]
	v_mfma_f32_16x16x32_bf16 v[56:59], v[146:149], v[210:213], v[56:59]
	v_mfma_f32_16x16x32_bf16 v[52:55], v[154:157], v[210:213], v[52:55]
	v_mfma_f32_16x16x32_bf16 v[40:43], v[146:149], v[218:221], v[40:43]
	v_mfma_f32_16x16x32_bf16 v[36:39], v[154:157], v[218:221], v[36:39]
	v_mfma_f32_16x16x32_bf16 v[22:25], v[146:149], v[234:237], v[22:25]
	v_mfma_f32_16x16x32_bf16 v[18:21], v[154:157], v[234:237], v[18:21]
	v_mfma_f32_16x16x32_bf16 v[64:67], v[150:153], v[206:209], v[64:67]
	v_mfma_f32_16x16x32_bf16 v[60:63], v[158:161], v[206:209], v[60:63]
	v_mfma_f32_16x16x32_bf16 v[56:59], v[150:153], v[214:217], v[56:59]
	v_mfma_f32_16x16x32_bf16 v[52:55], v[158:161], v[214:217], v[52:55]
	v_mfma_f32_16x16x32_bf16 v[40:43], v[150:153], v[222:225], v[40:43]
	v_mfma_f32_16x16x32_bf16 v[36:39], v[158:161], v[222:225], v[36:39]
	v_mfma_f32_16x16x32_bf16 v[22:25], v[150:153], v[238:241], v[22:25]
	v_mfma_f32_16x16x32_bf16 v[18:21], v[158:161], v[238:241], v[18:21]
	v_mfma_f32_16x16x32_bf16 v[48:51], v[186:189], v[202:205], v[48:51]
	v_mfma_f32_16x16x32_bf16 v[44:47], v[194:197], v[202:205], v[44:47]
	v_mfma_f32_16x16x32_bf16 v[30:33], v[186:189], v[210:213], v[30:33]
	v_mfma_f32_16x16x32_bf16 v[26:29], v[194:197], v[210:213], v[26:29]
	v_mfma_f32_16x16x32_bf16 v[14:17], v[186:189], v[218:221], v[14:17]
	v_mfma_f32_16x16x32_bf16 v[10:13], v[194:197], v[218:221], v[10:13]
	v_mfma_f32_16x16x32_bf16 v[6:9], v[186:189], v[234:237], v[6:9]
	v_mfma_f32_16x16x32_bf16 v[2:5], v[194:197], v[234:237], v[2:5]
	v_mfma_f32_16x16x32_bf16 v[48:51], v[190:193], v[206:209], v[48:51]
	v_mfma_f32_16x16x32_bf16 v[44:47], v[198:201], v[206:209], v[44:47]
	v_mfma_f32_16x16x32_bf16 v[30:33], v[190:193], v[214:217], v[30:33]
	v_mfma_f32_16x16x32_bf16 v[26:29], v[198:201], v[214:217], v[26:29]
	v_mfma_f32_16x16x32_bf16 v[14:17], v[190:193], v[222:225], v[14:17]
	v_mfma_f32_16x16x32_bf16 v[10:13], v[198:201], v[222:225], v[10:13]
	v_mfma_f32_16x16x32_bf16 v[6:9], v[190:193], v[238:241], v[6:9]
	v_mfma_f32_16x16x32_bf16 v[2:5], v[198:201], v[238:241], v[2:5]
	s_barrier
; #define PG8_STAGE(bufoff, gbase, voff) do { _Pragma("unroll") for (int _i = 0; _i < 2; ++_i) \
;         __builtin_amdgcn_global_load_lds((const unsigned*)((const char*)(gbase) + (voff)[_i]), (PG8_LAS unsigned*)(lds + (bufoff) + ldsw + _i * 8192), 16, 0, 0); } while (0)
; #define PG8_LDA(dst, b, h) do { _Pragma("unroll") for (int m = 0; m < 4; ++m) _Pragma("unroll") for (int k = 0; k < 2; ++k) dst[m][k] = *(const PG8_LAS bf16x8*)(lds + PG8_SA(b, h) + aoff + m * 2048 + k * 1024); } while (0)
; #define PG8_LDB(dst, b, h) do { _Pragma("unroll") for (int n = 0; n < 2; ++n) _Pragma("unroll") for (int k = 0; k < 2; ++k) dst[n][k] = *(const PG8_LAS bf16x8*)(lds + PG8_SB(b, h) + boff + n * 2048 + k * 1024); } while (0)
; #define PG8_WAIT_V(n) asm volatile("s_waitcnt vmcnt(" #n ")" ::: "memory")
; #define PG8_WAIT_L(n) asm volatile("s_waitcnt lgkmcnt(" #n ")" ::: "memory")
; #define PG8_BAR __builtin_amdgcn_s_barrier()
; #define PG8_SCHED __builtin_amdgcn_sched_barrier(0)
;     ...
;             PG8_LDB(B0, 1, 0); PG8_LDB(B1, 1, 1); PG8_SCHED; PG8_LDA(At, 1, 0); PG8_STAGE(PG8_SA(0, 1), a2 + hstepA, voffA);
;             PG8_WAIT_V(8); PG8_WAIT_L(0); PG8_BAR; PG8_MMA(0, 0, At, B0); PG8_MMA(0, 1, At, B1); PG8_BAR; PG8_SCHED;
;             PG8_LDA(At, 1, 1); PG8_STAGE(PG8_SB(1, 0), b3, voffB); PG8_STAGE(PG8_SB(1, 1), b3 + hstepB, voffB); PG8_STAGE(PG8_SA(1, 0), a3, voffA);
;             PG8_WAIT_V(8); PG8_WAIT_L(0); PG8_BAR; PG8_MMA(1, 0, At, B0); PG8_MMA(1, 1, At, B1); PG8_BAR; PG8_SCHED;
	s_add_i32 s61, 0, 0x18000
	s_add_i32 s62, 0, 0x1c000
	ds_read_b128 v[146:149], v163 offset:32768
	ds_read_b128 v[150:153], v163 offset:33792
	ds_read_b128 v[154:157], v163 offset:34816
	ds_read_b128 v[158:161], v163 offset:35840
	ds_read_b128 v[186:189], v163 offset:49152
	ds_read_b128 v[190:193], v163 offset:50176
	ds_read_b128 v[194:197], v163 offset:51200
	ds_read_b128 v[198:201], v163 offset:52224
	s_add_u32 s50, s50, 0x80000
	s_addc_u32 s51, s51, 0
	s_mov_b32 m0, s35
	ds_read_b128 v[202:205], v145 offset:32768
	ds_read_b128 v[206:209], v145 offset:33792
	ds_read_b128 v[210:213], v145 offset:34816
	ds_read_b128 v[214:217], v145 offset:35840
	ds_read_b128 v[218:221], v145 offset:36864
	ds_read_b128 v[222:225], v145 offset:37888
	ds_read_b128 v[234:237], v145 offset:38912
	ds_read_b128 v[238:241], v145 offset:39936
	global_load_lds_dwordx4 v132, s[50:51]
	s_mov_b32 m0, s52
	s_nop 0
	global_load_lds_dwordx4 v134, s[50:51]
	s_waitcnt vmcnt(8)
	s_waitcnt lgkmcnt(0)
	s_barrier
	v_mfma_f32_16x16x32_bf16 v[128:131], v[146:149], v[202:205], v[128:131]
	v_mfma_f32_16x16x32_bf16 v[124:127], v[154:157], v[202:205], v[124:127]
	v_mfma_f32_16x16x32_bf16 v[120:123], v[146:149], v[210:213], v[120:123]
	v_mfma_f32_16x16x32_bf16 v[116:119], v[154:157], v[210:213], v[116:119]
	v_mfma_f32_16x16x32_bf16 v[104:107], v[146:149], v[218:221], v[104:107]
	v_mfma_f32_16x16x32_bf16 v[100:103], v[154:157], v[218:221], v[100:103]
	v_mfma_f32_16x16x32_bf16 v[88:91], v[146:149], v[234:237], v[88:91]
	v_mfma_f32_16x16x32_bf16 v[84:87], v[154:157], v[234:237], v[84:87]
	v_mfma_f32_16x16x32_bf16 v[128:131], v[150:153], v[206:209], v[128:131]
	v_mfma_f32_16x16x32_bf16 v[124:127], v[158:161], v[206:209], v[124:127]
	v_mfma_f32_16x16x32_bf16 v[120:123], v[150:153], v[214:217], v[120:123]
	v_mfma_f32_16x16x32_bf16 v[116:119], v[158:161], v[214:217], v[116:119]
	v_mfma_f32_16x16x32_bf16 v[104:107], v[150:153], v[222:225], v[104:107]
	v_mfma_f32_16x16x32_bf16 v[100:103], v[158:161], v[222:225], v[100:103]
	v_mfma_f32_16x16x32_bf16 v[88:91], v[150:153], v[238:241], v[88:91]
	v_mfma_f32_16x16x32_bf16 v[84:87], v[158:161], v[238:241], v[84:87]
	v_mfma_f32_16x16x32_bf16 v[112:115], v[186:189], v[202:205], v[112:115]
	v_mfma_f32_16x16x32_bf16 v[108:111], v[194:197], v[202:205], v[108:111]
	v_mfma_f32_16x16x32_bf16 v[96:99], v[186:189], v[210:213], v[96:99]
	v_mfma_f32_16x16x32_bf16 v[92:95], v[194:197], v[210:213], v[92:95]
	v_mfma_f32_16x16x32_bf16 v[80:83], v[186:189], v[218:221], v[80:83]
	v_mfma_f32_16x16x32_bf16 v[76:79], v[194:197], v[218:221], v[76:79]
	v_mfma_f32_16x16x32_bf16 v[72:75], v[186:189], v[234:237], v[72:75]
	v_mfma_f32_16x16x32_bf16 v[68:71], v[194:197], v[234:237], v[68:71]
	v_mfma_f32_16x16x32_bf16 v[112:115], v[190:193], v[206:209], v[112:115]
	v_mfma_f32_16x16x32_bf16 v[108:111], v[198:201], v[206:209], v[108:111]
	v_mfma_f32_16x16x32_bf16 v[96:99], v[190:193], v[214:217], v[96:99]
	v_mfma_f32_16x16x32_bf16 v[92:95], v[198:201], v[214:217], v[92:95]
	v_mfma_f32_16x16x32_bf16 v[80:83], v[190:193], v[222:225], v[80:83]
	v_mfma_f32_16x16x32_bf16 v[76:79], v[198:201], v[222:225], v[76:79]
	v_mfma_f32_16x16x32_bf16 v[72:75], v[190:193], v[238:241], v[72:75]
	v_mfma_f32_16x16x32_bf16 v[68:71], v[198:201], v[238:241], v[68:71]
	s_barrier
	s_add_i32 s50, s61, s15
	s_mov_b32 m0, s50
	ds_read_b128 v[202:205], v145 offset:49152
	ds_read_b128 v[206:209], v145 offset:50176
	ds_read_b128 v[210:213], v145 offset:51200
	ds_read_b128 v[214:217], v145 offset:52224
	ds_read_b128 v[218:221], v145 offset:53248
	ds_read_b128 v[222:225], v145 offset:54272
	ds_read_b128 v[234:237], v145 offset:55296
	ds_read_b128 v[238:241], v145 offset:56320
	s_add_u32 vcc_lo, s48, 0x80
	s_addc_u32 vcc_hi, s49, 0
	global_load_lds_dwordx4 v34, vcc
	s_add_i32 m0, s50, 0x2000
	s_add_u32 s48, s48, 0x80080
	s_addc_u32 s49, s49, 0
	s_add_i32 s50, s62, s15
	s_add_u32 vcc_lo, s48, 0xfff80000
	s_addc_u32 vcc_hi, s49, -1
	global_load_lds_dwordx4 v136, vcc
	s_mov_b32 m0, s50
	s_nop 0
	global_load_lds_dwordx4 v34, s[48:49]
	s_add_i32 m0, s50, 0x2000
	s_nop 0
	global_load_lds_dwordx4 v136, s[48:49]
	s_mov_b32 m0, s24
	s_nop 0
	global_load_lds_dwordx4 v132, s[98:99]
	s_mov_b32 m0, s53
	s_nop 0
	global_load_lds_dwordx4 v134, s[98:99]
	s_waitcnt vmcnt(8)
	s_waitcnt lgkmcnt(0)
	s_barrier
	v_mfma_f32_16x16x32_bf16 v[64:67], v[146:149], v[202:205], v[64:67]
	v_mfma_f32_16x16x32_bf16 v[60:63], v[154:157], v[202:205], v[60:63]
	v_mfma_f32_16x16x32_bf16 v[56:59], v[146:149], v[210:213], v[56:59]
	v_mfma_f32_16x16x32_bf16 v[52:55], v[154:157], v[210:213], v[52:55]
	v_mfma_f32_16x16x32_bf16 v[40:43], v[146:149], v[218:221], v[40:43]
	v_mfma_f32_16x16x32_bf16 v[36:39], v[154:157], v[218:221], v[36:39]
	v_mfma_f32_16x16x32_bf16 v[22:25], v[146:149], v[234:237], v[22:25]
	v_mfma_f32_16x16x32_bf16 v[18:21], v[154:157], v[234:237], v[18:21]
	v_mfma_f32_16x16x32_bf16 v[64:67], v[150:153], v[206:209], v[64:67]
	v_mfma_f32_16x16x32_bf16 v[60:63], v[158:161], v[206:209], v[60:63]
	v_mfma_f32_16x16x32_bf16 v[56:59], v[150:153], v[214:217], v[56:59]
	v_mfma_f32_16x16x32_bf16 v[52:55], v[158:161], v[214:217], v[52:55]
	v_mfma_f32_16x16x32_bf16 v[40:43], v[150:153], v[222:225], v[40:43]
	v_mfma_f32_16x16x32_bf16 v[36:39], v[158:161], v[222:225], v[36:39]
	v_mfma_f32_16x16x32_bf16 v[22:25], v[150:153], v[238:241], v[22:25]
	v_mfma_f32_16x16x32_bf16 v[18:21], v[158:161], v[238:241], v[18:21]
	v_mfma_f32_16x16x32_bf16 v[48:51], v[186:189], v[202:205], v[48:51]
	v_mfma_f32_16x16x32_bf16 v[44:47], v[194:197], v[202:205], v[44:47]
	v_mfma_f32_16x16x32_bf16 v[30:33], v[186:189], v[210:213], v[30:33]
	v_mfma_f32_16x16x32_bf16 v[26:29], v[194:197], v[210:213], v[26:29]
	v_mfma_f32_16x16x32_bf16 v[14:17], v[186:189], v[218:221], v[14:17]
	v_mfma_f32_16x16x32_bf16 v[10:13], v[194:197], v[218:221], v[10:13]
	v_mfma_f32_16x16x32_bf16 v[6:9], v[186:189], v[234:237], v[6:9]
	v_mfma_f32_16x16x32_bf16 v[2:5], v[194:197], v[234:237], v[2:5]
	v_mfma_f32_16x16x32_bf16 v[48:51], v[190:193], v[206:209], v[48:51]
	v_mfma_f32_16x16x32_bf16 v[44:47], v[198:201], v[206:209], v[44:47]
	v_mfma_f32_16x16x32_bf16 v[30:33], v[190:193], v[214:217], v[30:33]
	v_mfma_f32_16x16x32_bf16 v[26:29], v[198:201], v[214:217], v[26:29]
	v_mfma_f32_16x16x32_bf16 v[14:17], v[190:193], v[222:225], v[14:17]
	v_mfma_f32_16x16x32_bf16 v[10:13], v[198:201], v[222:225], v[10:13]
	v_mfma_f32_16x16x32_bf16 v[6:9], v[190:193], v[238:241], v[6:9]
	v_mfma_f32_16x16x32_bf16 v[2:5], v[198:201], v[238:241], v[2:5]
	s_barrier
	s_add_i32 s60, s60, 2
	s_add_u32 s46, s46, 0x100
	s_addc_u32 s47, s47, 0
	s_add_u32 s58, s58, 0x100
	s_addc_u32 s59, s59, 0
	s_cmp_gt_u32 s60, 29
	s_cbranch_scc0 .LBB0_2138
	s_and_b64 vcc, exec, s[28:29]
	s_cbranch_vccz .LBB0_2141
	s_barrier
